# pooling rewritten with 32 rows x 4 columns per lane and every row load in flight at once; w_down conversion all on the bx<128 group
# speedup vs baseline: 1.0195x; 1.0001x over previous
.LBB0_449:
	s_and_b32 s39, s17, 31
	s_and_b32 s63, s17, 7
	s_ashr_i32 s62, s17, 5
	s_lshl_b32 s38, s39, 8
	s_lshl_b32 s74, s63, 8
	v_and_b32_e32 v125, 63, v252
	v_lshrrev_b32_e32 v126, 6, v252
	v_lshlrev_b32_e32 v127, 3, v125
	v_lshl_add_u32 v121, v126, 18, v127
	v_lshl_add_u32 v122, v126, 16, v127
	s_lshl_b32 s0, s63, 8
	v_lshl_add_u32 v120, v126, 5, s0
	v_mov_b32_e32 v118, 1.0
	s_lshl_b32 s0, s39, 21
	s_lshl_b32 s1, s62, 9
	s_add_u32 s0, s0, s1
	s_add_u32 s0, s0, 0x8001800
	s_add_u32 s68, s54, s0
	s_addc_u32 s69, s55, 0
	s_lshl_b32 s0, s39, 19
	s_add_u32 s0, s0, s1
	s_add_u32 s70, s6, s0
	s_addc_u32 s71, s7, 0
	s_cmp_eq_u32 s62, 0
	s_cbranch_scc1 .Lpl_w2
	s_cmp_eq_u32 s62, 1
	s_cbranch_scc1 .Lpl_w4
	s_cmp_eq_u32 s62, 2
	s_cbranch_scc1 .Lpl_w8
	s_branch .Lpl_w16
.Lpl_w2:
	s_sub_u32 s4, s68, 0x2000
	s_subb_u32 s5, s69, 0
	global_load_dwordx2 v[0:1], v121, s[4:5]
	s_add_u32 s4, s4, 0x2000
	s_addc_u32 s5, s5, 0
	global_load_dwordx2 v[2:3], v121, s[4:5]
	s_add_u32 s4, s4, 0x2000
	s_addc_u32 s5, s5, 0
	global_load_dwordx2 v[4:5], v121, s[4:5]
	s_add_u32 s4, s4, 0x2000
	s_addc_u32 s5, s5, 0
	global_load_dwordx2 v[6:7], v121, s[4:5]
	s_add_u32 s4, s4, 0x2000
	s_addc_u32 s5, s5, 0
	global_load_dwordx2 v[8:9], v121, s[4:5]
	s_add_u32 s4, s4, 0x2000
	s_addc_u32 s5, s5, 0
	global_load_dwordx2 v[10:11], v121, s[4:5]
	s_add_u32 s4, s4, 0x2000
	s_addc_u32 s5, s5, 0
	global_load_dwordx2 v[12:13], v121, s[4:5]
	s_add_u32 s4, s4, 0x2000
	s_addc_u32 s5, s5, 0
	global_load_dwordx2 v[14:15], v121, s[4:5]
	s_add_u32 s4, s4, 0x2000
	s_addc_u32 s5, s5, 0
	global_load_dwordx2 v[16:17], v121, s[4:5]
	s_add_u32 s4, s4, 0x2000
	s_addc_u32 s5, s5, 0
	global_load_dwordx2 v[18:19], v121, s[4:5]
	s_add_u32 s4, s4, 0x2000
	s_addc_u32 s5, s5, 0
	global_load_dwordx2 v[20:21], v121, s[4:5]
	s_add_u32 s4, s4, 0x2000
	s_addc_u32 s5, s5, 0
	global_load_dwordx2 v[22:23], v121, s[4:5]
	s_add_u32 s4, s4, 0x2000
	s_addc_u32 s5, s5, 0
	global_load_dwordx2 v[24:25], v121, s[4:5]
	s_add_u32 s4, s4, 0x2000
	s_addc_u32 s5, s5, 0
	global_load_dwordx2 v[26:27], v121, s[4:5]
	s_add_u32 s4, s4, 0x2000
	s_addc_u32 s5, s5, 0
	global_load_dwordx2 v[28:29], v121, s[4:5]
	s_add_u32 s4, s4, 0x2000
	s_addc_u32 s5, s5, 0
	global_load_dwordx2 v[30:31], v121, s[4:5]
	s_add_u32 s4, s4, 0x2000
	s_addc_u32 s5, s5, 0
	global_load_dwordx2 v[32:33], v121, s[4:5]
	s_add_u32 s4, s4, 0x2000
	s_addc_u32 s5, s5, 0
	global_load_dwordx2 v[34:35], v121, s[4:5]
	s_add_u32 s4, s4, 0x2000
	s_addc_u32 s5, s5, 0
	global_load_dwordx2 v[36:37], v121, s[4:5]
	s_add_u32 s4, s4, 0x2000
	s_addc_u32 s5, s5, 0
	global_load_dwordx2 v[38:39], v121, s[4:5]
	s_add_u32 s4, s4, 0x2000
	s_addc_u32 s5, s5, 0
	global_load_dwordx2 v[40:41], v121, s[4:5]
	s_add_u32 s4, s4, 0x2000
	s_addc_u32 s5, s5, 0
	global_load_dwordx2 v[42:43], v121, s[4:5]
	s_add_u32 s4, s4, 0x2000
	s_addc_u32 s5, s5, 0
	global_load_dwordx2 v[44:45], v121, s[4:5]
	s_add_u32 s4, s4, 0x2000
	s_addc_u32 s5, s5, 0
	global_load_dwordx2 v[46:47], v121, s[4:5]
	s_add_u32 s4, s4, 0x2000
	s_addc_u32 s5, s5, 0
	global_load_dwordx2 v[48:49], v121, s[4:5]
	s_add_u32 s4, s4, 0x2000
	s_addc_u32 s5, s5, 0
	global_load_dwordx2 v[50:51], v121, s[4:5]
	s_add_u32 s4, s4, 0x2000
	s_addc_u32 s5, s5, 0
	global_load_dwordx2 v[52:53], v121, s[4:5]
	s_add_u32 s4, s4, 0x2000
	s_addc_u32 s5, s5, 0
	global_load_dwordx2 v[54:55], v121, s[4:5]
	s_add_u32 s4, s4, 0x2000
	s_addc_u32 s5, s5, 0
	global_load_dwordx2 v[56:57], v121, s[4:5]
	s_add_u32 s4, s4, 0x2000
	s_addc_u32 s5, s5, 0
	global_load_dwordx2 v[58:59], v121, s[4:5]
	s_add_u32 s4, s4, 0x2000
	s_addc_u32 s5, s5, 0
	global_load_dwordx2 v[60:61], v121, s[4:5]
	s_add_u32 s4, s4, 0x2000
	s_addc_u32 s5, s5, 0
	global_load_dwordx2 v[62:63], v121, s[4:5]
	s_add_u32 s4, s4, 0x2000
	s_addc_u32 s5, s5, 0
	global_load_dwordx2 v[64:65], v121, s[4:5]
	s_waitcnt vmcnt(0)
	v_cmp_le_u32_e32 vcc, 1, v120
	s_nop 1
	v_cndmask_b32_e32 v0, 0, v0, vcc
	v_cndmask_b32_e32 v1, 0, v1, vcc
	v_lshlrev_b32_e32 v94, 16, v0
	v_and_b32_e32 v95, 0xffff0000, v0
	v_lshlrev_b32_e32 v96, 16, v1
	v_and_b32_e32 v97, 0xffff0000, v1
	v_add_u32_e32 v123, 1, v120
	v_min_u32_e32 v123, 2, v123
	v_cvt_f32_u32_e32 v112, v123
	v_div_scale_f32 v113, s[72:73], v112, v112, v118
	v_rcp_f32_e32 v114, v113
	v_div_scale_f32 v115, vcc, v118, v112, v118
	v_fma_f32 v116, -v113, v114, 1.0
	v_fmac_f32_e32 v114, v116, v114
	v_mul_f32_e32 v116, v115, v114
	v_fma_f32 v117, -v113, v116, v115
	v_fmac_f32_e32 v116, v117, v114
	v_fma_f32 v113, -v113, v116, v115
	v_div_fmas_f32 v113, v113, v114, v116
	v_div_fixup_f32 v119, v113, v112, v118
	v_lshlrev_b32_e32 v100, 16, v2
	v_and_b32_e32 v101, 0xffff0000, v2
	v_lshlrev_b32_e32 v102, 16, v3
	v_and_b32_e32 v103, 0xffff0000, v3
	v_add_f32_e32 v94, v94, v100
	v_add_f32_e32 v95, v95, v101
	v_add_f32_e32 v96, v96, v102
	v_add_f32_e32 v97, v97, v103
	v_fma_f32 v100, v94, v119, -v100
	v_fma_f32 v101, v95, v119, -v101
	v_fma_f32 v102, v96, v119, -v102
	v_fma_f32 v103, v97, v119, -v103
	v_cvt_pk_bf16_f32 v108, v100, v101
	v_cvt_pk_bf16_f32 v109, v102, v103
	global_store_dwordx2 v122, v[108:109], s[70:71]
	s_add_u32 s70, s70, 0x800
	s_addc_u32 s71, s71, 0
	v_lshlrev_b32_e32 v100, 16, v0
	v_and_b32_e32 v101, 0xffff0000, v0
	v_lshlrev_b32_e32 v102, 16, v1
	v_and_b32_e32 v103, 0xffff0000, v1
	v_sub_f32_e32 v94, v94, v100
	v_sub_f32_e32 v95, v95, v101
	v_sub_f32_e32 v96, v96, v102
	v_sub_f32_e32 v97, v97, v103
	v_mov_b32_e32 v119, 0x3f000000
	v_lshlrev_b32_e32 v100, 16, v4
	v_and_b32_e32 v101, 0xffff0000, v4
	v_lshlrev_b32_e32 v102, 16, v5
	v_and_b32_e32 v103, 0xffff0000, v5
	v_add_f32_e32 v94, v94, v100
	v_add_f32_e32 v95, v95, v101
	v_add_f32_e32 v96, v96, v102
	v_add_f32_e32 v97, v97, v103
	v_fma_f32 v100, v94, v119, -v100
	v_fma_f32 v101, v95, v119, -v101
	v_fma_f32 v102, v96, v119, -v102
	v_fma_f32 v103, v97, v119, -v103
	v_cvt_pk_bf16_f32 v110, v100, v101
	v_cvt_pk_bf16_f32 v111, v102, v103
	global_store_dwordx2 v122, v[110:111], s[70:71]
	s_add_u32 s70, s70, 0x800
	s_addc_u32 s71, s71, 0
	v_lshlrev_b32_e32 v100, 16, v2
	v_and_b32_e32 v101, 0xffff0000, v2
	v_lshlrev_b32_e32 v102, 16, v3
	v_and_b32_e32 v103, 0xffff0000, v3
	v_sub_f32_e32 v94, v94, v100
	v_sub_f32_e32 v95, v95, v101
	v_sub_f32_e32 v96, v96, v102
	v_sub_f32_e32 v97, v97, v103
	v_lshlrev_b32_e32 v100, 16, v6
	v_and_b32_e32 v101, 0xffff0000, v6
	v_lshlrev_b32_e32 v102, 16, v7
	v_and_b32_e32 v103, 0xffff0000, v7
	v_add_f32_e32 v94, v94, v100
	v_add_f32_e32 v95, v95, v101
	v_add_f32_e32 v96, v96, v102
	v_add_f32_e32 v97, v97, v103
	v_fma_f32 v100, v94, v119, -v100
	v_fma_f32 v101, v95, v119, -v101
	v_fma_f32 v102, v96, v119, -v102
	v_fma_f32 v103, v97, v119, -v103
	v_cvt_pk_bf16_f32 v108, v100, v101
	v_cvt_pk_bf16_f32 v109, v102, v103
	global_store_dwordx2 v122, v[108:109], s[70:71]
	s_add_u32 s70, s70, 0x800
	s_addc_u32 s71, s71, 0
	v_lshlrev_b32_e32 v100, 16, v4
	v_and_b32_e32 v101, 0xffff0000, v4
	v_lshlrev_b32_e32 v102, 16, v5
	v_and_b32_e32 v103, 0xffff0000, v5
	v_sub_f32_e32 v94, v94, v100
	v_sub_f32_e32 v95, v95, v101
	v_sub_f32_e32 v96, v96, v102
	v_sub_f32_e32 v97, v97, v103
	v_lshlrev_b32_e32 v100, 16, v8
	v_and_b32_e32 v101, 0xffff0000, v8
	v_lshlrev_b32_e32 v102, 16, v9
	v_and_b32_e32 v103, 0xffff0000, v9
	v_add_f32_e32 v94, v94, v100
	v_add_f32_e32 v95, v95, v101
	v_add_f32_e32 v96, v96, v102
	v_add_f32_e32 v97, v97, v103
	v_fma_f32 v100, v94, v119, -v100
	v_fma_f32 v101, v95, v119, -v101
	v_fma_f32 v102, v96, v119, -v102
	v_fma_f32 v103, v97, v119, -v103
	v_cvt_pk_bf16_f32 v110, v100, v101
	v_cvt_pk_bf16_f32 v111, v102, v103
	global_store_dwordx2 v122, v[110:111], s[70:71]
	s_add_u32 s70, s70, 0x800
	s_addc_u32 s71, s71, 0
	v_lshlrev_b32_e32 v100, 16, v6
	v_and_b32_e32 v101, 0xffff0000, v6
	v_lshlrev_b32_e32 v102, 16, v7
	v_and_b32_e32 v103, 0xffff0000, v7
	v_sub_f32_e32 v94, v94, v100
	v_sub_f32_e32 v95, v95, v101
	v_sub_f32_e32 v96, v96, v102
	v_sub_f32_e32 v97, v97, v103
	v_lshlrev_b32_e32 v100, 16, v10
	v_and_b32_e32 v101, 0xffff0000, v10
	v_lshlrev_b32_e32 v102, 16, v11
	v_and_b32_e32 v103, 0xffff0000, v11
	v_add_f32_e32 v94, v94, v100
	v_add_f32_e32 v95, v95, v101
	v_add_f32_e32 v96, v96, v102
	v_add_f32_e32 v97, v97, v103
	v_fma_f32 v100, v94, v119, -v100
	v_fma_f32 v101, v95, v119, -v101
	v_fma_f32 v102, v96, v119, -v102
	v_fma_f32 v103, v97, v119, -v103
	v_cvt_pk_bf16_f32 v108, v100, v101
	v_cvt_pk_bf16_f32 v109, v102, v103
	global_store_dwordx2 v122, v[108:109], s[70:71]
	s_add_u32 s70, s70, 0x800
	s_addc_u32 s71, s71, 0
	v_lshlrev_b32_e32 v100, 16, v8
	v_and_b32_e32 v101, 0xffff0000, v8
	v_lshlrev_b32_e32 v102, 16, v9
	v_and_b32_e32 v103, 0xffff0000, v9
	v_sub_f32_e32 v94, v94, v100
	v_sub_f32_e32 v95, v95, v101
	v_sub_f32_e32 v96, v96, v102
	v_sub_f32_e32 v97, v97, v103
	v_lshlrev_b32_e32 v100, 16, v12
	v_and_b32_e32 v101, 0xffff0000, v12
	v_lshlrev_b32_e32 v102, 16, v13
	v_and_b32_e32 v103, 0xffff0000, v13
	v_add_f32_e32 v94, v94, v100
	v_add_f32_e32 v95, v95, v101
	v_add_f32_e32 v96, v96, v102
	v_add_f32_e32 v97, v97, v103
	v_fma_f32 v100, v94, v119, -v100
	v_fma_f32 v101, v95, v119, -v101
	v_fma_f32 v102, v96, v119, -v102
	v_fma_f32 v103, v97, v119, -v103
	v_cvt_pk_bf16_f32 v110, v100, v101
	v_cvt_pk_bf16_f32 v111, v102, v103
	global_store_dwordx2 v122, v[110:111], s[70:71]
	s_add_u32 s70, s70, 0x800
	s_addc_u32 s71, s71, 0
	v_lshlrev_b32_e32 v100, 16, v10
	v_and_b32_e32 v101, 0xffff0000, v10
	v_lshlrev_b32_e32 v102, 16, v11
	v_and_b32_e32 v103, 0xffff0000, v11
	v_sub_f32_e32 v94, v94, v100
	v_sub_f32_e32 v95, v95, v101
	v_sub_f32_e32 v96, v96, v102
	v_sub_f32_e32 v97, v97, v103
	v_lshlrev_b32_e32 v100, 16, v14
	v_and_b32_e32 v101, 0xffff0000, v14
	v_lshlrev_b32_e32 v102, 16, v15
	v_and_b32_e32 v103, 0xffff0000, v15
	v_add_f32_e32 v94, v94, v100
	v_add_f32_e32 v95, v95, v101
	v_add_f32_e32 v96, v96, v102
	v_add_f32_e32 v97, v97, v103
	v_fma_f32 v100, v94, v119, -v100
	v_fma_f32 v101, v95, v119, -v101
	v_fma_f32 v102, v96, v119, -v102
	v_fma_f32 v103, v97, v119, -v103
	v_cvt_pk_bf16_f32 v108, v100, v101
	v_cvt_pk_bf16_f32 v109, v102, v103
	global_store_dwordx2 v122, v[108:109], s[70:71]
	s_add_u32 s70, s70, 0x800
	s_addc_u32 s71, s71, 0
	v_lshlrev_b32_e32 v100, 16, v12
	v_and_b32_e32 v101, 0xffff0000, v12
	v_lshlrev_b32_e32 v102, 16, v13
	v_and_b32_e32 v103, 0xffff0000, v13
	v_sub_f32_e32 v94, v94, v100
	v_sub_f32_e32 v95, v95, v101
	v_sub_f32_e32 v96, v96, v102
	v_sub_f32_e32 v97, v97, v103
	v_lshlrev_b32_e32 v100, 16, v16
	v_and_b32_e32 v101, 0xffff0000, v16
	v_lshlrev_b32_e32 v102, 16, v17
	v_and_b32_e32 v103, 0xffff0000, v17
	v_add_f32_e32 v94, v94, v100
	v_add_f32_e32 v95, v95, v101
	v_add_f32_e32 v96, v96, v102
	v_add_f32_e32 v97, v97, v103
	v_fma_f32 v100, v94, v119, -v100
	v_fma_f32 v101, v95, v119, -v101
	v_fma_f32 v102, v96, v119, -v102
	v_fma_f32 v103, v97, v119, -v103
	v_cvt_pk_bf16_f32 v110, v100, v101
	v_cvt_pk_bf16_f32 v111, v102, v103
	global_store_dwordx2 v122, v[110:111], s[70:71]
	s_add_u32 s70, s70, 0x800
	s_addc_u32 s71, s71, 0
	v_lshlrev_b32_e32 v100, 16, v14
	v_and_b32_e32 v101, 0xffff0000, v14
	v_lshlrev_b32_e32 v102, 16, v15
	v_and_b32_e32 v103, 0xffff0000, v15
	v_sub_f32_e32 v94, v94, v100
	v_sub_f32_e32 v95, v95, v101
	v_sub_f32_e32 v96, v96, v102
	v_sub_f32_e32 v97, v97, v103
	v_lshlrev_b32_e32 v100, 16, v18
	v_and_b32_e32 v101, 0xffff0000, v18
	v_lshlrev_b32_e32 v102, 16, v19
	v_and_b32_e32 v103, 0xffff0000, v19
	v_add_f32_e32 v94, v94, v100
	v_add_f32_e32 v95, v95, v101
	v_add_f32_e32 v96, v96, v102
	v_add_f32_e32 v97, v97, v103
	v_fma_f32 v100, v94, v119, -v100
	v_fma_f32 v101, v95, v119, -v101
	v_fma_f32 v102, v96, v119, -v102
	v_fma_f32 v103, v97, v119, -v103
	v_cvt_pk_bf16_f32 v108, v100, v101
	v_cvt_pk_bf16_f32 v109, v102, v103
	global_store_dwordx2 v122, v[108:109], s[70:71]
	s_add_u32 s70, s70, 0x800
	s_addc_u32 s71, s71, 0
	v_lshlrev_b32_e32 v100, 16, v16
	v_and_b32_e32 v101, 0xffff0000, v16
	v_lshlrev_b32_e32 v102, 16, v17
	v_and_b32_e32 v103, 0xffff0000, v17
	v_sub_f32_e32 v94, v94, v100
	v_sub_f32_e32 v95, v95, v101
	v_sub_f32_e32 v96, v96, v102
	v_sub_f32_e32 v97, v97, v103
	v_lshlrev_b32_e32 v100, 16, v20
	v_and_b32_e32 v101, 0xffff0000, v20
	v_lshlrev_b32_e32 v102, 16, v21
	v_and_b32_e32 v103, 0xffff0000, v21
	v_add_f32_e32 v94, v94, v100
	v_add_f32_e32 v95, v95, v101
	v_add_f32_e32 v96, v96, v102
	v_add_f32_e32 v97, v97, v103
	v_fma_f32 v100, v94, v119, -v100
	v_fma_f32 v101, v95, v119, -v101
	v_fma_f32 v102, v96, v119, -v102
	v_fma_f32 v103, v97, v119, -v103
	v_cvt_pk_bf16_f32 v110, v100, v101
	v_cvt_pk_bf16_f32 v111, v102, v103
	global_store_dwordx2 v122, v[110:111], s[70:71]
	s_add_u32 s70, s70, 0x800
	s_addc_u32 s71, s71, 0
	v_lshlrev_b32_e32 v100, 16, v18
	v_and_b32_e32 v101, 0xffff0000, v18
	v_lshlrev_b32_e32 v102, 16, v19
	v_and_b32_e32 v103, 0xffff0000, v19
	v_sub_f32_e32 v94, v94, v100
	v_sub_f32_e32 v95, v95, v101
	v_sub_f32_e32 v96, v96, v102
	v_sub_f32_e32 v97, v97, v103
	v_lshlrev_b32_e32 v100, 16, v22
	v_and_b32_e32 v101, 0xffff0000, v22
	v_lshlrev_b32_e32 v102, 16, v23
	v_and_b32_e32 v103, 0xffff0000, v23
	v_add_f32_e32 v94, v94, v100
	v_add_f32_e32 v95, v95, v101
	v_add_f32_e32 v96, v96, v102
	v_add_f32_e32 v97, v97, v103
	v_fma_f32 v100, v94, v119, -v100
	v_fma_f32 v101, v95, v119, -v101
	v_fma_f32 v102, v96, v119, -v102
	v_fma_f32 v103, v97, v119, -v103
	v_cvt_pk_bf16_f32 v108, v100, v101
	v_cvt_pk_bf16_f32 v109, v102, v103
	global_store_dwordx2 v122, v[108:109], s[70:71]
	s_add_u32 s70, s70, 0x800
	s_addc_u32 s71, s71, 0
	v_lshlrev_b32_e32 v100, 16, v20
	v_and_b32_e32 v101, 0xffff0000, v20
	v_lshlrev_b32_e32 v102, 16, v21
	v_and_b32_e32 v103, 0xffff0000, v21
	v_sub_f32_e32 v94, v94, v100
	v_sub_f32_e32 v95, v95, v101
	v_sub_f32_e32 v96, v96, v102
	v_sub_f32_e32 v97, v97, v103
	v_lshlrev_b32_e32 v100, 16, v24
	v_and_b32_e32 v101, 0xffff0000, v24
	v_lshlrev_b32_e32 v102, 16, v25
	v_and_b32_e32 v103, 0xffff0000, v25
	v_add_f32_e32 v94, v94, v100
	v_add_f32_e32 v95, v95, v101
	v_add_f32_e32 v96, v96, v102
	v_add_f32_e32 v97, v97, v103
	v_fma_f32 v100, v94, v119, -v100
	v_fma_f32 v101, v95, v119, -v101
	v_fma_f32 v102, v96, v119, -v102
	v_fma_f32 v103, v97, v119, -v103
	v_cvt_pk_bf16_f32 v110, v100, v101
	v_cvt_pk_bf16_f32 v111, v102, v103
	global_store_dwordx2 v122, v[110:111], s[70:71]
	s_add_u32 s70, s70, 0x800
	s_addc_u32 s71, s71, 0
	v_lshlrev_b32_e32 v100, 16, v22
	v_and_b32_e32 v101, 0xffff0000, v22
	v_lshlrev_b32_e32 v102, 16, v23
	v_and_b32_e32 v103, 0xffff0000, v23
	v_sub_f32_e32 v94, v94, v100
	v_sub_f32_e32 v95, v95, v101
	v_sub_f32_e32 v96, v96, v102
	v_sub_f32_e32 v97, v97, v103
	v_lshlrev_b32_e32 v100, 16, v26
	v_and_b32_e32 v101, 0xffff0000, v26
	v_lshlrev_b32_e32 v102, 16, v27
	v_and_b32_e32 v103, 0xffff0000, v27
	v_add_f32_e32 v94, v94, v100
	v_add_f32_e32 v95, v95, v101
	v_add_f32_e32 v96, v96, v102
	v_add_f32_e32 v97, v97, v103
	v_fma_f32 v100, v94, v119, -v100
	v_fma_f32 v101, v95, v119, -v101
	v_fma_f32 v102, v96, v119, -v102
	v_fma_f32 v103, v97, v119, -v103
	v_cvt_pk_bf16_f32 v108, v100, v101
	v_cvt_pk_bf16_f32 v109, v102, v103
	global_store_dwordx2 v122, v[108:109], s[70:71]
	s_add_u32 s70, s70, 0x800
	s_addc_u32 s71, s71, 0
	v_lshlrev_b32_e32 v100, 16, v24
	v_and_b32_e32 v101, 0xffff0000, v24
	v_lshlrev_b32_e32 v102, 16, v25
	v_and_b32_e32 v103, 0xffff0000, v25
	v_sub_f32_e32 v94, v94, v100
	v_sub_f32_e32 v95, v95, v101
	v_sub_f32_e32 v96, v96, v102
	v_sub_f32_e32 v97, v97, v103
	v_lshlrev_b32_e32 v100, 16, v28
	v_and_b32_e32 v101, 0xffff0000, v28
	v_lshlrev_b32_e32 v102, 16, v29
	v_and_b32_e32 v103, 0xffff0000, v29
	v_add_f32_e32 v94, v94, v100
	v_add_f32_e32 v95, v95, v101
	v_add_f32_e32 v96, v96, v102
	v_add_f32_e32 v97, v97, v103
	v_fma_f32 v100, v94, v119, -v100
	v_fma_f32 v101, v95, v119, -v101
	v_fma_f32 v102, v96, v119, -v102
	v_fma_f32 v103, v97, v119, -v103
	v_cvt_pk_bf16_f32 v110, v100, v101
	v_cvt_pk_bf16_f32 v111, v102, v103
	global_store_dwordx2 v122, v[110:111], s[70:71]
	s_add_u32 s70, s70, 0x800
	s_addc_u32 s71, s71, 0
	v_lshlrev_b32_e32 v100, 16, v26
	v_and_b32_e32 v101, 0xffff0000, v26
	v_lshlrev_b32_e32 v102, 16, v27
	v_and_b32_e32 v103, 0xffff0000, v27
	v_sub_f32_e32 v94, v94, v100
	v_sub_f32_e32 v95, v95, v101
	v_sub_f32_e32 v96, v96, v102
	v_sub_f32_e32 v97, v97, v103
	v_lshlrev_b32_e32 v100, 16, v30
	v_and_b32_e32 v101, 0xffff0000, v30
	v_lshlrev_b32_e32 v102, 16, v31
	v_and_b32_e32 v103, 0xffff0000, v31
	v_add_f32_e32 v94, v94, v100
	v_add_f32_e32 v95, v95, v101
	v_add_f32_e32 v96, v96, v102
	v_add_f32_e32 v97, v97, v103
	v_fma_f32 v100, v94, v119, -v100
	v_fma_f32 v101, v95, v119, -v101
	v_fma_f32 v102, v96, v119, -v102
	v_fma_f32 v103, v97, v119, -v103
	v_cvt_pk_bf16_f32 v108, v100, v101
	v_cvt_pk_bf16_f32 v109, v102, v103
	global_store_dwordx2 v122, v[108:109], s[70:71]
	s_add_u32 s70, s70, 0x800
	s_addc_u32 s71, s71, 0
	v_lshlrev_b32_e32 v100, 16, v28
	v_and_b32_e32 v101, 0xffff0000, v28
	v_lshlrev_b32_e32 v102, 16, v29
	v_and_b32_e32 v103, 0xffff0000, v29
	v_sub_f32_e32 v94, v94, v100
	v_sub_f32_e32 v95, v95, v101
	v_sub_f32_e32 v96, v96, v102
	v_sub_f32_e32 v97, v97, v103
	v_lshlrev_b32_e32 v100, 16, v32
	v_and_b32_e32 v101, 0xffff0000, v32
	v_lshlrev_b32_e32 v102, 16, v33
	v_and_b32_e32 v103, 0xffff0000, v33
	v_add_f32_e32 v94, v94, v100
	v_add_f32_e32 v95, v95, v101
	v_add_f32_e32 v96, v96, v102
	v_add_f32_e32 v97, v97, v103
	v_fma_f32 v100, v94, v119, -v100
	v_fma_f32 v101, v95, v119, -v101
	v_fma_f32 v102, v96, v119, -v102
	v_fma_f32 v103, v97, v119, -v103
	v_cvt_pk_bf16_f32 v110, v100, v101
	v_cvt_pk_bf16_f32 v111, v102, v103
	global_store_dwordx2 v122, v[110:111], s[70:71]
	s_add_u32 s70, s70, 0x800
	s_addc_u32 s71, s71, 0
	v_lshlrev_b32_e32 v100, 16, v30
	v_and_b32_e32 v101, 0xffff0000, v30
	v_lshlrev_b32_e32 v102, 16, v31
	v_and_b32_e32 v103, 0xffff0000, v31
	v_sub_f32_e32 v94, v94, v100
	v_sub_f32_e32 v95, v95, v101
	v_sub_f32_e32 v96, v96, v102
	v_sub_f32_e32 v97, v97, v103
	v_lshlrev_b32_e32 v100, 16, v34
	v_and_b32_e32 v101, 0xffff0000, v34
	v_lshlrev_b32_e32 v102, 16, v35
	v_and_b32_e32 v103, 0xffff0000, v35
	v_add_f32_e32 v94, v94, v100
	v_add_f32_e32 v95, v95, v101
	v_add_f32_e32 v96, v96, v102
	v_add_f32_e32 v97, v97, v103
	v_fma_f32 v100, v94, v119, -v100
	v_fma_f32 v101, v95, v119, -v101
	v_fma_f32 v102, v96, v119, -v102
	v_fma_f32 v103, v97, v119, -v103
	v_cvt_pk_bf16_f32 v108, v100, v101
	v_cvt_pk_bf16_f32 v109, v102, v103
	global_store_dwordx2 v122, v[108:109], s[70:71]
	s_add_u32 s70, s70, 0x800
	s_addc_u32 s71, s71, 0
	v_lshlrev_b32_e32 v100, 16, v32
	v_and_b32_e32 v101, 0xffff0000, v32
	v_lshlrev_b32_e32 v102, 16, v33
	v_and_b32_e32 v103, 0xffff0000, v33
	v_sub_f32_e32 v94, v94, v100
	v_sub_f32_e32 v95, v95, v101
	v_sub_f32_e32 v96, v96, v102
	v_sub_f32_e32 v97, v97, v103
	v_lshlrev_b32_e32 v100, 16, v36
	v_and_b32_e32 v101, 0xffff0000, v36
	v_lshlrev_b32_e32 v102, 16, v37
	v_and_b32_e32 v103, 0xffff0000, v37
	v_add_f32_e32 v94, v94, v100
	v_add_f32_e32 v95, v95, v101
	v_add_f32_e32 v96, v96, v102
	v_add_f32_e32 v97, v97, v103
	v_fma_f32 v100, v94, v119, -v100
	v_fma_f32 v101, v95, v119, -v101
	v_fma_f32 v102, v96, v119, -v102
	v_fma_f32 v103, v97, v119, -v103
	v_cvt_pk_bf16_f32 v110, v100, v101
	v_cvt_pk_bf16_f32 v111, v102, v103
	global_store_dwordx2 v122, v[110:111], s[70:71]
	s_add_u32 s70, s70, 0x800
	s_addc_u32 s71, s71, 0
	v_lshlrev_b32_e32 v100, 16, v34
	v_and_b32_e32 v101, 0xffff0000, v34
	v_lshlrev_b32_e32 v102, 16, v35
	v_and_b32_e32 v103, 0xffff0000, v35
	v_sub_f32_e32 v94, v94, v100
	v_sub_f32_e32 v95, v95, v101
	v_sub_f32_e32 v96, v96, v102
	v_sub_f32_e32 v97, v97, v103
	v_lshlrev_b32_e32 v100, 16, v38
	v_and_b32_e32 v101, 0xffff0000, v38
	v_lshlrev_b32_e32 v102, 16, v39
	v_and_b32_e32 v103, 0xffff0000, v39
	v_add_f32_e32 v94, v94, v100
	v_add_f32_e32 v95, v95, v101
	v_add_f32_e32 v96, v96, v102
	v_add_f32_e32 v97, v97, v103
	v_fma_f32 v100, v94, v119, -v100
	v_fma_f32 v101, v95, v119, -v101
	v_fma_f32 v102, v96, v119, -v102
	v_fma_f32 v103, v97, v119, -v103
	v_cvt_pk_bf16_f32 v108, v100, v101
	v_cvt_pk_bf16_f32 v109, v102, v103
	global_store_dwordx2 v122, v[108:109], s[70:71]
	s_add_u32 s70, s70, 0x800
	s_addc_u32 s71, s71, 0
	v_lshlrev_b32_e32 v100, 16, v36
	v_and_b32_e32 v101, 0xffff0000, v36
	v_lshlrev_b32_e32 v102, 16, v37
	v_and_b32_e32 v103, 0xffff0000, v37
	v_sub_f32_e32 v94, v94, v100
	v_sub_f32_e32 v95, v95, v101
	v_sub_f32_e32 v96, v96, v102
	v_sub_f32_e32 v97, v97, v103
	v_lshlrev_b32_e32 v100, 16, v40
	v_and_b32_e32 v101, 0xffff0000, v40
	v_lshlrev_b32_e32 v102, 16, v41
	v_and_b32_e32 v103, 0xffff0000, v41
	v_add_f32_e32 v94, v94, v100
	v_add_f32_e32 v95, v95, v101
	v_add_f32_e32 v96, v96, v102
	v_add_f32_e32 v97, v97, v103
	v_fma_f32 v100, v94, v119, -v100
	v_fma_f32 v101, v95, v119, -v101
	v_fma_f32 v102, v96, v119, -v102
	v_fma_f32 v103, v97, v119, -v103
	v_cvt_pk_bf16_f32 v110, v100, v101
	v_cvt_pk_bf16_f32 v111, v102, v103
	global_store_dwordx2 v122, v[110:111], s[70:71]
	s_add_u32 s70, s70, 0x800
	s_addc_u32 s71, s71, 0
	v_lshlrev_b32_e32 v100, 16, v38
	v_and_b32_e32 v101, 0xffff0000, v38
	v_lshlrev_b32_e32 v102, 16, v39
	v_and_b32_e32 v103, 0xffff0000, v39
	v_sub_f32_e32 v94, v94, v100
	v_sub_f32_e32 v95, v95, v101
	v_sub_f32_e32 v96, v96, v102
	v_sub_f32_e32 v97, v97, v103
	v_lshlrev_b32_e32 v100, 16, v42
	v_and_b32_e32 v101, 0xffff0000, v42
	v_lshlrev_b32_e32 v102, 16, v43
	v_and_b32_e32 v103, 0xffff0000, v43
	v_add_f32_e32 v94, v94, v100
	v_add_f32_e32 v95, v95, v101
	v_add_f32_e32 v96, v96, v102
	v_add_f32_e32 v97, v97, v103
	v_fma_f32 v100, v94, v119, -v100
	v_fma_f32 v101, v95, v119, -v101
	v_fma_f32 v102, v96, v119, -v102
	v_fma_f32 v103, v97, v119, -v103
	v_cvt_pk_bf16_f32 v108, v100, v101
	v_cvt_pk_bf16_f32 v109, v102, v103
	global_store_dwordx2 v122, v[108:109], s[70:71]
	s_add_u32 s70, s70, 0x800
	s_addc_u32 s71, s71, 0
	v_lshlrev_b32_e32 v100, 16, v40
	v_and_b32_e32 v101, 0xffff0000, v40
	v_lshlrev_b32_e32 v102, 16, v41
	v_and_b32_e32 v103, 0xffff0000, v41
	v_sub_f32_e32 v94, v94, v100
	v_sub_f32_e32 v95, v95, v101
	v_sub_f32_e32 v96, v96, v102
	v_sub_f32_e32 v97, v97, v103
	v_lshlrev_b32_e32 v100, 16, v44
	v_and_b32_e32 v101, 0xffff0000, v44
	v_lshlrev_b32_e32 v102, 16, v45
	v_and_b32_e32 v103, 0xffff0000, v45
	v_add_f32_e32 v94, v94, v100
	v_add_f32_e32 v95, v95, v101
	v_add_f32_e32 v96, v96, v102
	v_add_f32_e32 v97, v97, v103
	v_fma_f32 v100, v94, v119, -v100
	v_fma_f32 v101, v95, v119, -v101
	v_fma_f32 v102, v96, v119, -v102
	v_fma_f32 v103, v97, v119, -v103
	v_cvt_pk_bf16_f32 v110, v100, v101
	v_cvt_pk_bf16_f32 v111, v102, v103
	global_store_dwordx2 v122, v[110:111], s[70:71]
	s_add_u32 s70, s70, 0x800
	s_addc_u32 s71, s71, 0
	v_lshlrev_b32_e32 v100, 16, v42
	v_and_b32_e32 v101, 0xffff0000, v42
	v_lshlrev_b32_e32 v102, 16, v43
	v_and_b32_e32 v103, 0xffff0000, v43
	v_sub_f32_e32 v94, v94, v100
	v_sub_f32_e32 v95, v95, v101
	v_sub_f32_e32 v96, v96, v102
	v_sub_f32_e32 v97, v97, v103
	v_lshlrev_b32_e32 v100, 16, v46
	v_and_b32_e32 v101, 0xffff0000, v46
	v_lshlrev_b32_e32 v102, 16, v47
	v_and_b32_e32 v103, 0xffff0000, v47
	v_add_f32_e32 v94, v94, v100
	v_add_f32_e32 v95, v95, v101
	v_add_f32_e32 v96, v96, v102
	v_add_f32_e32 v97, v97, v103
	v_fma_f32 v100, v94, v119, -v100
	v_fma_f32 v101, v95, v119, -v101
	v_fma_f32 v102, v96, v119, -v102
	v_fma_f32 v103, v97, v119, -v103
	v_cvt_pk_bf16_f32 v108, v100, v101
	v_cvt_pk_bf16_f32 v109, v102, v103
	global_store_dwordx2 v122, v[108:109], s[70:71]
	s_add_u32 s70, s70, 0x800
	s_addc_u32 s71, s71, 0
	v_lshlrev_b32_e32 v100, 16, v44
	v_and_b32_e32 v101, 0xffff0000, v44
	v_lshlrev_b32_e32 v102, 16, v45
	v_and_b32_e32 v103, 0xffff0000, v45
	v_sub_f32_e32 v94, v94, v100
	v_sub_f32_e32 v95, v95, v101
	v_sub_f32_e32 v96, v96, v102
	v_sub_f32_e32 v97, v97, v103
	v_lshlrev_b32_e32 v100, 16, v48
	v_and_b32_e32 v101, 0xffff0000, v48
	v_lshlrev_b32_e32 v102, 16, v49
	v_and_b32_e32 v103, 0xffff0000, v49
	v_add_f32_e32 v94, v94, v100
	v_add_f32_e32 v95, v95, v101
	v_add_f32_e32 v96, v96, v102
	v_add_f32_e32 v97, v97, v103
	v_fma_f32 v100, v94, v119, -v100
	v_fma_f32 v101, v95, v119, -v101
	v_fma_f32 v102, v96, v119, -v102
	v_fma_f32 v103, v97, v119, -v103
	v_cvt_pk_bf16_f32 v110, v100, v101
	v_cvt_pk_bf16_f32 v111, v102, v103
	global_store_dwordx2 v122, v[110:111], s[70:71]
	s_add_u32 s70, s70, 0x800
	s_addc_u32 s71, s71, 0
	v_lshlrev_b32_e32 v100, 16, v46
	v_and_b32_e32 v101, 0xffff0000, v46
	v_lshlrev_b32_e32 v102, 16, v47
	v_and_b32_e32 v103, 0xffff0000, v47
	v_sub_f32_e32 v94, v94, v100
	v_sub_f32_e32 v95, v95, v101
	v_sub_f32_e32 v96, v96, v102
	v_sub_f32_e32 v97, v97, v103
	v_lshlrev_b32_e32 v100, 16, v50
	v_and_b32_e32 v101, 0xffff0000, v50
	v_lshlrev_b32_e32 v102, 16, v51
	v_and_b32_e32 v103, 0xffff0000, v51
	v_add_f32_e32 v94, v94, v100
	v_add_f32_e32 v95, v95, v101
	v_add_f32_e32 v96, v96, v102
	v_add_f32_e32 v97, v97, v103
	v_fma_f32 v100, v94, v119, -v100
	v_fma_f32 v101, v95, v119, -v101
	v_fma_f32 v102, v96, v119, -v102
	v_fma_f32 v103, v97, v119, -v103
	v_cvt_pk_bf16_f32 v108, v100, v101
	v_cvt_pk_bf16_f32 v109, v102, v103
	global_store_dwordx2 v122, v[108:109], s[70:71]
	s_add_u32 s70, s70, 0x800
	s_addc_u32 s71, s71, 0
	v_lshlrev_b32_e32 v100, 16, v48
	v_and_b32_e32 v101, 0xffff0000, v48
	v_lshlrev_b32_e32 v102, 16, v49
	v_and_b32_e32 v103, 0xffff0000, v49
	v_sub_f32_e32 v94, v94, v100
	v_sub_f32_e32 v95, v95, v101
	v_sub_f32_e32 v96, v96, v102
	v_sub_f32_e32 v97, v97, v103
	v_lshlrev_b32_e32 v100, 16, v52
	v_and_b32_e32 v101, 0xffff0000, v52
	v_lshlrev_b32_e32 v102, 16, v53
	v_and_b32_e32 v103, 0xffff0000, v53
	v_add_f32_e32 v94, v94, v100
	v_add_f32_e32 v95, v95, v101
	v_add_f32_e32 v96, v96, v102
	v_add_f32_e32 v97, v97, v103
	v_fma_f32 v100, v94, v119, -v100
	v_fma_f32 v101, v95, v119, -v101
	v_fma_f32 v102, v96, v119, -v102
	v_fma_f32 v103, v97, v119, -v103
	v_cvt_pk_bf16_f32 v110, v100, v101
	v_cvt_pk_bf16_f32 v111, v102, v103
	global_store_dwordx2 v122, v[110:111], s[70:71]
	s_add_u32 s70, s70, 0x800
	s_addc_u32 s71, s71, 0
	v_lshlrev_b32_e32 v100, 16, v50
	v_and_b32_e32 v101, 0xffff0000, v50
	v_lshlrev_b32_e32 v102, 16, v51
	v_and_b32_e32 v103, 0xffff0000, v51
	v_sub_f32_e32 v94, v94, v100
	v_sub_f32_e32 v95, v95, v101
	v_sub_f32_e32 v96, v96, v102
	v_sub_f32_e32 v97, v97, v103
	v_lshlrev_b32_e32 v100, 16, v54
	v_and_b32_e32 v101, 0xffff0000, v54
	v_lshlrev_b32_e32 v102, 16, v55
	v_and_b32_e32 v103, 0xffff0000, v55
	v_add_f32_e32 v94, v94, v100
	v_add_f32_e32 v95, v95, v101
	v_add_f32_e32 v96, v96, v102
	v_add_f32_e32 v97, v97, v103
	v_fma_f32 v100, v94, v119, -v100
	v_fma_f32 v101, v95, v119, -v101
	v_fma_f32 v102, v96, v119, -v102
	v_fma_f32 v103, v97, v119, -v103
	v_cvt_pk_bf16_f32 v108, v100, v101
	v_cvt_pk_bf16_f32 v109, v102, v103
	global_store_dwordx2 v122, v[108:109], s[70:71]
	s_add_u32 s70, s70, 0x800
	s_addc_u32 s71, s71, 0
	v_lshlrev_b32_e32 v100, 16, v52
	v_and_b32_e32 v101, 0xffff0000, v52
	v_lshlrev_b32_e32 v102, 16, v53
	v_and_b32_e32 v103, 0xffff0000, v53
	v_sub_f32_e32 v94, v94, v100
	v_sub_f32_e32 v95, v95, v101
	v_sub_f32_e32 v96, v96, v102
	v_sub_f32_e32 v97, v97, v103
	v_lshlrev_b32_e32 v100, 16, v56
	v_and_b32_e32 v101, 0xffff0000, v56
	v_lshlrev_b32_e32 v102, 16, v57
	v_and_b32_e32 v103, 0xffff0000, v57
	v_add_f32_e32 v94, v94, v100
	v_add_f32_e32 v95, v95, v101
	v_add_f32_e32 v96, v96, v102
	v_add_f32_e32 v97, v97, v103
	v_fma_f32 v100, v94, v119, -v100
	v_fma_f32 v101, v95, v119, -v101
	v_fma_f32 v102, v96, v119, -v102
	v_fma_f32 v103, v97, v119, -v103
	v_cvt_pk_bf16_f32 v110, v100, v101
	v_cvt_pk_bf16_f32 v111, v102, v103
	global_store_dwordx2 v122, v[110:111], s[70:71]
	s_add_u32 s70, s70, 0x800
	s_addc_u32 s71, s71, 0
	v_lshlrev_b32_e32 v100, 16, v54
	v_and_b32_e32 v101, 0xffff0000, v54
	v_lshlrev_b32_e32 v102, 16, v55
	v_and_b32_e32 v103, 0xffff0000, v55
	v_sub_f32_e32 v94, v94, v100
	v_sub_f32_e32 v95, v95, v101
	v_sub_f32_e32 v96, v96, v102
	v_sub_f32_e32 v97, v97, v103
	v_lshlrev_b32_e32 v100, 16, v58
	v_and_b32_e32 v101, 0xffff0000, v58
	v_lshlrev_b32_e32 v102, 16, v59
	v_and_b32_e32 v103, 0xffff0000, v59
	v_add_f32_e32 v94, v94, v100
	v_add_f32_e32 v95, v95, v101
	v_add_f32_e32 v96, v96, v102
	v_add_f32_e32 v97, v97, v103
	v_fma_f32 v100, v94, v119, -v100
	v_fma_f32 v101, v95, v119, -v101
	v_fma_f32 v102, v96, v119, -v102
	v_fma_f32 v103, v97, v119, -v103
	v_cvt_pk_bf16_f32 v108, v100, v101
	v_cvt_pk_bf16_f32 v109, v102, v103
	global_store_dwordx2 v122, v[108:109], s[70:71]
	s_add_u32 s70, s70, 0x800
	s_addc_u32 s71, s71, 0
	v_lshlrev_b32_e32 v100, 16, v56
	v_and_b32_e32 v101, 0xffff0000, v56
	v_lshlrev_b32_e32 v102, 16, v57
	v_and_b32_e32 v103, 0xffff0000, v57
	v_sub_f32_e32 v94, v94, v100
	v_sub_f32_e32 v95, v95, v101
	v_sub_f32_e32 v96, v96, v102
	v_sub_f32_e32 v97, v97, v103
	v_lshlrev_b32_e32 v100, 16, v60
	v_and_b32_e32 v101, 0xffff0000, v60
	v_lshlrev_b32_e32 v102, 16, v61
	v_and_b32_e32 v103, 0xffff0000, v61
	v_add_f32_e32 v94, v94, v100
	v_add_f32_e32 v95, v95, v101
	v_add_f32_e32 v96, v96, v102
	v_add_f32_e32 v97, v97, v103
	v_fma_f32 v100, v94, v119, -v100
	v_fma_f32 v101, v95, v119, -v101
	v_fma_f32 v102, v96, v119, -v102
	v_fma_f32 v103, v97, v119, -v103
	v_cvt_pk_bf16_f32 v110, v100, v101
	v_cvt_pk_bf16_f32 v111, v102, v103
	global_store_dwordx2 v122, v[110:111], s[70:71]
	s_add_u32 s70, s70, 0x800
	s_addc_u32 s71, s71, 0
	v_lshlrev_b32_e32 v100, 16, v58
	v_and_b32_e32 v101, 0xffff0000, v58
	v_lshlrev_b32_e32 v102, 16, v59
	v_and_b32_e32 v103, 0xffff0000, v59
	v_sub_f32_e32 v94, v94, v100
	v_sub_f32_e32 v95, v95, v101
	v_sub_f32_e32 v96, v96, v102
	v_sub_f32_e32 v97, v97, v103
	v_lshlrev_b32_e32 v100, 16, v62
	v_and_b32_e32 v101, 0xffff0000, v62
	v_lshlrev_b32_e32 v102, 16, v63
	v_and_b32_e32 v103, 0xffff0000, v63
	v_add_f32_e32 v94, v94, v100
	v_add_f32_e32 v95, v95, v101
	v_add_f32_e32 v96, v96, v102
	v_add_f32_e32 v97, v97, v103
	v_fma_f32 v100, v94, v119, -v100
	v_fma_f32 v101, v95, v119, -v101
	v_fma_f32 v102, v96, v119, -v102
	v_fma_f32 v103, v97, v119, -v103
	v_cvt_pk_bf16_f32 v108, v100, v101
	v_cvt_pk_bf16_f32 v109, v102, v103
	global_store_dwordx2 v122, v[108:109], s[70:71]
	s_add_u32 s70, s70, 0x800
	s_addc_u32 s71, s71, 0
	v_lshlrev_b32_e32 v100, 16, v60
	v_and_b32_e32 v101, 0xffff0000, v60
	v_lshlrev_b32_e32 v102, 16, v61
	v_and_b32_e32 v103, 0xffff0000, v61
	v_sub_f32_e32 v94, v94, v100
	v_sub_f32_e32 v95, v95, v101
	v_sub_f32_e32 v96, v96, v102
	v_sub_f32_e32 v97, v97, v103
	v_lshlrev_b32_e32 v100, 16, v64
	v_and_b32_e32 v101, 0xffff0000, v64
	v_lshlrev_b32_e32 v102, 16, v65
	v_and_b32_e32 v103, 0xffff0000, v65
	v_add_f32_e32 v94, v94, v100
	v_add_f32_e32 v95, v95, v101
	v_add_f32_e32 v96, v96, v102
	v_add_f32_e32 v97, v97, v103
	v_fma_f32 v100, v94, v119, -v100
	v_fma_f32 v101, v95, v119, -v101
	v_fma_f32 v102, v96, v119, -v102
	v_fma_f32 v103, v97, v119, -v103
	v_cvt_pk_bf16_f32 v110, v100, v101
	v_cvt_pk_bf16_f32 v111, v102, v103
	global_store_dwordx2 v122, v[110:111], s[70:71]
	s_branch .Lpl_done
.Lpl_w4:
	s_sub_u32 s4, s68, 0x6000
	s_subb_u32 s5, s69, 0
	global_load_dwordx2 v[0:1], v121, s[4:5]
	s_add_u32 s4, s4, 0x2000
	s_addc_u32 s5, s5, 0
	global_load_dwordx2 v[2:3], v121, s[4:5]
	s_add_u32 s4, s4, 0x2000
	s_addc_u32 s5, s5, 0
	global_load_dwordx2 v[4:5], v121, s[4:5]
	s_add_u32 s4, s4, 0x2000
	s_addc_u32 s5, s5, 0
	global_load_dwordx2 v[6:7], v121, s[4:5]
	s_add_u32 s4, s4, 0x2000
	s_addc_u32 s5, s5, 0
	global_load_dwordx2 v[8:9], v121, s[4:5]
	s_add_u32 s4, s4, 0x2000
	s_addc_u32 s5, s5, 0
	global_load_dwordx2 v[10:11], v121, s[4:5]
	s_add_u32 s4, s4, 0x2000
	s_addc_u32 s5, s5, 0
	global_load_dwordx2 v[12:13], v121, s[4:5]
	s_add_u32 s4, s4, 0x2000
	s_addc_u32 s5, s5, 0
	global_load_dwordx2 v[14:15], v121, s[4:5]
	s_add_u32 s4, s4, 0x2000
	s_addc_u32 s5, s5, 0
	global_load_dwordx2 v[16:17], v121, s[4:5]
	s_add_u32 s4, s4, 0x2000
	s_addc_u32 s5, s5, 0
	global_load_dwordx2 v[18:19], v121, s[4:5]
	s_add_u32 s4, s4, 0x2000
	s_addc_u32 s5, s5, 0
	global_load_dwordx2 v[20:21], v121, s[4:5]
	s_add_u32 s4, s4, 0x2000
	s_addc_u32 s5, s5, 0
	global_load_dwordx2 v[22:23], v121, s[4:5]
	s_add_u32 s4, s4, 0x2000
	s_addc_u32 s5, s5, 0
	global_load_dwordx2 v[24:25], v121, s[4:5]
	s_add_u32 s4, s4, 0x2000
	s_addc_u32 s5, s5, 0
	global_load_dwordx2 v[26:27], v121, s[4:5]
	s_add_u32 s4, s4, 0x2000
	s_addc_u32 s5, s5, 0
	global_load_dwordx2 v[28:29], v121, s[4:5]
	s_add_u32 s4, s4, 0x2000
	s_addc_u32 s5, s5, 0
	global_load_dwordx2 v[30:31], v121, s[4:5]
	s_add_u32 s4, s4, 0x2000
	s_addc_u32 s5, s5, 0
	global_load_dwordx2 v[32:33], v121, s[4:5]
	s_add_u32 s4, s4, 0x2000
	s_addc_u32 s5, s5, 0
	global_load_dwordx2 v[34:35], v121, s[4:5]
	s_add_u32 s4, s4, 0x2000
	s_addc_u32 s5, s5, 0
	global_load_dwordx2 v[36:37], v121, s[4:5]
	s_add_u32 s4, s4, 0x2000
	s_addc_u32 s5, s5, 0
	global_load_dwordx2 v[38:39], v121, s[4:5]
	s_add_u32 s4, s4, 0x2000
	s_addc_u32 s5, s5, 0
	global_load_dwordx2 v[40:41], v121, s[4:5]
	s_add_u32 s4, s4, 0x2000
	s_addc_u32 s5, s5, 0
	global_load_dwordx2 v[42:43], v121, s[4:5]
	s_add_u32 s4, s4, 0x2000
	s_addc_u32 s5, s5, 0
	global_load_dwordx2 v[44:45], v121, s[4:5]
	s_add_u32 s4, s4, 0x2000
	s_addc_u32 s5, s5, 0
	global_load_dwordx2 v[46:47], v121, s[4:5]
	s_add_u32 s4, s4, 0x2000
	s_addc_u32 s5, s5, 0
	global_load_dwordx2 v[48:49], v121, s[4:5]
	s_add_u32 s4, s4, 0x2000
	s_addc_u32 s5, s5, 0
	global_load_dwordx2 v[50:51], v121, s[4:5]
	s_add_u32 s4, s4, 0x2000
	s_addc_u32 s5, s5, 0
	global_load_dwordx2 v[52:53], v121, s[4:5]
	s_add_u32 s4, s4, 0x2000
	s_addc_u32 s5, s5, 0
	global_load_dwordx2 v[54:55], v121, s[4:5]
	s_add_u32 s4, s4, 0x2000
	s_addc_u32 s5, s5, 0
	global_load_dwordx2 v[56:57], v121, s[4:5]
	s_add_u32 s4, s4, 0x2000
	s_addc_u32 s5, s5, 0
	global_load_dwordx2 v[58:59], v121, s[4:5]
	s_add_u32 s4, s4, 0x2000
	s_addc_u32 s5, s5, 0
	global_load_dwordx2 v[60:61], v121, s[4:5]
	s_add_u32 s4, s4, 0x2000
	s_addc_u32 s5, s5, 0
	global_load_dwordx2 v[62:63], v121, s[4:5]
	s_add_u32 s4, s4, 0x2000
	s_addc_u32 s5, s5, 0
	global_load_dwordx2 v[64:65], v121, s[4:5]
	s_add_u32 s4, s4, 0x2000
	s_addc_u32 s5, s5, 0
	global_load_dwordx2 v[66:67], v121, s[4:5]
	s_add_u32 s4, s4, 0x2000
	s_addc_u32 s5, s5, 0
	global_load_dwordx2 v[68:69], v121, s[4:5]
	s_waitcnt vmcnt(0)
	v_cmp_le_u32_e32 vcc, 3, v120
	s_nop 1
	v_cndmask_b32_e32 v0, 0, v0, vcc
	v_cndmask_b32_e32 v1, 0, v1, vcc
	v_cmp_le_u32_e32 vcc, 2, v120
	s_nop 1
	v_cndmask_b32_e32 v2, 0, v2, vcc
	v_cndmask_b32_e32 v3, 0, v3, vcc
	v_cmp_le_u32_e32 vcc, 1, v120
	s_nop 1
	v_cndmask_b32_e32 v4, 0, v4, vcc
	v_cndmask_b32_e32 v5, 0, v5, vcc
	v_lshlrev_b32_e32 v94, 16, v0
	v_and_b32_e32 v95, 0xffff0000, v0
	v_lshlrev_b32_e32 v96, 16, v1
	v_and_b32_e32 v97, 0xffff0000, v1
	v_lshlrev_b32_e32 v100, 16, v2
	v_and_b32_e32 v101, 0xffff0000, v2
	v_lshlrev_b32_e32 v102, 16, v3
	v_and_b32_e32 v103, 0xffff0000, v3
	v_add_f32_e32 v94, v94, v100
	v_add_f32_e32 v95, v95, v101
	v_add_f32_e32 v96, v96, v102
	v_add_f32_e32 v97, v97, v103
	v_lshlrev_b32_e32 v100, 16, v4
	v_and_b32_e32 v101, 0xffff0000, v4
	v_lshlrev_b32_e32 v102, 16, v5
	v_and_b32_e32 v103, 0xffff0000, v5
	v_add_f32_e32 v94, v94, v100
	v_add_f32_e32 v95, v95, v101
	v_add_f32_e32 v96, v96, v102
	v_add_f32_e32 v97, v97, v103
	v_add_u32_e32 v123, 1, v120
	v_min_u32_e32 v123, 4, v123
	v_cvt_f32_u32_e32 v112, v123
	v_div_scale_f32 v113, s[72:73], v112, v112, v118
	v_rcp_f32_e32 v114, v113
	v_div_scale_f32 v115, vcc, v118, v112, v118
	v_fma_f32 v116, -v113, v114, 1.0
	v_fmac_f32_e32 v114, v116, v114
	v_mul_f32_e32 v116, v115, v114
	v_fma_f32 v117, -v113, v116, v115
	v_fmac_f32_e32 v116, v117, v114
	v_fma_f32 v113, -v113, v116, v115
	v_div_fmas_f32 v113, v113, v114, v116
	v_div_fixup_f32 v119, v113, v112, v118
	v_lshlrev_b32_e32 v100, 16, v6
	v_and_b32_e32 v101, 0xffff0000, v6
	v_lshlrev_b32_e32 v102, 16, v7
	v_and_b32_e32 v103, 0xffff0000, v7
	v_add_f32_e32 v94, v94, v100
	v_add_f32_e32 v95, v95, v101
	v_add_f32_e32 v96, v96, v102
	v_add_f32_e32 v97, v97, v103
	v_fma_f32 v100, v94, v119, -v100
	v_fma_f32 v101, v95, v119, -v101
	v_fma_f32 v102, v96, v119, -v102
	v_fma_f32 v103, v97, v119, -v103
	v_cvt_pk_bf16_f32 v108, v100, v101
	v_cvt_pk_bf16_f32 v109, v102, v103
	global_store_dwordx2 v122, v[108:109], s[70:71]
	s_add_u32 s70, s70, 0x800
	s_addc_u32 s71, s71, 0
	v_lshlrev_b32_e32 v100, 16, v0
	v_and_b32_e32 v101, 0xffff0000, v0
	v_lshlrev_b32_e32 v102, 16, v1
	v_and_b32_e32 v103, 0xffff0000, v1
	v_sub_f32_e32 v94, v94, v100
	v_sub_f32_e32 v95, v95, v101
	v_sub_f32_e32 v96, v96, v102
	v_sub_f32_e32 v97, v97, v103
	v_add_u32_e32 v123, 2, v120
	v_min_u32_e32 v123, 4, v123
	v_cvt_f32_u32_e32 v112, v123
	v_div_scale_f32 v113, s[72:73], v112, v112, v118
	v_rcp_f32_e32 v114, v113
	v_div_scale_f32 v115, vcc, v118, v112, v118
	v_fma_f32 v116, -v113, v114, 1.0
	v_fmac_f32_e32 v114, v116, v114
	v_mul_f32_e32 v116, v115, v114
	v_fma_f32 v117, -v113, v116, v115
	v_fmac_f32_e32 v116, v117, v114
	v_fma_f32 v113, -v113, v116, v115
	v_div_fmas_f32 v113, v113, v114, v116
	v_div_fixup_f32 v119, v113, v112, v118
	v_lshlrev_b32_e32 v100, 16, v8
	v_and_b32_e32 v101, 0xffff0000, v8
	v_lshlrev_b32_e32 v102, 16, v9
	v_and_b32_e32 v103, 0xffff0000, v9
	v_add_f32_e32 v94, v94, v100
	v_add_f32_e32 v95, v95, v101
	v_add_f32_e32 v96, v96, v102
	v_add_f32_e32 v97, v97, v103
	v_fma_f32 v100, v94, v119, -v100
	v_fma_f32 v101, v95, v119, -v101
	v_fma_f32 v102, v96, v119, -v102
	v_fma_f32 v103, v97, v119, -v103
	v_cvt_pk_bf16_f32 v110, v100, v101
	v_cvt_pk_bf16_f32 v111, v102, v103
	global_store_dwordx2 v122, v[110:111], s[70:71]
	s_add_u32 s70, s70, 0x800
	s_addc_u32 s71, s71, 0
	v_lshlrev_b32_e32 v100, 16, v2
	v_and_b32_e32 v101, 0xffff0000, v2
	v_lshlrev_b32_e32 v102, 16, v3
	v_and_b32_e32 v103, 0xffff0000, v3
	v_sub_f32_e32 v94, v94, v100
	v_sub_f32_e32 v95, v95, v101
	v_sub_f32_e32 v96, v96, v102
	v_sub_f32_e32 v97, v97, v103
	v_add_u32_e32 v123, 3, v120
	v_min_u32_e32 v123, 4, v123
	v_cvt_f32_u32_e32 v112, v123
	v_div_scale_f32 v113, s[72:73], v112, v112, v118
	v_rcp_f32_e32 v114, v113
	v_div_scale_f32 v115, vcc, v118, v112, v118
	v_fma_f32 v116, -v113, v114, 1.0
	v_fmac_f32_e32 v114, v116, v114
	v_mul_f32_e32 v116, v115, v114
	v_fma_f32 v117, -v113, v116, v115
	v_fmac_f32_e32 v116, v117, v114
	v_fma_f32 v113, -v113, v116, v115
	v_div_fmas_f32 v113, v113, v114, v116
	v_div_fixup_f32 v119, v113, v112, v118
	v_lshlrev_b32_e32 v100, 16, v10
	v_and_b32_e32 v101, 0xffff0000, v10
	v_lshlrev_b32_e32 v102, 16, v11
	v_and_b32_e32 v103, 0xffff0000, v11
	v_add_f32_e32 v94, v94, v100
	v_add_f32_e32 v95, v95, v101
	v_add_f32_e32 v96, v96, v102
	v_add_f32_e32 v97, v97, v103
	v_fma_f32 v100, v94, v119, -v100
	v_fma_f32 v101, v95, v119, -v101
	v_fma_f32 v102, v96, v119, -v102
	v_fma_f32 v103, v97, v119, -v103
	v_cvt_pk_bf16_f32 v108, v100, v101
	v_cvt_pk_bf16_f32 v109, v102, v103
	global_store_dwordx2 v122, v[108:109], s[70:71]
	s_add_u32 s70, s70, 0x800
	s_addc_u32 s71, s71, 0
	v_lshlrev_b32_e32 v100, 16, v4
	v_and_b32_e32 v101, 0xffff0000, v4
	v_lshlrev_b32_e32 v102, 16, v5
	v_and_b32_e32 v103, 0xffff0000, v5
	v_sub_f32_e32 v94, v94, v100
	v_sub_f32_e32 v95, v95, v101
	v_sub_f32_e32 v96, v96, v102
	v_sub_f32_e32 v97, v97, v103
	v_mov_b32_e32 v119, 0x3e800000
	v_lshlrev_b32_e32 v100, 16, v12
	v_and_b32_e32 v101, 0xffff0000, v12
	v_lshlrev_b32_e32 v102, 16, v13
	v_and_b32_e32 v103, 0xffff0000, v13
	v_add_f32_e32 v94, v94, v100
	v_add_f32_e32 v95, v95, v101
	v_add_f32_e32 v96, v96, v102
	v_add_f32_e32 v97, v97, v103
	v_fma_f32 v100, v94, v119, -v100
	v_fma_f32 v101, v95, v119, -v101
	v_fma_f32 v102, v96, v119, -v102
	v_fma_f32 v103, v97, v119, -v103
	v_cvt_pk_bf16_f32 v110, v100, v101
	v_cvt_pk_bf16_f32 v111, v102, v103
	global_store_dwordx2 v122, v[110:111], s[70:71]
	s_add_u32 s70, s70, 0x800
	s_addc_u32 s71, s71, 0
	v_lshlrev_b32_e32 v100, 16, v6
	v_and_b32_e32 v101, 0xffff0000, v6
	v_lshlrev_b32_e32 v102, 16, v7
	v_and_b32_e32 v103, 0xffff0000, v7
	v_sub_f32_e32 v94, v94, v100
	v_sub_f32_e32 v95, v95, v101
	v_sub_f32_e32 v96, v96, v102
	v_sub_f32_e32 v97, v97, v103
	v_lshlrev_b32_e32 v100, 16, v14
	v_and_b32_e32 v101, 0xffff0000, v14
	v_lshlrev_b32_e32 v102, 16, v15
	v_and_b32_e32 v103, 0xffff0000, v15
	v_add_f32_e32 v94, v94, v100
	v_add_f32_e32 v95, v95, v101
	v_add_f32_e32 v96, v96, v102
	v_add_f32_e32 v97, v97, v103
	v_fma_f32 v100, v94, v119, -v100
	v_fma_f32 v101, v95, v119, -v101
	v_fma_f32 v102, v96, v119, -v102
	v_fma_f32 v103, v97, v119, -v103
	v_cvt_pk_bf16_f32 v108, v100, v101
	v_cvt_pk_bf16_f32 v109, v102, v103
	global_store_dwordx2 v122, v[108:109], s[70:71]
	s_add_u32 s70, s70, 0x800
	s_addc_u32 s71, s71, 0
	v_lshlrev_b32_e32 v100, 16, v8
	v_and_b32_e32 v101, 0xffff0000, v8
	v_lshlrev_b32_e32 v102, 16, v9
	v_and_b32_e32 v103, 0xffff0000, v9
	v_sub_f32_e32 v94, v94, v100
	v_sub_f32_e32 v95, v95, v101
	v_sub_f32_e32 v96, v96, v102
	v_sub_f32_e32 v97, v97, v103
	v_lshlrev_b32_e32 v100, 16, v16
	v_and_b32_e32 v101, 0xffff0000, v16
	v_lshlrev_b32_e32 v102, 16, v17
	v_and_b32_e32 v103, 0xffff0000, v17
	v_add_f32_e32 v94, v94, v100
	v_add_f32_e32 v95, v95, v101
	v_add_f32_e32 v96, v96, v102
	v_add_f32_e32 v97, v97, v103
	v_fma_f32 v100, v94, v119, -v100
	v_fma_f32 v101, v95, v119, -v101
	v_fma_f32 v102, v96, v119, -v102
	v_fma_f32 v103, v97, v119, -v103
	v_cvt_pk_bf16_f32 v110, v100, v101
	v_cvt_pk_bf16_f32 v111, v102, v103
	global_store_dwordx2 v122, v[110:111], s[70:71]
	s_add_u32 s70, s70, 0x800
	s_addc_u32 s71, s71, 0
	v_lshlrev_b32_e32 v100, 16, v10
	v_and_b32_e32 v101, 0xffff0000, v10
	v_lshlrev_b32_e32 v102, 16, v11
	v_and_b32_e32 v103, 0xffff0000, v11
	v_sub_f32_e32 v94, v94, v100
	v_sub_f32_e32 v95, v95, v101
	v_sub_f32_e32 v96, v96, v102
	v_sub_f32_e32 v97, v97, v103
	v_lshlrev_b32_e32 v100, 16, v18
	v_and_b32_e32 v101, 0xffff0000, v18
	v_lshlrev_b32_e32 v102, 16, v19
	v_and_b32_e32 v103, 0xffff0000, v19
	v_add_f32_e32 v94, v94, v100
	v_add_f32_e32 v95, v95, v101
	v_add_f32_e32 v96, v96, v102
	v_add_f32_e32 v97, v97, v103
	v_fma_f32 v100, v94, v119, -v100
	v_fma_f32 v101, v95, v119, -v101
	v_fma_f32 v102, v96, v119, -v102
	v_fma_f32 v103, v97, v119, -v103
	v_cvt_pk_bf16_f32 v108, v100, v101
	v_cvt_pk_bf16_f32 v109, v102, v103
	global_store_dwordx2 v122, v[108:109], s[70:71]
	s_add_u32 s70, s70, 0x800
	s_addc_u32 s71, s71, 0
	v_lshlrev_b32_e32 v100, 16, v12
	v_and_b32_e32 v101, 0xffff0000, v12
	v_lshlrev_b32_e32 v102, 16, v13
	v_and_b32_e32 v103, 0xffff0000, v13
	v_sub_f32_e32 v94, v94, v100
	v_sub_f32_e32 v95, v95, v101
	v_sub_f32_e32 v96, v96, v102
	v_sub_f32_e32 v97, v97, v103
	v_lshlrev_b32_e32 v100, 16, v20
	v_and_b32_e32 v101, 0xffff0000, v20
	v_lshlrev_b32_e32 v102, 16, v21
	v_and_b32_e32 v103, 0xffff0000, v21
	v_add_f32_e32 v94, v94, v100
	v_add_f32_e32 v95, v95, v101
	v_add_f32_e32 v96, v96, v102
	v_add_f32_e32 v97, v97, v103
	v_fma_f32 v100, v94, v119, -v100
	v_fma_f32 v101, v95, v119, -v101
	v_fma_f32 v102, v96, v119, -v102
	v_fma_f32 v103, v97, v119, -v103
	v_cvt_pk_bf16_f32 v110, v100, v101
	v_cvt_pk_bf16_f32 v111, v102, v103
	global_store_dwordx2 v122, v[110:111], s[70:71]
	s_add_u32 s70, s70, 0x800
	s_addc_u32 s71, s71, 0
	v_lshlrev_b32_e32 v100, 16, v14
	v_and_b32_e32 v101, 0xffff0000, v14
	v_lshlrev_b32_e32 v102, 16, v15
	v_and_b32_e32 v103, 0xffff0000, v15
	v_sub_f32_e32 v94, v94, v100
	v_sub_f32_e32 v95, v95, v101
	v_sub_f32_e32 v96, v96, v102
	v_sub_f32_e32 v97, v97, v103
	v_lshlrev_b32_e32 v100, 16, v22
	v_and_b32_e32 v101, 0xffff0000, v22
	v_lshlrev_b32_e32 v102, 16, v23
	v_and_b32_e32 v103, 0xffff0000, v23
	v_add_f32_e32 v94, v94, v100
	v_add_f32_e32 v95, v95, v101
	v_add_f32_e32 v96, v96, v102
	v_add_f32_e32 v97, v97, v103
	v_fma_f32 v100, v94, v119, -v100
	v_fma_f32 v101, v95, v119, -v101
	v_fma_f32 v102, v96, v119, -v102
	v_fma_f32 v103, v97, v119, -v103
	v_cvt_pk_bf16_f32 v108, v100, v101
	v_cvt_pk_bf16_f32 v109, v102, v103
	global_store_dwordx2 v122, v[108:109], s[70:71]
	s_add_u32 s70, s70, 0x800
	s_addc_u32 s71, s71, 0
	v_lshlrev_b32_e32 v100, 16, v16
	v_and_b32_e32 v101, 0xffff0000, v16
	v_lshlrev_b32_e32 v102, 16, v17
	v_and_b32_e32 v103, 0xffff0000, v17
	v_sub_f32_e32 v94, v94, v100
	v_sub_f32_e32 v95, v95, v101
	v_sub_f32_e32 v96, v96, v102
	v_sub_f32_e32 v97, v97, v103
	v_lshlrev_b32_e32 v100, 16, v24
	v_and_b32_e32 v101, 0xffff0000, v24
	v_lshlrev_b32_e32 v102, 16, v25
	v_and_b32_e32 v103, 0xffff0000, v25
	v_add_f32_e32 v94, v94, v100
	v_add_f32_e32 v95, v95, v101
	v_add_f32_e32 v96, v96, v102
	v_add_f32_e32 v97, v97, v103
	v_fma_f32 v100, v94, v119, -v100
	v_fma_f32 v101, v95, v119, -v101
	v_fma_f32 v102, v96, v119, -v102
	v_fma_f32 v103, v97, v119, -v103
	v_cvt_pk_bf16_f32 v110, v100, v101
	v_cvt_pk_bf16_f32 v111, v102, v103
	global_store_dwordx2 v122, v[110:111], s[70:71]
	s_add_u32 s70, s70, 0x800
	s_addc_u32 s71, s71, 0
	v_lshlrev_b32_e32 v100, 16, v18
	v_and_b32_e32 v101, 0xffff0000, v18
	v_lshlrev_b32_e32 v102, 16, v19
	v_and_b32_e32 v103, 0xffff0000, v19
	v_sub_f32_e32 v94, v94, v100
	v_sub_f32_e32 v95, v95, v101
	v_sub_f32_e32 v96, v96, v102
	v_sub_f32_e32 v97, v97, v103
	v_lshlrev_b32_e32 v100, 16, v26
	v_and_b32_e32 v101, 0xffff0000, v26
	v_lshlrev_b32_e32 v102, 16, v27
	v_and_b32_e32 v103, 0xffff0000, v27
	v_add_f32_e32 v94, v94, v100
	v_add_f32_e32 v95, v95, v101
	v_add_f32_e32 v96, v96, v102
	v_add_f32_e32 v97, v97, v103
	v_fma_f32 v100, v94, v119, -v100
	v_fma_f32 v101, v95, v119, -v101
	v_fma_f32 v102, v96, v119, -v102
	v_fma_f32 v103, v97, v119, -v103
	v_cvt_pk_bf16_f32 v108, v100, v101
	v_cvt_pk_bf16_f32 v109, v102, v103
	global_store_dwordx2 v122, v[108:109], s[70:71]
	s_add_u32 s70, s70, 0x800
	s_addc_u32 s71, s71, 0
	v_lshlrev_b32_e32 v100, 16, v20
	v_and_b32_e32 v101, 0xffff0000, v20
	v_lshlrev_b32_e32 v102, 16, v21
	v_and_b32_e32 v103, 0xffff0000, v21
	v_sub_f32_e32 v94, v94, v100
	v_sub_f32_e32 v95, v95, v101
	v_sub_f32_e32 v96, v96, v102
	v_sub_f32_e32 v97, v97, v103
	v_lshlrev_b32_e32 v100, 16, v28
	v_and_b32_e32 v101, 0xffff0000, v28
	v_lshlrev_b32_e32 v102, 16, v29
	v_and_b32_e32 v103, 0xffff0000, v29
	v_add_f32_e32 v94, v94, v100
	v_add_f32_e32 v95, v95, v101
	v_add_f32_e32 v96, v96, v102
	v_add_f32_e32 v97, v97, v103
	v_fma_f32 v100, v94, v119, -v100
	v_fma_f32 v101, v95, v119, -v101
	v_fma_f32 v102, v96, v119, -v102
	v_fma_f32 v103, v97, v119, -v103
	v_cvt_pk_bf16_f32 v110, v100, v101
	v_cvt_pk_bf16_f32 v111, v102, v103
	global_store_dwordx2 v122, v[110:111], s[70:71]
	s_add_u32 s70, s70, 0x800
	s_addc_u32 s71, s71, 0
	v_lshlrev_b32_e32 v100, 16, v22
	v_and_b32_e32 v101, 0xffff0000, v22
	v_lshlrev_b32_e32 v102, 16, v23
	v_and_b32_e32 v103, 0xffff0000, v23
	v_sub_f32_e32 v94, v94, v100
	v_sub_f32_e32 v95, v95, v101
	v_sub_f32_e32 v96, v96, v102
	v_sub_f32_e32 v97, v97, v103
	v_lshlrev_b32_e32 v100, 16, v30
	v_and_b32_e32 v101, 0xffff0000, v30
	v_lshlrev_b32_e32 v102, 16, v31
	v_and_b32_e32 v103, 0xffff0000, v31
	v_add_f32_e32 v94, v94, v100
	v_add_f32_e32 v95, v95, v101
	v_add_f32_e32 v96, v96, v102
	v_add_f32_e32 v97, v97, v103
	v_fma_f32 v100, v94, v119, -v100
	v_fma_f32 v101, v95, v119, -v101
	v_fma_f32 v102, v96, v119, -v102
	v_fma_f32 v103, v97, v119, -v103
	v_cvt_pk_bf16_f32 v108, v100, v101
	v_cvt_pk_bf16_f32 v109, v102, v103
	global_store_dwordx2 v122, v[108:109], s[70:71]
	s_add_u32 s70, s70, 0x800
	s_addc_u32 s71, s71, 0
	v_lshlrev_b32_e32 v100, 16, v24
	v_and_b32_e32 v101, 0xffff0000, v24
	v_lshlrev_b32_e32 v102, 16, v25
	v_and_b32_e32 v103, 0xffff0000, v25
	v_sub_f32_e32 v94, v94, v100
	v_sub_f32_e32 v95, v95, v101
	v_sub_f32_e32 v96, v96, v102
	v_sub_f32_e32 v97, v97, v103
	v_lshlrev_b32_e32 v100, 16, v32
	v_and_b32_e32 v101, 0xffff0000, v32
	v_lshlrev_b32_e32 v102, 16, v33
	v_and_b32_e32 v103, 0xffff0000, v33
	v_add_f32_e32 v94, v94, v100
	v_add_f32_e32 v95, v95, v101
	v_add_f32_e32 v96, v96, v102
	v_add_f32_e32 v97, v97, v103
	v_fma_f32 v100, v94, v119, -v100
	v_fma_f32 v101, v95, v119, -v101
	v_fma_f32 v102, v96, v119, -v102
	v_fma_f32 v103, v97, v119, -v103
	v_cvt_pk_bf16_f32 v110, v100, v101
	v_cvt_pk_bf16_f32 v111, v102, v103
	global_store_dwordx2 v122, v[110:111], s[70:71]
	s_add_u32 s70, s70, 0x800
	s_addc_u32 s71, s71, 0
	v_lshlrev_b32_e32 v100, 16, v26
	v_and_b32_e32 v101, 0xffff0000, v26
	v_lshlrev_b32_e32 v102, 16, v27
	v_and_b32_e32 v103, 0xffff0000, v27
	v_sub_f32_e32 v94, v94, v100
	v_sub_f32_e32 v95, v95, v101
	v_sub_f32_e32 v96, v96, v102
	v_sub_f32_e32 v97, v97, v103
	v_lshlrev_b32_e32 v100, 16, v34
	v_and_b32_e32 v101, 0xffff0000, v34
	v_lshlrev_b32_e32 v102, 16, v35
	v_and_b32_e32 v103, 0xffff0000, v35
	v_add_f32_e32 v94, v94, v100
	v_add_f32_e32 v95, v95, v101
	v_add_f32_e32 v96, v96, v102
	v_add_f32_e32 v97, v97, v103
	v_fma_f32 v100, v94, v119, -v100
	v_fma_f32 v101, v95, v119, -v101
	v_fma_f32 v102, v96, v119, -v102
	v_fma_f32 v103, v97, v119, -v103
	v_cvt_pk_bf16_f32 v108, v100, v101
	v_cvt_pk_bf16_f32 v109, v102, v103
	global_store_dwordx2 v122, v[108:109], s[70:71]
	s_add_u32 s70, s70, 0x800
	s_addc_u32 s71, s71, 0
	v_lshlrev_b32_e32 v100, 16, v28
	v_and_b32_e32 v101, 0xffff0000, v28
	v_lshlrev_b32_e32 v102, 16, v29
	v_and_b32_e32 v103, 0xffff0000, v29
	v_sub_f32_e32 v94, v94, v100
	v_sub_f32_e32 v95, v95, v101
	v_sub_f32_e32 v96, v96, v102
	v_sub_f32_e32 v97, v97, v103
	v_lshlrev_b32_e32 v100, 16, v36
	v_and_b32_e32 v101, 0xffff0000, v36
	v_lshlrev_b32_e32 v102, 16, v37
	v_and_b32_e32 v103, 0xffff0000, v37
	v_add_f32_e32 v94, v94, v100
	v_add_f32_e32 v95, v95, v101
	v_add_f32_e32 v96, v96, v102
	v_add_f32_e32 v97, v97, v103
	v_fma_f32 v100, v94, v119, -v100
	v_fma_f32 v101, v95, v119, -v101
	v_fma_f32 v102, v96, v119, -v102
	v_fma_f32 v103, v97, v119, -v103
	v_cvt_pk_bf16_f32 v110, v100, v101
	v_cvt_pk_bf16_f32 v111, v102, v103
	global_store_dwordx2 v122, v[110:111], s[70:71]
	s_add_u32 s70, s70, 0x800
	s_addc_u32 s71, s71, 0
	v_lshlrev_b32_e32 v100, 16, v30
	v_and_b32_e32 v101, 0xffff0000, v30
	v_lshlrev_b32_e32 v102, 16, v31
	v_and_b32_e32 v103, 0xffff0000, v31
	v_sub_f32_e32 v94, v94, v100
	v_sub_f32_e32 v95, v95, v101
	v_sub_f32_e32 v96, v96, v102
	v_sub_f32_e32 v97, v97, v103
	v_lshlrev_b32_e32 v100, 16, v38
	v_and_b32_e32 v101, 0xffff0000, v38
	v_lshlrev_b32_e32 v102, 16, v39
	v_and_b32_e32 v103, 0xffff0000, v39
	v_add_f32_e32 v94, v94, v100
	v_add_f32_e32 v95, v95, v101
	v_add_f32_e32 v96, v96, v102
	v_add_f32_e32 v97, v97, v103
	v_fma_f32 v100, v94, v119, -v100
	v_fma_f32 v101, v95, v119, -v101
	v_fma_f32 v102, v96, v119, -v102
	v_fma_f32 v103, v97, v119, -v103
	v_cvt_pk_bf16_f32 v108, v100, v101
	v_cvt_pk_bf16_f32 v109, v102, v103
	global_store_dwordx2 v122, v[108:109], s[70:71]
	s_add_u32 s70, s70, 0x800
	s_addc_u32 s71, s71, 0
	v_lshlrev_b32_e32 v100, 16, v32
	v_and_b32_e32 v101, 0xffff0000, v32
	v_lshlrev_b32_e32 v102, 16, v33
	v_and_b32_e32 v103, 0xffff0000, v33
	v_sub_f32_e32 v94, v94, v100
	v_sub_f32_e32 v95, v95, v101
	v_sub_f32_e32 v96, v96, v102
	v_sub_f32_e32 v97, v97, v103
	v_lshlrev_b32_e32 v100, 16, v40
	v_and_b32_e32 v101, 0xffff0000, v40
	v_lshlrev_b32_e32 v102, 16, v41
	v_and_b32_e32 v103, 0xffff0000, v41
	v_add_f32_e32 v94, v94, v100
	v_add_f32_e32 v95, v95, v101
	v_add_f32_e32 v96, v96, v102
	v_add_f32_e32 v97, v97, v103
	v_fma_f32 v100, v94, v119, -v100
	v_fma_f32 v101, v95, v119, -v101
	v_fma_f32 v102, v96, v119, -v102
	v_fma_f32 v103, v97, v119, -v103
	v_cvt_pk_bf16_f32 v110, v100, v101
	v_cvt_pk_bf16_f32 v111, v102, v103
	global_store_dwordx2 v122, v[110:111], s[70:71]
	s_add_u32 s70, s70, 0x800
	s_addc_u32 s71, s71, 0
	v_lshlrev_b32_e32 v100, 16, v34
	v_and_b32_e32 v101, 0xffff0000, v34
	v_lshlrev_b32_e32 v102, 16, v35
	v_and_b32_e32 v103, 0xffff0000, v35
	v_sub_f32_e32 v94, v94, v100
	v_sub_f32_e32 v95, v95, v101
	v_sub_f32_e32 v96, v96, v102
	v_sub_f32_e32 v97, v97, v103
	v_lshlrev_b32_e32 v100, 16, v42
	v_and_b32_e32 v101, 0xffff0000, v42
	v_lshlrev_b32_e32 v102, 16, v43
	v_and_b32_e32 v103, 0xffff0000, v43
	v_add_f32_e32 v94, v94, v100
	v_add_f32_e32 v95, v95, v101
	v_add_f32_e32 v96, v96, v102
	v_add_f32_e32 v97, v97, v103
	v_fma_f32 v100, v94, v119, -v100
	v_fma_f32 v101, v95, v119, -v101
	v_fma_f32 v102, v96, v119, -v102
	v_fma_f32 v103, v97, v119, -v103
	v_cvt_pk_bf16_f32 v108, v100, v101
	v_cvt_pk_bf16_f32 v109, v102, v103
	global_store_dwordx2 v122, v[108:109], s[70:71]
	s_add_u32 s70, s70, 0x800
	s_addc_u32 s71, s71, 0
	v_lshlrev_b32_e32 v100, 16, v36
	v_and_b32_e32 v101, 0xffff0000, v36
	v_lshlrev_b32_e32 v102, 16, v37
	v_and_b32_e32 v103, 0xffff0000, v37
	v_sub_f32_e32 v94, v94, v100
	v_sub_f32_e32 v95, v95, v101
	v_sub_f32_e32 v96, v96, v102
	v_sub_f32_e32 v97, v97, v103
	v_lshlrev_b32_e32 v100, 16, v44
	v_and_b32_e32 v101, 0xffff0000, v44
	v_lshlrev_b32_e32 v102, 16, v45
	v_and_b32_e32 v103, 0xffff0000, v45
	v_add_f32_e32 v94, v94, v100
	v_add_f32_e32 v95, v95, v101
	v_add_f32_e32 v96, v96, v102
	v_add_f32_e32 v97, v97, v103
	v_fma_f32 v100, v94, v119, -v100
	v_fma_f32 v101, v95, v119, -v101
	v_fma_f32 v102, v96, v119, -v102
	v_fma_f32 v103, v97, v119, -v103
	v_cvt_pk_bf16_f32 v110, v100, v101
	v_cvt_pk_bf16_f32 v111, v102, v103
	global_store_dwordx2 v122, v[110:111], s[70:71]
	s_add_u32 s70, s70, 0x800
	s_addc_u32 s71, s71, 0
	v_lshlrev_b32_e32 v100, 16, v38
	v_and_b32_e32 v101, 0xffff0000, v38
	v_lshlrev_b32_e32 v102, 16, v39
	v_and_b32_e32 v103, 0xffff0000, v39
	v_sub_f32_e32 v94, v94, v100
	v_sub_f32_e32 v95, v95, v101
	v_sub_f32_e32 v96, v96, v102
	v_sub_f32_e32 v97, v97, v103
	v_lshlrev_b32_e32 v100, 16, v46
	v_and_b32_e32 v101, 0xffff0000, v46
	v_lshlrev_b32_e32 v102, 16, v47
	v_and_b32_e32 v103, 0xffff0000, v47
	v_add_f32_e32 v94, v94, v100
	v_add_f32_e32 v95, v95, v101
	v_add_f32_e32 v96, v96, v102
	v_add_f32_e32 v97, v97, v103
	v_fma_f32 v100, v94, v119, -v100
	v_fma_f32 v101, v95, v119, -v101
	v_fma_f32 v102, v96, v119, -v102
	v_fma_f32 v103, v97, v119, -v103
	v_cvt_pk_bf16_f32 v108, v100, v101
	v_cvt_pk_bf16_f32 v109, v102, v103
	global_store_dwordx2 v122, v[108:109], s[70:71]
	s_add_u32 s70, s70, 0x800
	s_addc_u32 s71, s71, 0
	v_lshlrev_b32_e32 v100, 16, v40
	v_and_b32_e32 v101, 0xffff0000, v40
	v_lshlrev_b32_e32 v102, 16, v41
	v_and_b32_e32 v103, 0xffff0000, v41
	v_sub_f32_e32 v94, v94, v100
	v_sub_f32_e32 v95, v95, v101
	v_sub_f32_e32 v96, v96, v102
	v_sub_f32_e32 v97, v97, v103
	v_lshlrev_b32_e32 v100, 16, v48
	v_and_b32_e32 v101, 0xffff0000, v48
	v_lshlrev_b32_e32 v102, 16, v49
	v_and_b32_e32 v103, 0xffff0000, v49
	v_add_f32_e32 v94, v94, v100
	v_add_f32_e32 v95, v95, v101
	v_add_f32_e32 v96, v96, v102
	v_add_f32_e32 v97, v97, v103
	v_fma_f32 v100, v94, v119, -v100
	v_fma_f32 v101, v95, v119, -v101
	v_fma_f32 v102, v96, v119, -v102
	v_fma_f32 v103, v97, v119, -v103
	v_cvt_pk_bf16_f32 v110, v100, v101
	v_cvt_pk_bf16_f32 v111, v102, v103
	global_store_dwordx2 v122, v[110:111], s[70:71]
	s_add_u32 s70, s70, 0x800
	s_addc_u32 s71, s71, 0
	v_lshlrev_b32_e32 v100, 16, v42
	v_and_b32_e32 v101, 0xffff0000, v42
	v_lshlrev_b32_e32 v102, 16, v43
	v_and_b32_e32 v103, 0xffff0000, v43
	v_sub_f32_e32 v94, v94, v100
	v_sub_f32_e32 v95, v95, v101
	v_sub_f32_e32 v96, v96, v102
	v_sub_f32_e32 v97, v97, v103
	v_lshlrev_b32_e32 v100, 16, v50
	v_and_b32_e32 v101, 0xffff0000, v50
	v_lshlrev_b32_e32 v102, 16, v51
	v_and_b32_e32 v103, 0xffff0000, v51
	v_add_f32_e32 v94, v94, v100
	v_add_f32_e32 v95, v95, v101
	v_add_f32_e32 v96, v96, v102
	v_add_f32_e32 v97, v97, v103
	v_fma_f32 v100, v94, v119, -v100
	v_fma_f32 v101, v95, v119, -v101
	v_fma_f32 v102, v96, v119, -v102
	v_fma_f32 v103, v97, v119, -v103
	v_cvt_pk_bf16_f32 v108, v100, v101
	v_cvt_pk_bf16_f32 v109, v102, v103
	global_store_dwordx2 v122, v[108:109], s[70:71]
	s_add_u32 s70, s70, 0x800
	s_addc_u32 s71, s71, 0
	v_lshlrev_b32_e32 v100, 16, v44
	v_and_b32_e32 v101, 0xffff0000, v44
	v_lshlrev_b32_e32 v102, 16, v45
	v_and_b32_e32 v103, 0xffff0000, v45
	v_sub_f32_e32 v94, v94, v100
	v_sub_f32_e32 v95, v95, v101
	v_sub_f32_e32 v96, v96, v102
	v_sub_f32_e32 v97, v97, v103
	v_lshlrev_b32_e32 v100, 16, v52
	v_and_b32_e32 v101, 0xffff0000, v52
	v_lshlrev_b32_e32 v102, 16, v53
	v_and_b32_e32 v103, 0xffff0000, v53
	v_add_f32_e32 v94, v94, v100
	v_add_f32_e32 v95, v95, v101
	v_add_f32_e32 v96, v96, v102
	v_add_f32_e32 v97, v97, v103
	v_fma_f32 v100, v94, v119, -v100
	v_fma_f32 v101, v95, v119, -v101
	v_fma_f32 v102, v96, v119, -v102
	v_fma_f32 v103, v97, v119, -v103
	v_cvt_pk_bf16_f32 v110, v100, v101
	v_cvt_pk_bf16_f32 v111, v102, v103
	global_store_dwordx2 v122, v[110:111], s[70:71]
	s_add_u32 s70, s70, 0x800
	s_addc_u32 s71, s71, 0
	v_lshlrev_b32_e32 v100, 16, v46
	v_and_b32_e32 v101, 0xffff0000, v46
	v_lshlrev_b32_e32 v102, 16, v47
	v_and_b32_e32 v103, 0xffff0000, v47
	v_sub_f32_e32 v94, v94, v100
	v_sub_f32_e32 v95, v95, v101
	v_sub_f32_e32 v96, v96, v102
	v_sub_f32_e32 v97, v97, v103
	v_lshlrev_b32_e32 v100, 16, v54
	v_and_b32_e32 v101, 0xffff0000, v54
	v_lshlrev_b32_e32 v102, 16, v55
	v_and_b32_e32 v103, 0xffff0000, v55
	v_add_f32_e32 v94, v94, v100
	v_add_f32_e32 v95, v95, v101
	v_add_f32_e32 v96, v96, v102
	v_add_f32_e32 v97, v97, v103
	v_fma_f32 v100, v94, v119, -v100
	v_fma_f32 v101, v95, v119, -v101
	v_fma_f32 v102, v96, v119, -v102
	v_fma_f32 v103, v97, v119, -v103
	v_cvt_pk_bf16_f32 v108, v100, v101
	v_cvt_pk_bf16_f32 v109, v102, v103
	global_store_dwordx2 v122, v[108:109], s[70:71]
	s_add_u32 s70, s70, 0x800
	s_addc_u32 s71, s71, 0
	v_lshlrev_b32_e32 v100, 16, v48
	v_and_b32_e32 v101, 0xffff0000, v48
	v_lshlrev_b32_e32 v102, 16, v49
	v_and_b32_e32 v103, 0xffff0000, v49
	v_sub_f32_e32 v94, v94, v100
	v_sub_f32_e32 v95, v95, v101
	v_sub_f32_e32 v96, v96, v102
	v_sub_f32_e32 v97, v97, v103
	v_lshlrev_b32_e32 v100, 16, v56
	v_and_b32_e32 v101, 0xffff0000, v56
	v_lshlrev_b32_e32 v102, 16, v57
	v_and_b32_e32 v103, 0xffff0000, v57
	v_add_f32_e32 v94, v94, v100
	v_add_f32_e32 v95, v95, v101
	v_add_f32_e32 v96, v96, v102
	v_add_f32_e32 v97, v97, v103
	v_fma_f32 v100, v94, v119, -v100
	v_fma_f32 v101, v95, v119, -v101
	v_fma_f32 v102, v96, v119, -v102
	v_fma_f32 v103, v97, v119, -v103
	v_cvt_pk_bf16_f32 v110, v100, v101
	v_cvt_pk_bf16_f32 v111, v102, v103
	global_store_dwordx2 v122, v[110:111], s[70:71]
	s_add_u32 s70, s70, 0x800
	s_addc_u32 s71, s71, 0
	v_lshlrev_b32_e32 v100, 16, v50
	v_and_b32_e32 v101, 0xffff0000, v50
	v_lshlrev_b32_e32 v102, 16, v51
	v_and_b32_e32 v103, 0xffff0000, v51
	v_sub_f32_e32 v94, v94, v100
	v_sub_f32_e32 v95, v95, v101
	v_sub_f32_e32 v96, v96, v102
	v_sub_f32_e32 v97, v97, v103
	v_lshlrev_b32_e32 v100, 16, v58
	v_and_b32_e32 v101, 0xffff0000, v58
	v_lshlrev_b32_e32 v102, 16, v59
	v_and_b32_e32 v103, 0xffff0000, v59
	v_add_f32_e32 v94, v94, v100
	v_add_f32_e32 v95, v95, v101
	v_add_f32_e32 v96, v96, v102
	v_add_f32_e32 v97, v97, v103
	v_fma_f32 v100, v94, v119, -v100
	v_fma_f32 v101, v95, v119, -v101
	v_fma_f32 v102, v96, v119, -v102
	v_fma_f32 v103, v97, v119, -v103
	v_cvt_pk_bf16_f32 v108, v100, v101
	v_cvt_pk_bf16_f32 v109, v102, v103
	global_store_dwordx2 v122, v[108:109], s[70:71]
	s_add_u32 s70, s70, 0x800
	s_addc_u32 s71, s71, 0
	v_lshlrev_b32_e32 v100, 16, v52
	v_and_b32_e32 v101, 0xffff0000, v52
	v_lshlrev_b32_e32 v102, 16, v53
	v_and_b32_e32 v103, 0xffff0000, v53
	v_sub_f32_e32 v94, v94, v100
	v_sub_f32_e32 v95, v95, v101
	v_sub_f32_e32 v96, v96, v102
	v_sub_f32_e32 v97, v97, v103
	v_lshlrev_b32_e32 v100, 16, v60
	v_and_b32_e32 v101, 0xffff0000, v60
	v_lshlrev_b32_e32 v102, 16, v61
	v_and_b32_e32 v103, 0xffff0000, v61
	v_add_f32_e32 v94, v94, v100
	v_add_f32_e32 v95, v95, v101
	v_add_f32_e32 v96, v96, v102
	v_add_f32_e32 v97, v97, v103
	v_fma_f32 v100, v94, v119, -v100
	v_fma_f32 v101, v95, v119, -v101
	v_fma_f32 v102, v96, v119, -v102
	v_fma_f32 v103, v97, v119, -v103
	v_cvt_pk_bf16_f32 v110, v100, v101
	v_cvt_pk_bf16_f32 v111, v102, v103
	global_store_dwordx2 v122, v[110:111], s[70:71]
	s_add_u32 s70, s70, 0x800
	s_addc_u32 s71, s71, 0
	v_lshlrev_b32_e32 v100, 16, v54
	v_and_b32_e32 v101, 0xffff0000, v54
	v_lshlrev_b32_e32 v102, 16, v55
	v_and_b32_e32 v103, 0xffff0000, v55
	v_sub_f32_e32 v94, v94, v100
	v_sub_f32_e32 v95, v95, v101
	v_sub_f32_e32 v96, v96, v102
	v_sub_f32_e32 v97, v97, v103
	v_lshlrev_b32_e32 v100, 16, v62
	v_and_b32_e32 v101, 0xffff0000, v62
	v_lshlrev_b32_e32 v102, 16, v63
	v_and_b32_e32 v103, 0xffff0000, v63
	v_add_f32_e32 v94, v94, v100
	v_add_f32_e32 v95, v95, v101
	v_add_f32_e32 v96, v96, v102
	v_add_f32_e32 v97, v97, v103
	v_fma_f32 v100, v94, v119, -v100
	v_fma_f32 v101, v95, v119, -v101
	v_fma_f32 v102, v96, v119, -v102
	v_fma_f32 v103, v97, v119, -v103
	v_cvt_pk_bf16_f32 v108, v100, v101
	v_cvt_pk_bf16_f32 v109, v102, v103
	global_store_dwordx2 v122, v[108:109], s[70:71]
	s_add_u32 s70, s70, 0x800
	s_addc_u32 s71, s71, 0
	v_lshlrev_b32_e32 v100, 16, v56
	v_and_b32_e32 v101, 0xffff0000, v56
	v_lshlrev_b32_e32 v102, 16, v57
	v_and_b32_e32 v103, 0xffff0000, v57
	v_sub_f32_e32 v94, v94, v100
	v_sub_f32_e32 v95, v95, v101
	v_sub_f32_e32 v96, v96, v102
	v_sub_f32_e32 v97, v97, v103
	v_lshlrev_b32_e32 v100, 16, v64
	v_and_b32_e32 v101, 0xffff0000, v64
	v_lshlrev_b32_e32 v102, 16, v65
	v_and_b32_e32 v103, 0xffff0000, v65
	v_add_f32_e32 v94, v94, v100
	v_add_f32_e32 v95, v95, v101
	v_add_f32_e32 v96, v96, v102
	v_add_f32_e32 v97, v97, v103
	v_fma_f32 v100, v94, v119, -v100
	v_fma_f32 v101, v95, v119, -v101
	v_fma_f32 v102, v96, v119, -v102
	v_fma_f32 v103, v97, v119, -v103
	v_cvt_pk_bf16_f32 v110, v100, v101
	v_cvt_pk_bf16_f32 v111, v102, v103
	global_store_dwordx2 v122, v[110:111], s[70:71]
	s_add_u32 s70, s70, 0x800
	s_addc_u32 s71, s71, 0
	v_lshlrev_b32_e32 v100, 16, v58
	v_and_b32_e32 v101, 0xffff0000, v58
	v_lshlrev_b32_e32 v102, 16, v59
	v_and_b32_e32 v103, 0xffff0000, v59
	v_sub_f32_e32 v94, v94, v100
	v_sub_f32_e32 v95, v95, v101
	v_sub_f32_e32 v96, v96, v102
	v_sub_f32_e32 v97, v97, v103
	v_lshlrev_b32_e32 v100, 16, v66
	v_and_b32_e32 v101, 0xffff0000, v66
	v_lshlrev_b32_e32 v102, 16, v67
	v_and_b32_e32 v103, 0xffff0000, v67
	v_add_f32_e32 v94, v94, v100
	v_add_f32_e32 v95, v95, v101
	v_add_f32_e32 v96, v96, v102
	v_add_f32_e32 v97, v97, v103
	v_fma_f32 v100, v94, v119, -v100
	v_fma_f32 v101, v95, v119, -v101
	v_fma_f32 v102, v96, v119, -v102
	v_fma_f32 v103, v97, v119, -v103
	v_cvt_pk_bf16_f32 v108, v100, v101
	v_cvt_pk_bf16_f32 v109, v102, v103
	global_store_dwordx2 v122, v[108:109], s[70:71]
	s_add_u32 s70, s70, 0x800
	s_addc_u32 s71, s71, 0
	v_lshlrev_b32_e32 v100, 16, v60
	v_and_b32_e32 v101, 0xffff0000, v60
	v_lshlrev_b32_e32 v102, 16, v61
	v_and_b32_e32 v103, 0xffff0000, v61
	v_sub_f32_e32 v94, v94, v100
	v_sub_f32_e32 v95, v95, v101
	v_sub_f32_e32 v96, v96, v102
	v_sub_f32_e32 v97, v97, v103
	v_lshlrev_b32_e32 v100, 16, v68
	v_and_b32_e32 v101, 0xffff0000, v68
	v_lshlrev_b32_e32 v102, 16, v69
	v_and_b32_e32 v103, 0xffff0000, v69
	v_add_f32_e32 v94, v94, v100
	v_add_f32_e32 v95, v95, v101
	v_add_f32_e32 v96, v96, v102
	v_add_f32_e32 v97, v97, v103
	v_fma_f32 v100, v94, v119, -v100
	v_fma_f32 v101, v95, v119, -v101
	v_fma_f32 v102, v96, v119, -v102
	v_fma_f32 v103, v97, v119, -v103
	v_cvt_pk_bf16_f32 v110, v100, v101
	v_cvt_pk_bf16_f32 v111, v102, v103
	global_store_dwordx2 v122, v[110:111], s[70:71]
	s_branch .Lpl_done
.Lpl_w8:
	s_sub_u32 s4, s68, 0xe000
	s_subb_u32 s5, s69, 0
	global_load_dwordx2 v[0:1], v121, s[4:5]
	s_add_u32 s4, s4, 0x2000
	s_addc_u32 s5, s5, 0
	global_load_dwordx2 v[2:3], v121, s[4:5]
	s_add_u32 s4, s4, 0x2000
	s_addc_u32 s5, s5, 0
	global_load_dwordx2 v[4:5], v121, s[4:5]
	s_add_u32 s4, s4, 0x2000
	s_addc_u32 s5, s5, 0
	global_load_dwordx2 v[6:7], v121, s[4:5]
	s_add_u32 s4, s4, 0x2000
	s_addc_u32 s5, s5, 0
	global_load_dwordx2 v[8:9], v121, s[4:5]
	s_add_u32 s4, s4, 0x2000
	s_addc_u32 s5, s5, 0
	global_load_dwordx2 v[10:11], v121, s[4:5]
	s_add_u32 s4, s4, 0x2000
	s_addc_u32 s5, s5, 0
	global_load_dwordx2 v[12:13], v121, s[4:5]
	s_add_u32 s4, s4, 0x2000
	s_addc_u32 s5, s5, 0
	global_load_dwordx2 v[14:15], v121, s[4:5]
	s_add_u32 s4, s4, 0x2000
	s_addc_u32 s5, s5, 0
	global_load_dwordx2 v[16:17], v121, s[4:5]
	s_add_u32 s4, s4, 0x2000
	s_addc_u32 s5, s5, 0
	global_load_dwordx2 v[18:19], v121, s[4:5]
	s_add_u32 s4, s4, 0x2000
	s_addc_u32 s5, s5, 0
	global_load_dwordx2 v[20:21], v121, s[4:5]
	s_add_u32 s4, s4, 0x2000
	s_addc_u32 s5, s5, 0
	global_load_dwordx2 v[22:23], v121, s[4:5]
	s_add_u32 s4, s4, 0x2000
	s_addc_u32 s5, s5, 0
	global_load_dwordx2 v[24:25], v121, s[4:5]
	s_add_u32 s4, s4, 0x2000
	s_addc_u32 s5, s5, 0
	global_load_dwordx2 v[26:27], v121, s[4:5]
	s_add_u32 s4, s4, 0x2000
	s_addc_u32 s5, s5, 0
	global_load_dwordx2 v[28:29], v121, s[4:5]
	s_add_u32 s4, s4, 0x2000
	s_addc_u32 s5, s5, 0
	global_load_dwordx2 v[30:31], v121, s[4:5]
	s_add_u32 s4, s4, 0x2000
	s_addc_u32 s5, s5, 0
	global_load_dwordx2 v[32:33], v121, s[4:5]
	s_add_u32 s4, s4, 0x2000
	s_addc_u32 s5, s5, 0
	global_load_dwordx2 v[34:35], v121, s[4:5]
	s_add_u32 s4, s4, 0x2000
	s_addc_u32 s5, s5, 0
	global_load_dwordx2 v[36:37], v121, s[4:5]
	s_add_u32 s4, s4, 0x2000
	s_addc_u32 s5, s5, 0
	global_load_dwordx2 v[38:39], v121, s[4:5]
	s_add_u32 s4, s4, 0x2000
	s_addc_u32 s5, s5, 0
	global_load_dwordx2 v[40:41], v121, s[4:5]
	s_add_u32 s4, s4, 0x2000
	s_addc_u32 s5, s5, 0
	global_load_dwordx2 v[42:43], v121, s[4:5]
	s_add_u32 s4, s4, 0x2000
	s_addc_u32 s5, s5, 0
	global_load_dwordx2 v[44:45], v121, s[4:5]
	s_add_u32 s4, s4, 0x2000
	s_addc_u32 s5, s5, 0
	global_load_dwordx2 v[46:47], v121, s[4:5]
	s_add_u32 s4, s4, 0x2000
	s_addc_u32 s5, s5, 0
	global_load_dwordx2 v[48:49], v121, s[4:5]
	s_add_u32 s4, s4, 0x2000
	s_addc_u32 s5, s5, 0
	global_load_dwordx2 v[50:51], v121, s[4:5]
	s_add_u32 s4, s4, 0x2000
	s_addc_u32 s5, s5, 0
	global_load_dwordx2 v[52:53], v121, s[4:5]
	s_add_u32 s4, s4, 0x2000
	s_addc_u32 s5, s5, 0
	global_load_dwordx2 v[54:55], v121, s[4:5]
	s_add_u32 s4, s4, 0x2000
	s_addc_u32 s5, s5, 0
	global_load_dwordx2 v[56:57], v121, s[4:5]
	s_add_u32 s4, s4, 0x2000
	s_addc_u32 s5, s5, 0
	global_load_dwordx2 v[58:59], v121, s[4:5]
	s_add_u32 s4, s4, 0x2000
	s_addc_u32 s5, s5, 0
	global_load_dwordx2 v[60:61], v121, s[4:5]
	s_add_u32 s4, s4, 0x2000
	s_addc_u32 s5, s5, 0
	global_load_dwordx2 v[62:63], v121, s[4:5]
	s_add_u32 s4, s4, 0x2000
	s_addc_u32 s5, s5, 0
	global_load_dwordx2 v[64:65], v121, s[4:5]
	s_add_u32 s4, s4, 0x2000
	s_addc_u32 s5, s5, 0
	global_load_dwordx2 v[66:67], v121, s[4:5]
	s_add_u32 s4, s4, 0x2000
	s_addc_u32 s5, s5, 0
	global_load_dwordx2 v[68:69], v121, s[4:5]
	s_add_u32 s4, s4, 0x2000
	s_addc_u32 s5, s5, 0
	global_load_dwordx2 v[70:71], v121, s[4:5]
	s_add_u32 s4, s4, 0x2000
	s_addc_u32 s5, s5, 0
	global_load_dwordx2 v[72:73], v121, s[4:5]
	s_add_u32 s4, s4, 0x2000
	s_addc_u32 s5, s5, 0
	global_load_dwordx2 v[74:75], v121, s[4:5]
	s_add_u32 s4, s4, 0x2000
	s_addc_u32 s5, s5, 0
	global_load_dwordx2 v[76:77], v121, s[4:5]
	s_waitcnt vmcnt(0)
	v_cmp_le_u32_e32 vcc, 7, v120
	s_nop 1
	v_cndmask_b32_e32 v0, 0, v0, vcc
	v_cndmask_b32_e32 v1, 0, v1, vcc
	v_cmp_le_u32_e32 vcc, 6, v120
	s_nop 1
	v_cndmask_b32_e32 v2, 0, v2, vcc
	v_cndmask_b32_e32 v3, 0, v3, vcc
	v_cmp_le_u32_e32 vcc, 5, v120
	s_nop 1
	v_cndmask_b32_e32 v4, 0, v4, vcc
	v_cndmask_b32_e32 v5, 0, v5, vcc
	v_cmp_le_u32_e32 vcc, 4, v120
	s_nop 1
	v_cndmask_b32_e32 v6, 0, v6, vcc
	v_cndmask_b32_e32 v7, 0, v7, vcc
	v_cmp_le_u32_e32 vcc, 3, v120
	s_nop 1
	v_cndmask_b32_e32 v8, 0, v8, vcc
	v_cndmask_b32_e32 v9, 0, v9, vcc
	v_cmp_le_u32_e32 vcc, 2, v120
	s_nop 1
	v_cndmask_b32_e32 v10, 0, v10, vcc
	v_cndmask_b32_e32 v11, 0, v11, vcc
	v_cmp_le_u32_e32 vcc, 1, v120
	s_nop 1
	v_cndmask_b32_e32 v12, 0, v12, vcc
	v_cndmask_b32_e32 v13, 0, v13, vcc
	v_lshlrev_b32_e32 v94, 16, v0
	v_and_b32_e32 v95, 0xffff0000, v0
	v_lshlrev_b32_e32 v96, 16, v1
	v_and_b32_e32 v97, 0xffff0000, v1
	v_lshlrev_b32_e32 v100, 16, v2
	v_and_b32_e32 v101, 0xffff0000, v2
	v_lshlrev_b32_e32 v102, 16, v3
	v_and_b32_e32 v103, 0xffff0000, v3
	v_add_f32_e32 v94, v94, v100
	v_add_f32_e32 v95, v95, v101
	v_add_f32_e32 v96, v96, v102
	v_add_f32_e32 v97, v97, v103
	v_lshlrev_b32_e32 v100, 16, v4
	v_and_b32_e32 v101, 0xffff0000, v4
	v_lshlrev_b32_e32 v102, 16, v5
	v_and_b32_e32 v103, 0xffff0000, v5
	v_add_f32_e32 v94, v94, v100
	v_add_f32_e32 v95, v95, v101
	v_add_f32_e32 v96, v96, v102
	v_add_f32_e32 v97, v97, v103
	v_lshlrev_b32_e32 v100, 16, v6
	v_and_b32_e32 v101, 0xffff0000, v6
	v_lshlrev_b32_e32 v102, 16, v7
	v_and_b32_e32 v103, 0xffff0000, v7
	v_add_f32_e32 v94, v94, v100
	v_add_f32_e32 v95, v95, v101
	v_add_f32_e32 v96, v96, v102
	v_add_f32_e32 v97, v97, v103
	v_lshlrev_b32_e32 v100, 16, v8
	v_and_b32_e32 v101, 0xffff0000, v8
	v_lshlrev_b32_e32 v102, 16, v9
	v_and_b32_e32 v103, 0xffff0000, v9
	v_add_f32_e32 v94, v94, v100
	v_add_f32_e32 v95, v95, v101
	v_add_f32_e32 v96, v96, v102
	v_add_f32_e32 v97, v97, v103
	v_lshlrev_b32_e32 v100, 16, v10
	v_and_b32_e32 v101, 0xffff0000, v10
	v_lshlrev_b32_e32 v102, 16, v11
	v_and_b32_e32 v103, 0xffff0000, v11
	v_add_f32_e32 v94, v94, v100
	v_add_f32_e32 v95, v95, v101
	v_add_f32_e32 v96, v96, v102
	v_add_f32_e32 v97, v97, v103
	v_lshlrev_b32_e32 v100, 16, v12
	v_and_b32_e32 v101, 0xffff0000, v12
	v_lshlrev_b32_e32 v102, 16, v13
	v_and_b32_e32 v103, 0xffff0000, v13
	v_add_f32_e32 v94, v94, v100
	v_add_f32_e32 v95, v95, v101
	v_add_f32_e32 v96, v96, v102
	v_add_f32_e32 v97, v97, v103
	v_add_u32_e32 v123, 1, v120
	v_min_u32_e32 v123, 8, v123
	v_cvt_f32_u32_e32 v112, v123
	v_div_scale_f32 v113, s[72:73], v112, v112, v118
	v_rcp_f32_e32 v114, v113
	v_div_scale_f32 v115, vcc, v118, v112, v118
	v_fma_f32 v116, -v113, v114, 1.0
	v_fmac_f32_e32 v114, v116, v114
	v_mul_f32_e32 v116, v115, v114
	v_fma_f32 v117, -v113, v116, v115
	v_fmac_f32_e32 v116, v117, v114
	v_fma_f32 v113, -v113, v116, v115
	v_div_fmas_f32 v113, v113, v114, v116
	v_div_fixup_f32 v119, v113, v112, v118
	v_lshlrev_b32_e32 v100, 16, v14
	v_and_b32_e32 v101, 0xffff0000, v14
	v_lshlrev_b32_e32 v102, 16, v15
	v_and_b32_e32 v103, 0xffff0000, v15
	v_add_f32_e32 v94, v94, v100
	v_add_f32_e32 v95, v95, v101
	v_add_f32_e32 v96, v96, v102
	v_add_f32_e32 v97, v97, v103
	v_fma_f32 v100, v94, v119, -v100
	v_fma_f32 v101, v95, v119, -v101
	v_fma_f32 v102, v96, v119, -v102
	v_fma_f32 v103, v97, v119, -v103
	v_cvt_pk_bf16_f32 v108, v100, v101
	v_cvt_pk_bf16_f32 v109, v102, v103
	global_store_dwordx2 v122, v[108:109], s[70:71]
	s_add_u32 s70, s70, 0x800
	s_addc_u32 s71, s71, 0
	v_lshlrev_b32_e32 v100, 16, v0
	v_and_b32_e32 v101, 0xffff0000, v0
	v_lshlrev_b32_e32 v102, 16, v1
	v_and_b32_e32 v103, 0xffff0000, v1
	v_sub_f32_e32 v94, v94, v100
	v_sub_f32_e32 v95, v95, v101
	v_sub_f32_e32 v96, v96, v102
	v_sub_f32_e32 v97, v97, v103
	v_add_u32_e32 v123, 2, v120
	v_min_u32_e32 v123, 8, v123
	v_cvt_f32_u32_e32 v112, v123
	v_div_scale_f32 v113, s[72:73], v112, v112, v118
	v_rcp_f32_e32 v114, v113
	v_div_scale_f32 v115, vcc, v118, v112, v118
	v_fma_f32 v116, -v113, v114, 1.0
	v_fmac_f32_e32 v114, v116, v114
	v_mul_f32_e32 v116, v115, v114
	v_fma_f32 v117, -v113, v116, v115
	v_fmac_f32_e32 v116, v117, v114
	v_fma_f32 v113, -v113, v116, v115
	v_div_fmas_f32 v113, v113, v114, v116
	v_div_fixup_f32 v119, v113, v112, v118
	v_lshlrev_b32_e32 v100, 16, v16
	v_and_b32_e32 v101, 0xffff0000, v16
	v_lshlrev_b32_e32 v102, 16, v17
	v_and_b32_e32 v103, 0xffff0000, v17
	v_add_f32_e32 v94, v94, v100
	v_add_f32_e32 v95, v95, v101
	v_add_f32_e32 v96, v96, v102
	v_add_f32_e32 v97, v97, v103
	v_fma_f32 v100, v94, v119, -v100
	v_fma_f32 v101, v95, v119, -v101
	v_fma_f32 v102, v96, v119, -v102
	v_fma_f32 v103, v97, v119, -v103
	v_cvt_pk_bf16_f32 v110, v100, v101
	v_cvt_pk_bf16_f32 v111, v102, v103
	global_store_dwordx2 v122, v[110:111], s[70:71]
	s_add_u32 s70, s70, 0x800
	s_addc_u32 s71, s71, 0
	v_lshlrev_b32_e32 v100, 16, v2
	v_and_b32_e32 v101, 0xffff0000, v2
	v_lshlrev_b32_e32 v102, 16, v3
	v_and_b32_e32 v103, 0xffff0000, v3
	v_sub_f32_e32 v94, v94, v100
	v_sub_f32_e32 v95, v95, v101
	v_sub_f32_e32 v96, v96, v102
	v_sub_f32_e32 v97, v97, v103
	v_add_u32_e32 v123, 3, v120
	v_min_u32_e32 v123, 8, v123
	v_cvt_f32_u32_e32 v112, v123
	v_div_scale_f32 v113, s[72:73], v112, v112, v118
	v_rcp_f32_e32 v114, v113
	v_div_scale_f32 v115, vcc, v118, v112, v118
	v_fma_f32 v116, -v113, v114, 1.0
	v_fmac_f32_e32 v114, v116, v114
	v_mul_f32_e32 v116, v115, v114
	v_fma_f32 v117, -v113, v116, v115
	v_fmac_f32_e32 v116, v117, v114
	v_fma_f32 v113, -v113, v116, v115
	v_div_fmas_f32 v113, v113, v114, v116
	v_div_fixup_f32 v119, v113, v112, v118
	v_lshlrev_b32_e32 v100, 16, v18
	v_and_b32_e32 v101, 0xffff0000, v18
	v_lshlrev_b32_e32 v102, 16, v19
	v_and_b32_e32 v103, 0xffff0000, v19
	v_add_f32_e32 v94, v94, v100
	v_add_f32_e32 v95, v95, v101
	v_add_f32_e32 v96, v96, v102
	v_add_f32_e32 v97, v97, v103
	v_fma_f32 v100, v94, v119, -v100
	v_fma_f32 v101, v95, v119, -v101
	v_fma_f32 v102, v96, v119, -v102
	v_fma_f32 v103, v97, v119, -v103
	v_cvt_pk_bf16_f32 v108, v100, v101
	v_cvt_pk_bf16_f32 v109, v102, v103
	global_store_dwordx2 v122, v[108:109], s[70:71]
	s_add_u32 s70, s70, 0x800
	s_addc_u32 s71, s71, 0
	v_lshlrev_b32_e32 v100, 16, v4
	v_and_b32_e32 v101, 0xffff0000, v4
	v_lshlrev_b32_e32 v102, 16, v5
	v_and_b32_e32 v103, 0xffff0000, v5
	v_sub_f32_e32 v94, v94, v100
	v_sub_f32_e32 v95, v95, v101
	v_sub_f32_e32 v96, v96, v102
	v_sub_f32_e32 v97, v97, v103
	v_add_u32_e32 v123, 4, v120
	v_min_u32_e32 v123, 8, v123
	v_cvt_f32_u32_e32 v112, v123
	v_div_scale_f32 v113, s[72:73], v112, v112, v118
	v_rcp_f32_e32 v114, v113
	v_div_scale_f32 v115, vcc, v118, v112, v118
	v_fma_f32 v116, -v113, v114, 1.0
	v_fmac_f32_e32 v114, v116, v114
	v_mul_f32_e32 v116, v115, v114
	v_fma_f32 v117, -v113, v116, v115
	v_fmac_f32_e32 v116, v117, v114
	v_fma_f32 v113, -v113, v116, v115
	v_div_fmas_f32 v113, v113, v114, v116
	v_div_fixup_f32 v119, v113, v112, v118
	v_lshlrev_b32_e32 v100, 16, v20
	v_and_b32_e32 v101, 0xffff0000, v20
	v_lshlrev_b32_e32 v102, 16, v21
	v_and_b32_e32 v103, 0xffff0000, v21
	v_add_f32_e32 v94, v94, v100
	v_add_f32_e32 v95, v95, v101
	v_add_f32_e32 v96, v96, v102
	v_add_f32_e32 v97, v97, v103
	v_fma_f32 v100, v94, v119, -v100
	v_fma_f32 v101, v95, v119, -v101
	v_fma_f32 v102, v96, v119, -v102
	v_fma_f32 v103, v97, v119, -v103
	v_cvt_pk_bf16_f32 v110, v100, v101
	v_cvt_pk_bf16_f32 v111, v102, v103
	global_store_dwordx2 v122, v[110:111], s[70:71]
	s_add_u32 s70, s70, 0x800
	s_addc_u32 s71, s71, 0
	v_lshlrev_b32_e32 v100, 16, v6
	v_and_b32_e32 v101, 0xffff0000, v6
	v_lshlrev_b32_e32 v102, 16, v7
	v_and_b32_e32 v103, 0xffff0000, v7
	v_sub_f32_e32 v94, v94, v100
	v_sub_f32_e32 v95, v95, v101
	v_sub_f32_e32 v96, v96, v102
	v_sub_f32_e32 v97, v97, v103
	v_add_u32_e32 v123, 5, v120
	v_min_u32_e32 v123, 8, v123
	v_cvt_f32_u32_e32 v112, v123
	v_div_scale_f32 v113, s[72:73], v112, v112, v118
	v_rcp_f32_e32 v114, v113
	v_div_scale_f32 v115, vcc, v118, v112, v118
	v_fma_f32 v116, -v113, v114, 1.0
	v_fmac_f32_e32 v114, v116, v114
	v_mul_f32_e32 v116, v115, v114
	v_fma_f32 v117, -v113, v116, v115
	v_fmac_f32_e32 v116, v117, v114
	v_fma_f32 v113, -v113, v116, v115
	v_div_fmas_f32 v113, v113, v114, v116
	v_div_fixup_f32 v119, v113, v112, v118
	v_lshlrev_b32_e32 v100, 16, v22
	v_and_b32_e32 v101, 0xffff0000, v22
	v_lshlrev_b32_e32 v102, 16, v23
	v_and_b32_e32 v103, 0xffff0000, v23
	v_add_f32_e32 v94, v94, v100
	v_add_f32_e32 v95, v95, v101
	v_add_f32_e32 v96, v96, v102
	v_add_f32_e32 v97, v97, v103
	v_fma_f32 v100, v94, v119, -v100
	v_fma_f32 v101, v95, v119, -v101
	v_fma_f32 v102, v96, v119, -v102
	v_fma_f32 v103, v97, v119, -v103
	v_cvt_pk_bf16_f32 v108, v100, v101
	v_cvt_pk_bf16_f32 v109, v102, v103
	global_store_dwordx2 v122, v[108:109], s[70:71]
	s_add_u32 s70, s70, 0x800
	s_addc_u32 s71, s71, 0
	v_lshlrev_b32_e32 v100, 16, v8
	v_and_b32_e32 v101, 0xffff0000, v8
	v_lshlrev_b32_e32 v102, 16, v9
	v_and_b32_e32 v103, 0xffff0000, v9
	v_sub_f32_e32 v94, v94, v100
	v_sub_f32_e32 v95, v95, v101
	v_sub_f32_e32 v96, v96, v102
	v_sub_f32_e32 v97, v97, v103
	v_add_u32_e32 v123, 6, v120
	v_min_u32_e32 v123, 8, v123
	v_cvt_f32_u32_e32 v112, v123
	v_div_scale_f32 v113, s[72:73], v112, v112, v118
	v_rcp_f32_e32 v114, v113
	v_div_scale_f32 v115, vcc, v118, v112, v118
	v_fma_f32 v116, -v113, v114, 1.0
	v_fmac_f32_e32 v114, v116, v114
	v_mul_f32_e32 v116, v115, v114
	v_fma_f32 v117, -v113, v116, v115
	v_fmac_f32_e32 v116, v117, v114
	v_fma_f32 v113, -v113, v116, v115
	v_div_fmas_f32 v113, v113, v114, v116
	v_div_fixup_f32 v119, v113, v112, v118
	v_lshlrev_b32_e32 v100, 16, v24
	v_and_b32_e32 v101, 0xffff0000, v24
	v_lshlrev_b32_e32 v102, 16, v25
	v_and_b32_e32 v103, 0xffff0000, v25
	v_add_f32_e32 v94, v94, v100
	v_add_f32_e32 v95, v95, v101
	v_add_f32_e32 v96, v96, v102
	v_add_f32_e32 v97, v97, v103
	v_fma_f32 v100, v94, v119, -v100
	v_fma_f32 v101, v95, v119, -v101
	v_fma_f32 v102, v96, v119, -v102
	v_fma_f32 v103, v97, v119, -v103
	v_cvt_pk_bf16_f32 v110, v100, v101
	v_cvt_pk_bf16_f32 v111, v102, v103
	global_store_dwordx2 v122, v[110:111], s[70:71]
	s_add_u32 s70, s70, 0x800
	s_addc_u32 s71, s71, 0
	v_lshlrev_b32_e32 v100, 16, v10
	v_and_b32_e32 v101, 0xffff0000, v10
	v_lshlrev_b32_e32 v102, 16, v11
	v_and_b32_e32 v103, 0xffff0000, v11
	v_sub_f32_e32 v94, v94, v100
	v_sub_f32_e32 v95, v95, v101
	v_sub_f32_e32 v96, v96, v102
	v_sub_f32_e32 v97, v97, v103
	v_add_u32_e32 v123, 7, v120
	v_min_u32_e32 v123, 8, v123
	v_cvt_f32_u32_e32 v112, v123
	v_div_scale_f32 v113, s[72:73], v112, v112, v118
	v_rcp_f32_e32 v114, v113
	v_div_scale_f32 v115, vcc, v118, v112, v118
	v_fma_f32 v116, -v113, v114, 1.0
	v_fmac_f32_e32 v114, v116, v114
	v_mul_f32_e32 v116, v115, v114
	v_fma_f32 v117, -v113, v116, v115
	v_fmac_f32_e32 v116, v117, v114
	v_fma_f32 v113, -v113, v116, v115
	v_div_fmas_f32 v113, v113, v114, v116
	v_div_fixup_f32 v119, v113, v112, v118
	v_lshlrev_b32_e32 v100, 16, v26
	v_and_b32_e32 v101, 0xffff0000, v26
	v_lshlrev_b32_e32 v102, 16, v27
	v_and_b32_e32 v103, 0xffff0000, v27
	v_add_f32_e32 v94, v94, v100
	v_add_f32_e32 v95, v95, v101
	v_add_f32_e32 v96, v96, v102
	v_add_f32_e32 v97, v97, v103
	v_fma_f32 v100, v94, v119, -v100
	v_fma_f32 v101, v95, v119, -v101
	v_fma_f32 v102, v96, v119, -v102
	v_fma_f32 v103, v97, v119, -v103
	v_cvt_pk_bf16_f32 v108, v100, v101
	v_cvt_pk_bf16_f32 v109, v102, v103
	global_store_dwordx2 v122, v[108:109], s[70:71]
	s_add_u32 s70, s70, 0x800
	s_addc_u32 s71, s71, 0
	v_lshlrev_b32_e32 v100, 16, v12
	v_and_b32_e32 v101, 0xffff0000, v12
	v_lshlrev_b32_e32 v102, 16, v13
	v_and_b32_e32 v103, 0xffff0000, v13
	v_sub_f32_e32 v94, v94, v100
	v_sub_f32_e32 v95, v95, v101
	v_sub_f32_e32 v96, v96, v102
	v_sub_f32_e32 v97, v97, v103
	v_mov_b32_e32 v119, 0x3e000000
	v_lshlrev_b32_e32 v100, 16, v28
	v_and_b32_e32 v101, 0xffff0000, v28
	v_lshlrev_b32_e32 v102, 16, v29
	v_and_b32_e32 v103, 0xffff0000, v29
	v_add_f32_e32 v94, v94, v100
	v_add_f32_e32 v95, v95, v101
	v_add_f32_e32 v96, v96, v102
	v_add_f32_e32 v97, v97, v103
	v_fma_f32 v100, v94, v119, -v100
	v_fma_f32 v101, v95, v119, -v101
	v_fma_f32 v102, v96, v119, -v102
	v_fma_f32 v103, v97, v119, -v103
	v_cvt_pk_bf16_f32 v110, v100, v101
	v_cvt_pk_bf16_f32 v111, v102, v103
	global_store_dwordx2 v122, v[110:111], s[70:71]
	s_add_u32 s70, s70, 0x800
	s_addc_u32 s71, s71, 0
	v_lshlrev_b32_e32 v100, 16, v14
	v_and_b32_e32 v101, 0xffff0000, v14
	v_lshlrev_b32_e32 v102, 16, v15
	v_and_b32_e32 v103, 0xffff0000, v15
	v_sub_f32_e32 v94, v94, v100
	v_sub_f32_e32 v95, v95, v101
	v_sub_f32_e32 v96, v96, v102
	v_sub_f32_e32 v97, v97, v103
	v_lshlrev_b32_e32 v100, 16, v30
	v_and_b32_e32 v101, 0xffff0000, v30
	v_lshlrev_b32_e32 v102, 16, v31
	v_and_b32_e32 v103, 0xffff0000, v31
	v_add_f32_e32 v94, v94, v100
	v_add_f32_e32 v95, v95, v101
	v_add_f32_e32 v96, v96, v102
	v_add_f32_e32 v97, v97, v103
	v_fma_f32 v100, v94, v119, -v100
	v_fma_f32 v101, v95, v119, -v101
	v_fma_f32 v102, v96, v119, -v102
	v_fma_f32 v103, v97, v119, -v103
	v_cvt_pk_bf16_f32 v108, v100, v101
	v_cvt_pk_bf16_f32 v109, v102, v103
	global_store_dwordx2 v122, v[108:109], s[70:71]
	s_add_u32 s70, s70, 0x800
	s_addc_u32 s71, s71, 0
	v_lshlrev_b32_e32 v100, 16, v16
	v_and_b32_e32 v101, 0xffff0000, v16
	v_lshlrev_b32_e32 v102, 16, v17
	v_and_b32_e32 v103, 0xffff0000, v17
	v_sub_f32_e32 v94, v94, v100
	v_sub_f32_e32 v95, v95, v101
	v_sub_f32_e32 v96, v96, v102
	v_sub_f32_e32 v97, v97, v103
	v_lshlrev_b32_e32 v100, 16, v32
	v_and_b32_e32 v101, 0xffff0000, v32
	v_lshlrev_b32_e32 v102, 16, v33
	v_and_b32_e32 v103, 0xffff0000, v33
	v_add_f32_e32 v94, v94, v100
	v_add_f32_e32 v95, v95, v101
	v_add_f32_e32 v96, v96, v102
	v_add_f32_e32 v97, v97, v103
	v_fma_f32 v100, v94, v119, -v100
	v_fma_f32 v101, v95, v119, -v101
	v_fma_f32 v102, v96, v119, -v102
	v_fma_f32 v103, v97, v119, -v103
	v_cvt_pk_bf16_f32 v110, v100, v101
	v_cvt_pk_bf16_f32 v111, v102, v103
	global_store_dwordx2 v122, v[110:111], s[70:71]
	s_add_u32 s70, s70, 0x800
	s_addc_u32 s71, s71, 0
	v_lshlrev_b32_e32 v100, 16, v18
	v_and_b32_e32 v101, 0xffff0000, v18
	v_lshlrev_b32_e32 v102, 16, v19
	v_and_b32_e32 v103, 0xffff0000, v19
	v_sub_f32_e32 v94, v94, v100
	v_sub_f32_e32 v95, v95, v101
	v_sub_f32_e32 v96, v96, v102
	v_sub_f32_e32 v97, v97, v103
	v_lshlrev_b32_e32 v100, 16, v34
	v_and_b32_e32 v101, 0xffff0000, v34
	v_lshlrev_b32_e32 v102, 16, v35
	v_and_b32_e32 v103, 0xffff0000, v35
	v_add_f32_e32 v94, v94, v100
	v_add_f32_e32 v95, v95, v101
	v_add_f32_e32 v96, v96, v102
	v_add_f32_e32 v97, v97, v103
	v_fma_f32 v100, v94, v119, -v100
	v_fma_f32 v101, v95, v119, -v101
	v_fma_f32 v102, v96, v119, -v102
	v_fma_f32 v103, v97, v119, -v103
	v_cvt_pk_bf16_f32 v108, v100, v101
	v_cvt_pk_bf16_f32 v109, v102, v103
	global_store_dwordx2 v122, v[108:109], s[70:71]
	s_add_u32 s70, s70, 0x800
	s_addc_u32 s71, s71, 0
	v_lshlrev_b32_e32 v100, 16, v20
	v_and_b32_e32 v101, 0xffff0000, v20
	v_lshlrev_b32_e32 v102, 16, v21
	v_and_b32_e32 v103, 0xffff0000, v21
	v_sub_f32_e32 v94, v94, v100
	v_sub_f32_e32 v95, v95, v101
	v_sub_f32_e32 v96, v96, v102
	v_sub_f32_e32 v97, v97, v103
	v_lshlrev_b32_e32 v100, 16, v36
	v_and_b32_e32 v101, 0xffff0000, v36
	v_lshlrev_b32_e32 v102, 16, v37
	v_and_b32_e32 v103, 0xffff0000, v37
	v_add_f32_e32 v94, v94, v100
	v_add_f32_e32 v95, v95, v101
	v_add_f32_e32 v96, v96, v102
	v_add_f32_e32 v97, v97, v103
	v_fma_f32 v100, v94, v119, -v100
	v_fma_f32 v101, v95, v119, -v101
	v_fma_f32 v102, v96, v119, -v102
	v_fma_f32 v103, v97, v119, -v103
	v_cvt_pk_bf16_f32 v110, v100, v101
	v_cvt_pk_bf16_f32 v111, v102, v103
	global_store_dwordx2 v122, v[110:111], s[70:71]
	s_add_u32 s70, s70, 0x800
	s_addc_u32 s71, s71, 0
	v_lshlrev_b32_e32 v100, 16, v22
	v_and_b32_e32 v101, 0xffff0000, v22
	v_lshlrev_b32_e32 v102, 16, v23
	v_and_b32_e32 v103, 0xffff0000, v23
	v_sub_f32_e32 v94, v94, v100
	v_sub_f32_e32 v95, v95, v101
	v_sub_f32_e32 v96, v96, v102
	v_sub_f32_e32 v97, v97, v103
	v_lshlrev_b32_e32 v100, 16, v38
	v_and_b32_e32 v101, 0xffff0000, v38
	v_lshlrev_b32_e32 v102, 16, v39
	v_and_b32_e32 v103, 0xffff0000, v39
	v_add_f32_e32 v94, v94, v100
	v_add_f32_e32 v95, v95, v101
	v_add_f32_e32 v96, v96, v102
	v_add_f32_e32 v97, v97, v103
	v_fma_f32 v100, v94, v119, -v100
	v_fma_f32 v101, v95, v119, -v101
	v_fma_f32 v102, v96, v119, -v102
	v_fma_f32 v103, v97, v119, -v103
	v_cvt_pk_bf16_f32 v108, v100, v101
	v_cvt_pk_bf16_f32 v109, v102, v103
	global_store_dwordx2 v122, v[108:109], s[70:71]
	s_add_u32 s70, s70, 0x800
	s_addc_u32 s71, s71, 0
	v_lshlrev_b32_e32 v100, 16, v24
	v_and_b32_e32 v101, 0xffff0000, v24
	v_lshlrev_b32_e32 v102, 16, v25
	v_and_b32_e32 v103, 0xffff0000, v25
	v_sub_f32_e32 v94, v94, v100
	v_sub_f32_e32 v95, v95, v101
	v_sub_f32_e32 v96, v96, v102
	v_sub_f32_e32 v97, v97, v103
	v_lshlrev_b32_e32 v100, 16, v40
	v_and_b32_e32 v101, 0xffff0000, v40
	v_lshlrev_b32_e32 v102, 16, v41
	v_and_b32_e32 v103, 0xffff0000, v41
	v_add_f32_e32 v94, v94, v100
	v_add_f32_e32 v95, v95, v101
	v_add_f32_e32 v96, v96, v102
	v_add_f32_e32 v97, v97, v103
	v_fma_f32 v100, v94, v119, -v100
	v_fma_f32 v101, v95, v119, -v101
	v_fma_f32 v102, v96, v119, -v102
	v_fma_f32 v103, v97, v119, -v103
	v_cvt_pk_bf16_f32 v110, v100, v101
	v_cvt_pk_bf16_f32 v111, v102, v103
	global_store_dwordx2 v122, v[110:111], s[70:71]
	s_add_u32 s70, s70, 0x800
	s_addc_u32 s71, s71, 0
	v_lshlrev_b32_e32 v100, 16, v26
	v_and_b32_e32 v101, 0xffff0000, v26
	v_lshlrev_b32_e32 v102, 16, v27
	v_and_b32_e32 v103, 0xffff0000, v27
	v_sub_f32_e32 v94, v94, v100
	v_sub_f32_e32 v95, v95, v101
	v_sub_f32_e32 v96, v96, v102
	v_sub_f32_e32 v97, v97, v103
	v_lshlrev_b32_e32 v100, 16, v42
	v_and_b32_e32 v101, 0xffff0000, v42
	v_lshlrev_b32_e32 v102, 16, v43
	v_and_b32_e32 v103, 0xffff0000, v43
	v_add_f32_e32 v94, v94, v100
	v_add_f32_e32 v95, v95, v101
	v_add_f32_e32 v96, v96, v102
	v_add_f32_e32 v97, v97, v103
	v_fma_f32 v100, v94, v119, -v100
	v_fma_f32 v101, v95, v119, -v101
	v_fma_f32 v102, v96, v119, -v102
	v_fma_f32 v103, v97, v119, -v103
	v_cvt_pk_bf16_f32 v108, v100, v101
	v_cvt_pk_bf16_f32 v109, v102, v103
	global_store_dwordx2 v122, v[108:109], s[70:71]
	s_add_u32 s70, s70, 0x800
	s_addc_u32 s71, s71, 0
	v_lshlrev_b32_e32 v100, 16, v28
	v_and_b32_e32 v101, 0xffff0000, v28
	v_lshlrev_b32_e32 v102, 16, v29
	v_and_b32_e32 v103, 0xffff0000, v29
	v_sub_f32_e32 v94, v94, v100
	v_sub_f32_e32 v95, v95, v101
	v_sub_f32_e32 v96, v96, v102
	v_sub_f32_e32 v97, v97, v103
	v_lshlrev_b32_e32 v100, 16, v44
	v_and_b32_e32 v101, 0xffff0000, v44
	v_lshlrev_b32_e32 v102, 16, v45
	v_and_b32_e32 v103, 0xffff0000, v45
	v_add_f32_e32 v94, v94, v100
	v_add_f32_e32 v95, v95, v101
	v_add_f32_e32 v96, v96, v102
	v_add_f32_e32 v97, v97, v103
	v_fma_f32 v100, v94, v119, -v100
	v_fma_f32 v101, v95, v119, -v101
	v_fma_f32 v102, v96, v119, -v102
	v_fma_f32 v103, v97, v119, -v103
	v_cvt_pk_bf16_f32 v110, v100, v101
	v_cvt_pk_bf16_f32 v111, v102, v103
	global_store_dwordx2 v122, v[110:111], s[70:71]
	s_add_u32 s70, s70, 0x800
	s_addc_u32 s71, s71, 0
	v_lshlrev_b32_e32 v100, 16, v30
	v_and_b32_e32 v101, 0xffff0000, v30
	v_lshlrev_b32_e32 v102, 16, v31
	v_and_b32_e32 v103, 0xffff0000, v31
	v_sub_f32_e32 v94, v94, v100
	v_sub_f32_e32 v95, v95, v101
	v_sub_f32_e32 v96, v96, v102
	v_sub_f32_e32 v97, v97, v103
	v_lshlrev_b32_e32 v100, 16, v46
	v_and_b32_e32 v101, 0xffff0000, v46
	v_lshlrev_b32_e32 v102, 16, v47
	v_and_b32_e32 v103, 0xffff0000, v47
	v_add_f32_e32 v94, v94, v100
	v_add_f32_e32 v95, v95, v101
	v_add_f32_e32 v96, v96, v102
	v_add_f32_e32 v97, v97, v103
	v_fma_f32 v100, v94, v119, -v100
	v_fma_f32 v101, v95, v119, -v101
	v_fma_f32 v102, v96, v119, -v102
	v_fma_f32 v103, v97, v119, -v103
	v_cvt_pk_bf16_f32 v108, v100, v101
	v_cvt_pk_bf16_f32 v109, v102, v103
	global_store_dwordx2 v122, v[108:109], s[70:71]
	s_add_u32 s70, s70, 0x800
	s_addc_u32 s71, s71, 0
	v_lshlrev_b32_e32 v100, 16, v32
	v_and_b32_e32 v101, 0xffff0000, v32
	v_lshlrev_b32_e32 v102, 16, v33
	v_and_b32_e32 v103, 0xffff0000, v33
	v_sub_f32_e32 v94, v94, v100
	v_sub_f32_e32 v95, v95, v101
	v_sub_f32_e32 v96, v96, v102
	v_sub_f32_e32 v97, v97, v103
	v_lshlrev_b32_e32 v100, 16, v48
	v_and_b32_e32 v101, 0xffff0000, v48
	v_lshlrev_b32_e32 v102, 16, v49
	v_and_b32_e32 v103, 0xffff0000, v49
	v_add_f32_e32 v94, v94, v100
	v_add_f32_e32 v95, v95, v101
	v_add_f32_e32 v96, v96, v102
	v_add_f32_e32 v97, v97, v103
	v_fma_f32 v100, v94, v119, -v100
	v_fma_f32 v101, v95, v119, -v101
	v_fma_f32 v102, v96, v119, -v102
	v_fma_f32 v103, v97, v119, -v103
	v_cvt_pk_bf16_f32 v110, v100, v101
	v_cvt_pk_bf16_f32 v111, v102, v103
	global_store_dwordx2 v122, v[110:111], s[70:71]
	s_add_u32 s70, s70, 0x800
	s_addc_u32 s71, s71, 0
	v_lshlrev_b32_e32 v100, 16, v34
	v_and_b32_e32 v101, 0xffff0000, v34
	v_lshlrev_b32_e32 v102, 16, v35
	v_and_b32_e32 v103, 0xffff0000, v35
	v_sub_f32_e32 v94, v94, v100
	v_sub_f32_e32 v95, v95, v101
	v_sub_f32_e32 v96, v96, v102
	v_sub_f32_e32 v97, v97, v103
	v_lshlrev_b32_e32 v100, 16, v50
	v_and_b32_e32 v101, 0xffff0000, v50
	v_lshlrev_b32_e32 v102, 16, v51
	v_and_b32_e32 v103, 0xffff0000, v51
	v_add_f32_e32 v94, v94, v100
	v_add_f32_e32 v95, v95, v101
	v_add_f32_e32 v96, v96, v102
	v_add_f32_e32 v97, v97, v103
	v_fma_f32 v100, v94, v119, -v100
	v_fma_f32 v101, v95, v119, -v101
	v_fma_f32 v102, v96, v119, -v102
	v_fma_f32 v103, v97, v119, -v103
	v_cvt_pk_bf16_f32 v108, v100, v101
	v_cvt_pk_bf16_f32 v109, v102, v103
	global_store_dwordx2 v122, v[108:109], s[70:71]
	s_add_u32 s70, s70, 0x800
	s_addc_u32 s71, s71, 0
	v_lshlrev_b32_e32 v100, 16, v36
	v_and_b32_e32 v101, 0xffff0000, v36
	v_lshlrev_b32_e32 v102, 16, v37
	v_and_b32_e32 v103, 0xffff0000, v37
	v_sub_f32_e32 v94, v94, v100
	v_sub_f32_e32 v95, v95, v101
	v_sub_f32_e32 v96, v96, v102
	v_sub_f32_e32 v97, v97, v103
	v_lshlrev_b32_e32 v100, 16, v52
	v_and_b32_e32 v101, 0xffff0000, v52
	v_lshlrev_b32_e32 v102, 16, v53
	v_and_b32_e32 v103, 0xffff0000, v53
	v_add_f32_e32 v94, v94, v100
	v_add_f32_e32 v95, v95, v101
	v_add_f32_e32 v96, v96, v102
	v_add_f32_e32 v97, v97, v103
	v_fma_f32 v100, v94, v119, -v100
	v_fma_f32 v101, v95, v119, -v101
	v_fma_f32 v102, v96, v119, -v102
	v_fma_f32 v103, v97, v119, -v103
	v_cvt_pk_bf16_f32 v110, v100, v101
	v_cvt_pk_bf16_f32 v111, v102, v103
	global_store_dwordx2 v122, v[110:111], s[70:71]
	s_add_u32 s70, s70, 0x800
	s_addc_u32 s71, s71, 0
	v_lshlrev_b32_e32 v100, 16, v38
	v_and_b32_e32 v101, 0xffff0000, v38
	v_lshlrev_b32_e32 v102, 16, v39
	v_and_b32_e32 v103, 0xffff0000, v39
	v_sub_f32_e32 v94, v94, v100
	v_sub_f32_e32 v95, v95, v101
	v_sub_f32_e32 v96, v96, v102
	v_sub_f32_e32 v97, v97, v103
	v_lshlrev_b32_e32 v100, 16, v54
	v_and_b32_e32 v101, 0xffff0000, v54
	v_lshlrev_b32_e32 v102, 16, v55
	v_and_b32_e32 v103, 0xffff0000, v55
	v_add_f32_e32 v94, v94, v100
	v_add_f32_e32 v95, v95, v101
	v_add_f32_e32 v96, v96, v102
	v_add_f32_e32 v97, v97, v103
	v_fma_f32 v100, v94, v119, -v100
	v_fma_f32 v101, v95, v119, -v101
	v_fma_f32 v102, v96, v119, -v102
	v_fma_f32 v103, v97, v119, -v103
	v_cvt_pk_bf16_f32 v108, v100, v101
	v_cvt_pk_bf16_f32 v109, v102, v103
	global_store_dwordx2 v122, v[108:109], s[70:71]
	s_add_u32 s70, s70, 0x800
	s_addc_u32 s71, s71, 0
	v_lshlrev_b32_e32 v100, 16, v40
	v_and_b32_e32 v101, 0xffff0000, v40
	v_lshlrev_b32_e32 v102, 16, v41
	v_and_b32_e32 v103, 0xffff0000, v41
	v_sub_f32_e32 v94, v94, v100
	v_sub_f32_e32 v95, v95, v101
	v_sub_f32_e32 v96, v96, v102
	v_sub_f32_e32 v97, v97, v103
	v_lshlrev_b32_e32 v100, 16, v56
	v_and_b32_e32 v101, 0xffff0000, v56
	v_lshlrev_b32_e32 v102, 16, v57
	v_and_b32_e32 v103, 0xffff0000, v57
	v_add_f32_e32 v94, v94, v100
	v_add_f32_e32 v95, v95, v101
	v_add_f32_e32 v96, v96, v102
	v_add_f32_e32 v97, v97, v103
	v_fma_f32 v100, v94, v119, -v100
	v_fma_f32 v101, v95, v119, -v101
	v_fma_f32 v102, v96, v119, -v102
	v_fma_f32 v103, v97, v119, -v103
	v_cvt_pk_bf16_f32 v110, v100, v101
	v_cvt_pk_bf16_f32 v111, v102, v103
	global_store_dwordx2 v122, v[110:111], s[70:71]
	s_add_u32 s70, s70, 0x800
	s_addc_u32 s71, s71, 0
	v_lshlrev_b32_e32 v100, 16, v42
	v_and_b32_e32 v101, 0xffff0000, v42
	v_lshlrev_b32_e32 v102, 16, v43
	v_and_b32_e32 v103, 0xffff0000, v43
	v_sub_f32_e32 v94, v94, v100
	v_sub_f32_e32 v95, v95, v101
	v_sub_f32_e32 v96, v96, v102
	v_sub_f32_e32 v97, v97, v103
	v_lshlrev_b32_e32 v100, 16, v58
	v_and_b32_e32 v101, 0xffff0000, v58
	v_lshlrev_b32_e32 v102, 16, v59
	v_and_b32_e32 v103, 0xffff0000, v59
	v_add_f32_e32 v94, v94, v100
	v_add_f32_e32 v95, v95, v101
	v_add_f32_e32 v96, v96, v102
	v_add_f32_e32 v97, v97, v103
	v_fma_f32 v100, v94, v119, -v100
	v_fma_f32 v101, v95, v119, -v101
	v_fma_f32 v102, v96, v119, -v102
	v_fma_f32 v103, v97, v119, -v103
	v_cvt_pk_bf16_f32 v108, v100, v101
	v_cvt_pk_bf16_f32 v109, v102, v103
	global_store_dwordx2 v122, v[108:109], s[70:71]
	s_add_u32 s70, s70, 0x800
	s_addc_u32 s71, s71, 0
	v_lshlrev_b32_e32 v100, 16, v44
	v_and_b32_e32 v101, 0xffff0000, v44
	v_lshlrev_b32_e32 v102, 16, v45
	v_and_b32_e32 v103, 0xffff0000, v45
	v_sub_f32_e32 v94, v94, v100
	v_sub_f32_e32 v95, v95, v101
	v_sub_f32_e32 v96, v96, v102
	v_sub_f32_e32 v97, v97, v103
	v_lshlrev_b32_e32 v100, 16, v60
	v_and_b32_e32 v101, 0xffff0000, v60
	v_lshlrev_b32_e32 v102, 16, v61
	v_and_b32_e32 v103, 0xffff0000, v61
	v_add_f32_e32 v94, v94, v100
	v_add_f32_e32 v95, v95, v101
	v_add_f32_e32 v96, v96, v102
	v_add_f32_e32 v97, v97, v103
	v_fma_f32 v100, v94, v119, -v100
	v_fma_f32 v101, v95, v119, -v101
	v_fma_f32 v102, v96, v119, -v102
	v_fma_f32 v103, v97, v119, -v103
	v_cvt_pk_bf16_f32 v110, v100, v101
	v_cvt_pk_bf16_f32 v111, v102, v103
	global_store_dwordx2 v122, v[110:111], s[70:71]
	s_add_u32 s70, s70, 0x800
	s_addc_u32 s71, s71, 0
	v_lshlrev_b32_e32 v100, 16, v46
	v_and_b32_e32 v101, 0xffff0000, v46
	v_lshlrev_b32_e32 v102, 16, v47
	v_and_b32_e32 v103, 0xffff0000, v47
	v_sub_f32_e32 v94, v94, v100
	v_sub_f32_e32 v95, v95, v101
	v_sub_f32_e32 v96, v96, v102
	v_sub_f32_e32 v97, v97, v103
	v_lshlrev_b32_e32 v100, 16, v62
	v_and_b32_e32 v101, 0xffff0000, v62
	v_lshlrev_b32_e32 v102, 16, v63
	v_and_b32_e32 v103, 0xffff0000, v63
	v_add_f32_e32 v94, v94, v100
	v_add_f32_e32 v95, v95, v101
	v_add_f32_e32 v96, v96, v102
	v_add_f32_e32 v97, v97, v103
	v_fma_f32 v100, v94, v119, -v100
	v_fma_f32 v101, v95, v119, -v101
	v_fma_f32 v102, v96, v119, -v102
	v_fma_f32 v103, v97, v119, -v103
	v_cvt_pk_bf16_f32 v108, v100, v101
	v_cvt_pk_bf16_f32 v109, v102, v103
	global_store_dwordx2 v122, v[108:109], s[70:71]
	s_add_u32 s70, s70, 0x800
	s_addc_u32 s71, s71, 0
	v_lshlrev_b32_e32 v100, 16, v48
	v_and_b32_e32 v101, 0xffff0000, v48
	v_lshlrev_b32_e32 v102, 16, v49
	v_and_b32_e32 v103, 0xffff0000, v49
	v_sub_f32_e32 v94, v94, v100
	v_sub_f32_e32 v95, v95, v101
	v_sub_f32_e32 v96, v96, v102
	v_sub_f32_e32 v97, v97, v103
	v_lshlrev_b32_e32 v100, 16, v64
	v_and_b32_e32 v101, 0xffff0000, v64
	v_lshlrev_b32_e32 v102, 16, v65
	v_and_b32_e32 v103, 0xffff0000, v65
	v_add_f32_e32 v94, v94, v100
	v_add_f32_e32 v95, v95, v101
	v_add_f32_e32 v96, v96, v102
	v_add_f32_e32 v97, v97, v103
	v_fma_f32 v100, v94, v119, -v100
	v_fma_f32 v101, v95, v119, -v101
	v_fma_f32 v102, v96, v119, -v102
	v_fma_f32 v103, v97, v119, -v103
	v_cvt_pk_bf16_f32 v110, v100, v101
	v_cvt_pk_bf16_f32 v111, v102, v103
	global_store_dwordx2 v122, v[110:111], s[70:71]
	s_add_u32 s70, s70, 0x800
	s_addc_u32 s71, s71, 0
	v_lshlrev_b32_e32 v100, 16, v50
	v_and_b32_e32 v101, 0xffff0000, v50
	v_lshlrev_b32_e32 v102, 16, v51
	v_and_b32_e32 v103, 0xffff0000, v51
	v_sub_f32_e32 v94, v94, v100
	v_sub_f32_e32 v95, v95, v101
	v_sub_f32_e32 v96, v96, v102
	v_sub_f32_e32 v97, v97, v103
	v_lshlrev_b32_e32 v100, 16, v66
	v_and_b32_e32 v101, 0xffff0000, v66
	v_lshlrev_b32_e32 v102, 16, v67
	v_and_b32_e32 v103, 0xffff0000, v67
	v_add_f32_e32 v94, v94, v100
	v_add_f32_e32 v95, v95, v101
	v_add_f32_e32 v96, v96, v102
	v_add_f32_e32 v97, v97, v103
	v_fma_f32 v100, v94, v119, -v100
	v_fma_f32 v101, v95, v119, -v101
	v_fma_f32 v102, v96, v119, -v102
	v_fma_f32 v103, v97, v119, -v103
	v_cvt_pk_bf16_f32 v108, v100, v101
	v_cvt_pk_bf16_f32 v109, v102, v103
	global_store_dwordx2 v122, v[108:109], s[70:71]
	s_add_u32 s70, s70, 0x800
	s_addc_u32 s71, s71, 0
	v_lshlrev_b32_e32 v100, 16, v52
	v_and_b32_e32 v101, 0xffff0000, v52
	v_lshlrev_b32_e32 v102, 16, v53
	v_and_b32_e32 v103, 0xffff0000, v53
	v_sub_f32_e32 v94, v94, v100
	v_sub_f32_e32 v95, v95, v101
	v_sub_f32_e32 v96, v96, v102
	v_sub_f32_e32 v97, v97, v103
	v_lshlrev_b32_e32 v100, 16, v68
	v_and_b32_e32 v101, 0xffff0000, v68
	v_lshlrev_b32_e32 v102, 16, v69
	v_and_b32_e32 v103, 0xffff0000, v69
	v_add_f32_e32 v94, v94, v100
	v_add_f32_e32 v95, v95, v101
	v_add_f32_e32 v96, v96, v102
	v_add_f32_e32 v97, v97, v103
	v_fma_f32 v100, v94, v119, -v100
	v_fma_f32 v101, v95, v119, -v101
	v_fma_f32 v102, v96, v119, -v102
	v_fma_f32 v103, v97, v119, -v103
	v_cvt_pk_bf16_f32 v110, v100, v101
	v_cvt_pk_bf16_f32 v111, v102, v103
	global_store_dwordx2 v122, v[110:111], s[70:71]
	s_add_u32 s70, s70, 0x800
	s_addc_u32 s71, s71, 0
	v_lshlrev_b32_e32 v100, 16, v54
	v_and_b32_e32 v101, 0xffff0000, v54
	v_lshlrev_b32_e32 v102, 16, v55
	v_and_b32_e32 v103, 0xffff0000, v55
	v_sub_f32_e32 v94, v94, v100
	v_sub_f32_e32 v95, v95, v101
	v_sub_f32_e32 v96, v96, v102
	v_sub_f32_e32 v97, v97, v103
	v_lshlrev_b32_e32 v100, 16, v70
	v_and_b32_e32 v101, 0xffff0000, v70
	v_lshlrev_b32_e32 v102, 16, v71
	v_and_b32_e32 v103, 0xffff0000, v71
	v_add_f32_e32 v94, v94, v100
	v_add_f32_e32 v95, v95, v101
	v_add_f32_e32 v96, v96, v102
	v_add_f32_e32 v97, v97, v103
	v_fma_f32 v100, v94, v119, -v100
	v_fma_f32 v101, v95, v119, -v101
	v_fma_f32 v102, v96, v119, -v102
	v_fma_f32 v103, v97, v119, -v103
	v_cvt_pk_bf16_f32 v108, v100, v101
	v_cvt_pk_bf16_f32 v109, v102, v103
	global_store_dwordx2 v122, v[108:109], s[70:71]
	s_add_u32 s70, s70, 0x800
	s_addc_u32 s71, s71, 0
	v_lshlrev_b32_e32 v100, 16, v56
	v_and_b32_e32 v101, 0xffff0000, v56
	v_lshlrev_b32_e32 v102, 16, v57
	v_and_b32_e32 v103, 0xffff0000, v57
	v_sub_f32_e32 v94, v94, v100
	v_sub_f32_e32 v95, v95, v101
	v_sub_f32_e32 v96, v96, v102
	v_sub_f32_e32 v97, v97, v103
	v_lshlrev_b32_e32 v100, 16, v72
	v_and_b32_e32 v101, 0xffff0000, v72
	v_lshlrev_b32_e32 v102, 16, v73
	v_and_b32_e32 v103, 0xffff0000, v73
	v_add_f32_e32 v94, v94, v100
	v_add_f32_e32 v95, v95, v101
	v_add_f32_e32 v96, v96, v102
	v_add_f32_e32 v97, v97, v103
	v_fma_f32 v100, v94, v119, -v100
	v_fma_f32 v101, v95, v119, -v101
	v_fma_f32 v102, v96, v119, -v102
	v_fma_f32 v103, v97, v119, -v103
	v_cvt_pk_bf16_f32 v110, v100, v101
	v_cvt_pk_bf16_f32 v111, v102, v103
	global_store_dwordx2 v122, v[110:111], s[70:71]
	s_add_u32 s70, s70, 0x800
	s_addc_u32 s71, s71, 0
	v_lshlrev_b32_e32 v100, 16, v58
	v_and_b32_e32 v101, 0xffff0000, v58
	v_lshlrev_b32_e32 v102, 16, v59
	v_and_b32_e32 v103, 0xffff0000, v59
	v_sub_f32_e32 v94, v94, v100
	v_sub_f32_e32 v95, v95, v101
	v_sub_f32_e32 v96, v96, v102
	v_sub_f32_e32 v97, v97, v103
	v_lshlrev_b32_e32 v100, 16, v74
	v_and_b32_e32 v101, 0xffff0000, v74
	v_lshlrev_b32_e32 v102, 16, v75
	v_and_b32_e32 v103, 0xffff0000, v75
	v_add_f32_e32 v94, v94, v100
	v_add_f32_e32 v95, v95, v101
	v_add_f32_e32 v96, v96, v102
	v_add_f32_e32 v97, v97, v103
	v_fma_f32 v100, v94, v119, -v100
	v_fma_f32 v101, v95, v119, -v101
	v_fma_f32 v102, v96, v119, -v102
	v_fma_f32 v103, v97, v119, -v103
	v_cvt_pk_bf16_f32 v108, v100, v101
	v_cvt_pk_bf16_f32 v109, v102, v103
	global_store_dwordx2 v122, v[108:109], s[70:71]
	s_add_u32 s70, s70, 0x800
	s_addc_u32 s71, s71, 0
	v_lshlrev_b32_e32 v100, 16, v60
	v_and_b32_e32 v101, 0xffff0000, v60
	v_lshlrev_b32_e32 v102, 16, v61
	v_and_b32_e32 v103, 0xffff0000, v61
	v_sub_f32_e32 v94, v94, v100
	v_sub_f32_e32 v95, v95, v101
	v_sub_f32_e32 v96, v96, v102
	v_sub_f32_e32 v97, v97, v103
	v_lshlrev_b32_e32 v100, 16, v76
	v_and_b32_e32 v101, 0xffff0000, v76
	v_lshlrev_b32_e32 v102, 16, v77
	v_and_b32_e32 v103, 0xffff0000, v77
	v_add_f32_e32 v94, v94, v100
	v_add_f32_e32 v95, v95, v101
	v_add_f32_e32 v96, v96, v102
	v_add_f32_e32 v97, v97, v103
	v_fma_f32 v100, v94, v119, -v100
	v_fma_f32 v101, v95, v119, -v101
	v_fma_f32 v102, v96, v119, -v102
	v_fma_f32 v103, v97, v119, -v103
	v_cvt_pk_bf16_f32 v110, v100, v101
	v_cvt_pk_bf16_f32 v111, v102, v103
	global_store_dwordx2 v122, v[110:111], s[70:71]
	s_branch .Lpl_done
.Lpl_w16:
	s_sub_u32 s4, s68, 0x1e000
	s_subb_u32 s5, s69, 0
	global_load_dwordx2 v[0:1], v121, s[4:5]
	s_add_u32 s4, s4, 0x2000
	s_addc_u32 s5, s5, 0
	global_load_dwordx2 v[2:3], v121, s[4:5]
	s_add_u32 s4, s4, 0x2000
	s_addc_u32 s5, s5, 0
	global_load_dwordx2 v[4:5], v121, s[4:5]
	s_add_u32 s4, s4, 0x2000
	s_addc_u32 s5, s5, 0
	global_load_dwordx2 v[6:7], v121, s[4:5]
	s_add_u32 s4, s4, 0x2000
	s_addc_u32 s5, s5, 0
	global_load_dwordx2 v[8:9], v121, s[4:5]
	s_add_u32 s4, s4, 0x2000
	s_addc_u32 s5, s5, 0
	global_load_dwordx2 v[10:11], v121, s[4:5]
	s_add_u32 s4, s4, 0x2000
	s_addc_u32 s5, s5, 0
	global_load_dwordx2 v[12:13], v121, s[4:5]
	s_add_u32 s4, s4, 0x2000
	s_addc_u32 s5, s5, 0
	global_load_dwordx2 v[14:15], v121, s[4:5]
	s_add_u32 s4, s4, 0x2000
	s_addc_u32 s5, s5, 0
	global_load_dwordx2 v[16:17], v121, s[4:5]
	s_add_u32 s4, s4, 0x2000
	s_addc_u32 s5, s5, 0
	global_load_dwordx2 v[18:19], v121, s[4:5]
	s_add_u32 s4, s4, 0x2000
	s_addc_u32 s5, s5, 0
	global_load_dwordx2 v[20:21], v121, s[4:5]
	s_add_u32 s4, s4, 0x2000
	s_addc_u32 s5, s5, 0
	global_load_dwordx2 v[22:23], v121, s[4:5]
	s_add_u32 s4, s4, 0x2000
	s_addc_u32 s5, s5, 0
	global_load_dwordx2 v[24:25], v121, s[4:5]
	s_add_u32 s4, s4, 0x2000
	s_addc_u32 s5, s5, 0
	global_load_dwordx2 v[26:27], v121, s[4:5]
	s_add_u32 s4, s4, 0x2000
	s_addc_u32 s5, s5, 0
	global_load_dwordx2 v[28:29], v121, s[4:5]
	s_add_u32 s4, s4, 0x2000
	s_addc_u32 s5, s5, 0
	global_load_dwordx2 v[30:31], v121, s[4:5]
	s_add_u32 s4, s4, 0x2000
	s_addc_u32 s5, s5, 0
	global_load_dwordx2 v[32:33], v121, s[4:5]
	s_add_u32 s4, s4, 0x2000
	s_addc_u32 s5, s5, 0
	global_load_dwordx2 v[34:35], v121, s[4:5]
	s_add_u32 s4, s4, 0x2000
	s_addc_u32 s5, s5, 0
	global_load_dwordx2 v[36:37], v121, s[4:5]
	s_add_u32 s4, s4, 0x2000
	s_addc_u32 s5, s5, 0
	global_load_dwordx2 v[38:39], v121, s[4:5]
	s_add_u32 s4, s4, 0x2000
	s_addc_u32 s5, s5, 0
	global_load_dwordx2 v[40:41], v121, s[4:5]
	s_add_u32 s4, s4, 0x2000
	s_addc_u32 s5, s5, 0
	global_load_dwordx2 v[42:43], v121, s[4:5]
	s_add_u32 s4, s4, 0x2000
	s_addc_u32 s5, s5, 0
	global_load_dwordx2 v[44:45], v121, s[4:5]
	s_add_u32 s4, s4, 0x2000
	s_addc_u32 s5, s5, 0
	global_load_dwordx2 v[46:47], v121, s[4:5]
	s_add_u32 s4, s4, 0x2000
	s_addc_u32 s5, s5, 0
	global_load_dwordx2 v[48:49], v121, s[4:5]
	s_add_u32 s4, s4, 0x2000
	s_addc_u32 s5, s5, 0
	global_load_dwordx2 v[50:51], v121, s[4:5]
	s_add_u32 s4, s4, 0x2000
	s_addc_u32 s5, s5, 0
	global_load_dwordx2 v[52:53], v121, s[4:5]
	s_add_u32 s4, s4, 0x2000
	s_addc_u32 s5, s5, 0
	global_load_dwordx2 v[54:55], v121, s[4:5]
	s_add_u32 s4, s4, 0x2000
	s_addc_u32 s5, s5, 0
	global_load_dwordx2 v[56:57], v121, s[4:5]
	s_add_u32 s4, s4, 0x2000
	s_addc_u32 s5, s5, 0
	global_load_dwordx2 v[58:59], v121, s[4:5]
	s_add_u32 s4, s4, 0x2000
	s_addc_u32 s5, s5, 0
	global_load_dwordx2 v[60:61], v121, s[4:5]
	s_add_u32 s4, s4, 0x2000
	s_addc_u32 s5, s5, 0
	global_load_dwordx2 v[62:63], v121, s[4:5]
	s_add_u32 s4, s4, 0x2000
	s_addc_u32 s5, s5, 0
	global_load_dwordx2 v[64:65], v121, s[4:5]
	s_add_u32 s4, s4, 0x2000
	s_addc_u32 s5, s5, 0
	global_load_dwordx2 v[66:67], v121, s[4:5]
	s_add_u32 s4, s4, 0x2000
	s_addc_u32 s5, s5, 0
	global_load_dwordx2 v[68:69], v121, s[4:5]
	s_add_u32 s4, s4, 0x2000
	s_addc_u32 s5, s5, 0
	global_load_dwordx2 v[70:71], v121, s[4:5]
	s_add_u32 s4, s4, 0x2000
	s_addc_u32 s5, s5, 0
	global_load_dwordx2 v[72:73], v121, s[4:5]
	s_add_u32 s4, s4, 0x2000
	s_addc_u32 s5, s5, 0
	global_load_dwordx2 v[74:75], v121, s[4:5]
	s_add_u32 s4, s4, 0x2000
	s_addc_u32 s5, s5, 0
	global_load_dwordx2 v[76:77], v121, s[4:5]
	s_add_u32 s4, s4, 0x2000
	s_addc_u32 s5, s5, 0
	global_load_dwordx2 v[78:79], v121, s[4:5]
	s_add_u32 s4, s4, 0x2000
	s_addc_u32 s5, s5, 0
	global_load_dwordx2 v[80:81], v121, s[4:5]
	s_add_u32 s4, s4, 0x2000
	s_addc_u32 s5, s5, 0
	global_load_dwordx2 v[82:83], v121, s[4:5]
	s_add_u32 s4, s4, 0x2000
	s_addc_u32 s5, s5, 0
	global_load_dwordx2 v[84:85], v121, s[4:5]
	s_add_u32 s4, s4, 0x2000
	s_addc_u32 s5, s5, 0
	global_load_dwordx2 v[86:87], v121, s[4:5]
	s_add_u32 s4, s4, 0x2000
	s_addc_u32 s5, s5, 0
	global_load_dwordx2 v[88:89], v121, s[4:5]
	s_add_u32 s4, s4, 0x2000
	s_addc_u32 s5, s5, 0
	global_load_dwordx2 v[90:91], v121, s[4:5]
	s_add_u32 s4, s4, 0x2000
	s_addc_u32 s5, s5, 0
	global_load_dwordx2 v[92:93], v121, s[4:5]
	s_waitcnt vmcnt(0)
	v_cmp_le_u32_e32 vcc, 15, v120
	s_nop 1
	v_cndmask_b32_e32 v0, 0, v0, vcc
	v_cndmask_b32_e32 v1, 0, v1, vcc
	v_cmp_le_u32_e32 vcc, 14, v120
	s_nop 1
	v_cndmask_b32_e32 v2, 0, v2, vcc
	v_cndmask_b32_e32 v3, 0, v3, vcc
	v_cmp_le_u32_e32 vcc, 13, v120
	s_nop 1
	v_cndmask_b32_e32 v4, 0, v4, vcc
	v_cndmask_b32_e32 v5, 0, v5, vcc
	v_cmp_le_u32_e32 vcc, 12, v120
	s_nop 1
	v_cndmask_b32_e32 v6, 0, v6, vcc
	v_cndmask_b32_e32 v7, 0, v7, vcc
	v_cmp_le_u32_e32 vcc, 11, v120
	s_nop 1
	v_cndmask_b32_e32 v8, 0, v8, vcc
	v_cndmask_b32_e32 v9, 0, v9, vcc
	v_cmp_le_u32_e32 vcc, 10, v120
	s_nop 1
	v_cndmask_b32_e32 v10, 0, v10, vcc
	v_cndmask_b32_e32 v11, 0, v11, vcc
	v_cmp_le_u32_e32 vcc, 9, v120
	s_nop 1
	v_cndmask_b32_e32 v12, 0, v12, vcc
	v_cndmask_b32_e32 v13, 0, v13, vcc
	v_cmp_le_u32_e32 vcc, 8, v120
	s_nop 1
	v_cndmask_b32_e32 v14, 0, v14, vcc
	v_cndmask_b32_e32 v15, 0, v15, vcc
	v_cmp_le_u32_e32 vcc, 7, v120
	s_nop 1
	v_cndmask_b32_e32 v16, 0, v16, vcc
	v_cndmask_b32_e32 v17, 0, v17, vcc
	v_cmp_le_u32_e32 vcc, 6, v120
	s_nop 1
	v_cndmask_b32_e32 v18, 0, v18, vcc
	v_cndmask_b32_e32 v19, 0, v19, vcc
	v_cmp_le_u32_e32 vcc, 5, v120
	s_nop 1
	v_cndmask_b32_e32 v20, 0, v20, vcc
	v_cndmask_b32_e32 v21, 0, v21, vcc
	v_cmp_le_u32_e32 vcc, 4, v120
	s_nop 1
	v_cndmask_b32_e32 v22, 0, v22, vcc
	v_cndmask_b32_e32 v23, 0, v23, vcc
	v_cmp_le_u32_e32 vcc, 3, v120
	s_nop 1
	v_cndmask_b32_e32 v24, 0, v24, vcc
	v_cndmask_b32_e32 v25, 0, v25, vcc
	v_cmp_le_u32_e32 vcc, 2, v120
	s_nop 1
	v_cndmask_b32_e32 v26, 0, v26, vcc
	v_cndmask_b32_e32 v27, 0, v27, vcc
	v_cmp_le_u32_e32 vcc, 1, v120
	s_nop 1
	v_cndmask_b32_e32 v28, 0, v28, vcc
	v_cndmask_b32_e32 v29, 0, v29, vcc
	v_lshlrev_b32_e32 v94, 16, v0
	v_and_b32_e32 v95, 0xffff0000, v0
	v_lshlrev_b32_e32 v96, 16, v1
	v_and_b32_e32 v97, 0xffff0000, v1
	v_lshlrev_b32_e32 v100, 16, v2
	v_and_b32_e32 v101, 0xffff0000, v2
	v_lshlrev_b32_e32 v102, 16, v3
	v_and_b32_e32 v103, 0xffff0000, v3
	v_add_f32_e32 v94, v94, v100
	v_add_f32_e32 v95, v95, v101
	v_add_f32_e32 v96, v96, v102
	v_add_f32_e32 v97, v97, v103
	v_lshlrev_b32_e32 v100, 16, v4
	v_and_b32_e32 v101, 0xffff0000, v4
	v_lshlrev_b32_e32 v102, 16, v5
	v_and_b32_e32 v103, 0xffff0000, v5
	v_add_f32_e32 v94, v94, v100
	v_add_f32_e32 v95, v95, v101
	v_add_f32_e32 v96, v96, v102
	v_add_f32_e32 v97, v97, v103
	v_lshlrev_b32_e32 v100, 16, v6
	v_and_b32_e32 v101, 0xffff0000, v6
	v_lshlrev_b32_e32 v102, 16, v7
	v_and_b32_e32 v103, 0xffff0000, v7
	v_add_f32_e32 v94, v94, v100
	v_add_f32_e32 v95, v95, v101
	v_add_f32_e32 v96, v96, v102
	v_add_f32_e32 v97, v97, v103
	v_lshlrev_b32_e32 v100, 16, v8
	v_and_b32_e32 v101, 0xffff0000, v8
	v_lshlrev_b32_e32 v102, 16, v9
	v_and_b32_e32 v103, 0xffff0000, v9
	v_add_f32_e32 v94, v94, v100
	v_add_f32_e32 v95, v95, v101
	v_add_f32_e32 v96, v96, v102
	v_add_f32_e32 v97, v97, v103
	v_lshlrev_b32_e32 v100, 16, v10
	v_and_b32_e32 v101, 0xffff0000, v10
	v_lshlrev_b32_e32 v102, 16, v11
	v_and_b32_e32 v103, 0xffff0000, v11
	v_add_f32_e32 v94, v94, v100
	v_add_f32_e32 v95, v95, v101
	v_add_f32_e32 v96, v96, v102
	v_add_f32_e32 v97, v97, v103
	v_lshlrev_b32_e32 v100, 16, v12
	v_and_b32_e32 v101, 0xffff0000, v12
	v_lshlrev_b32_e32 v102, 16, v13
	v_and_b32_e32 v103, 0xffff0000, v13
	v_add_f32_e32 v94, v94, v100
	v_add_f32_e32 v95, v95, v101
	v_add_f32_e32 v96, v96, v102
	v_add_f32_e32 v97, v97, v103
	v_lshlrev_b32_e32 v100, 16, v14
	v_and_b32_e32 v101, 0xffff0000, v14
	v_lshlrev_b32_e32 v102, 16, v15
	v_and_b32_e32 v103, 0xffff0000, v15
	v_add_f32_e32 v94, v94, v100
	v_add_f32_e32 v95, v95, v101
	v_add_f32_e32 v96, v96, v102
	v_add_f32_e32 v97, v97, v103
	v_lshlrev_b32_e32 v100, 16, v16
	v_and_b32_e32 v101, 0xffff0000, v16
	v_lshlrev_b32_e32 v102, 16, v17
	v_and_b32_e32 v103, 0xffff0000, v17
	v_add_f32_e32 v94, v94, v100
	v_add_f32_e32 v95, v95, v101
	v_add_f32_e32 v96, v96, v102
	v_add_f32_e32 v97, v97, v103
	v_lshlrev_b32_e32 v100, 16, v18
	v_and_b32_e32 v101, 0xffff0000, v18
	v_lshlrev_b32_e32 v102, 16, v19
	v_and_b32_e32 v103, 0xffff0000, v19
	v_add_f32_e32 v94, v94, v100
	v_add_f32_e32 v95, v95, v101
	v_add_f32_e32 v96, v96, v102
	v_add_f32_e32 v97, v97, v103
	v_lshlrev_b32_e32 v100, 16, v20
	v_and_b32_e32 v101, 0xffff0000, v20
	v_lshlrev_b32_e32 v102, 16, v21
	v_and_b32_e32 v103, 0xffff0000, v21
	v_add_f32_e32 v94, v94, v100
	v_add_f32_e32 v95, v95, v101
	v_add_f32_e32 v96, v96, v102
	v_add_f32_e32 v97, v97, v103
	v_lshlrev_b32_e32 v100, 16, v22
	v_and_b32_e32 v101, 0xffff0000, v22
	v_lshlrev_b32_e32 v102, 16, v23
	v_and_b32_e32 v103, 0xffff0000, v23
	v_add_f32_e32 v94, v94, v100
	v_add_f32_e32 v95, v95, v101
	v_add_f32_e32 v96, v96, v102
	v_add_f32_e32 v97, v97, v103
	v_lshlrev_b32_e32 v100, 16, v24
	v_and_b32_e32 v101, 0xffff0000, v24
	v_lshlrev_b32_e32 v102, 16, v25
	v_and_b32_e32 v103, 0xffff0000, v25
	v_add_f32_e32 v94, v94, v100
	v_add_f32_e32 v95, v95, v101
	v_add_f32_e32 v96, v96, v102
	v_add_f32_e32 v97, v97, v103
	v_lshlrev_b32_e32 v100, 16, v26
	v_and_b32_e32 v101, 0xffff0000, v26
	v_lshlrev_b32_e32 v102, 16, v27
	v_and_b32_e32 v103, 0xffff0000, v27
	v_add_f32_e32 v94, v94, v100
	v_add_f32_e32 v95, v95, v101
	v_add_f32_e32 v96, v96, v102
	v_add_f32_e32 v97, v97, v103
	v_lshlrev_b32_e32 v100, 16, v28
	v_and_b32_e32 v101, 0xffff0000, v28
	v_lshlrev_b32_e32 v102, 16, v29
	v_and_b32_e32 v103, 0xffff0000, v29
	v_add_f32_e32 v94, v94, v100
	v_add_f32_e32 v95, v95, v101
	v_add_f32_e32 v96, v96, v102
	v_add_f32_e32 v97, v97, v103
	v_add_u32_e32 v123, 1, v120
	v_min_u32_e32 v123, 16, v123
	v_cvt_f32_u32_e32 v112, v123
	v_div_scale_f32 v113, s[72:73], v112, v112, v118
	v_rcp_f32_e32 v114, v113
	v_div_scale_f32 v115, vcc, v118, v112, v118
	v_fma_f32 v116, -v113, v114, 1.0
	v_fmac_f32_e32 v114, v116, v114
	v_mul_f32_e32 v116, v115, v114
	v_fma_f32 v117, -v113, v116, v115
	v_fmac_f32_e32 v116, v117, v114
	v_fma_f32 v113, -v113, v116, v115
	v_div_fmas_f32 v113, v113, v114, v116
	v_div_fixup_f32 v119, v113, v112, v118
	v_lshlrev_b32_e32 v100, 16, v30
	v_and_b32_e32 v101, 0xffff0000, v30
	v_lshlrev_b32_e32 v102, 16, v31
	v_and_b32_e32 v103, 0xffff0000, v31
	v_add_f32_e32 v94, v94, v100
	v_add_f32_e32 v95, v95, v101
	v_add_f32_e32 v96, v96, v102
	v_add_f32_e32 v97, v97, v103
	v_fma_f32 v100, v94, v119, -v100
	v_fma_f32 v101, v95, v119, -v101
	v_fma_f32 v102, v96, v119, -v102
	v_fma_f32 v103, v97, v119, -v103
	v_cvt_pk_bf16_f32 v108, v100, v101
	v_cvt_pk_bf16_f32 v109, v102, v103
	global_store_dwordx2 v122, v[108:109], s[70:71]
	s_add_u32 s70, s70, 0x800
	s_addc_u32 s71, s71, 0
	v_lshlrev_b32_e32 v100, 16, v0
	v_and_b32_e32 v101, 0xffff0000, v0
	v_lshlrev_b32_e32 v102, 16, v1
	v_and_b32_e32 v103, 0xffff0000, v1
	v_sub_f32_e32 v94, v94, v100
	v_sub_f32_e32 v95, v95, v101
	v_sub_f32_e32 v96, v96, v102
	v_sub_f32_e32 v97, v97, v103
	v_add_u32_e32 v123, 2, v120
	v_min_u32_e32 v123, 16, v123
	v_cvt_f32_u32_e32 v112, v123
	v_div_scale_f32 v113, s[72:73], v112, v112, v118
	v_rcp_f32_e32 v114, v113
	v_div_scale_f32 v115, vcc, v118, v112, v118
	v_fma_f32 v116, -v113, v114, 1.0
	v_fmac_f32_e32 v114, v116, v114
	v_mul_f32_e32 v116, v115, v114
	v_fma_f32 v117, -v113, v116, v115
	v_fmac_f32_e32 v116, v117, v114
	v_fma_f32 v113, -v113, v116, v115
	v_div_fmas_f32 v113, v113, v114, v116
	v_div_fixup_f32 v119, v113, v112, v118
	v_lshlrev_b32_e32 v100, 16, v32
	v_and_b32_e32 v101, 0xffff0000, v32
	v_lshlrev_b32_e32 v102, 16, v33
	v_and_b32_e32 v103, 0xffff0000, v33
	v_add_f32_e32 v94, v94, v100
	v_add_f32_e32 v95, v95, v101
	v_add_f32_e32 v96, v96, v102
	v_add_f32_e32 v97, v97, v103
	v_fma_f32 v100, v94, v119, -v100
	v_fma_f32 v101, v95, v119, -v101
	v_fma_f32 v102, v96, v119, -v102
	v_fma_f32 v103, v97, v119, -v103
	v_cvt_pk_bf16_f32 v110, v100, v101
	v_cvt_pk_bf16_f32 v111, v102, v103
	global_store_dwordx2 v122, v[110:111], s[70:71]
	s_add_u32 s70, s70, 0x800
	s_addc_u32 s71, s71, 0
	v_lshlrev_b32_e32 v100, 16, v2
	v_and_b32_e32 v101, 0xffff0000, v2
	v_lshlrev_b32_e32 v102, 16, v3
	v_and_b32_e32 v103, 0xffff0000, v3
	v_sub_f32_e32 v94, v94, v100
	v_sub_f32_e32 v95, v95, v101
	v_sub_f32_e32 v96, v96, v102
	v_sub_f32_e32 v97, v97, v103
	v_add_u32_e32 v123, 3, v120
	v_min_u32_e32 v123, 16, v123
	v_cvt_f32_u32_e32 v112, v123
	v_div_scale_f32 v113, s[72:73], v112, v112, v118
	v_rcp_f32_e32 v114, v113
	v_div_scale_f32 v115, vcc, v118, v112, v118
	v_fma_f32 v116, -v113, v114, 1.0
	v_fmac_f32_e32 v114, v116, v114
	v_mul_f32_e32 v116, v115, v114
	v_fma_f32 v117, -v113, v116, v115
	v_fmac_f32_e32 v116, v117, v114
	v_fma_f32 v113, -v113, v116, v115
	v_div_fmas_f32 v113, v113, v114, v116
	v_div_fixup_f32 v119, v113, v112, v118
	v_lshlrev_b32_e32 v100, 16, v34
	v_and_b32_e32 v101, 0xffff0000, v34
	v_lshlrev_b32_e32 v102, 16, v35
	v_and_b32_e32 v103, 0xffff0000, v35
	v_add_f32_e32 v94, v94, v100
	v_add_f32_e32 v95, v95, v101
	v_add_f32_e32 v96, v96, v102
	v_add_f32_e32 v97, v97, v103
	v_fma_f32 v100, v94, v119, -v100
	v_fma_f32 v101, v95, v119, -v101
	v_fma_f32 v102, v96, v119, -v102
	v_fma_f32 v103, v97, v119, -v103
	v_cvt_pk_bf16_f32 v108, v100, v101
	v_cvt_pk_bf16_f32 v109, v102, v103
	global_store_dwordx2 v122, v[108:109], s[70:71]
	s_add_u32 s70, s70, 0x800
	s_addc_u32 s71, s71, 0
	v_lshlrev_b32_e32 v100, 16, v4
	v_and_b32_e32 v101, 0xffff0000, v4
	v_lshlrev_b32_e32 v102, 16, v5
	v_and_b32_e32 v103, 0xffff0000, v5
	v_sub_f32_e32 v94, v94, v100
	v_sub_f32_e32 v95, v95, v101
	v_sub_f32_e32 v96, v96, v102
	v_sub_f32_e32 v97, v97, v103
	v_add_u32_e32 v123, 4, v120
	v_min_u32_e32 v123, 16, v123
	v_cvt_f32_u32_e32 v112, v123
	v_div_scale_f32 v113, s[72:73], v112, v112, v118
	v_rcp_f32_e32 v114, v113
	v_div_scale_f32 v115, vcc, v118, v112, v118
	v_fma_f32 v116, -v113, v114, 1.0
	v_fmac_f32_e32 v114, v116, v114
	v_mul_f32_e32 v116, v115, v114
	v_fma_f32 v117, -v113, v116, v115
	v_fmac_f32_e32 v116, v117, v114
	v_fma_f32 v113, -v113, v116, v115
	v_div_fmas_f32 v113, v113, v114, v116
	v_div_fixup_f32 v119, v113, v112, v118
	v_lshlrev_b32_e32 v100, 16, v36
	v_and_b32_e32 v101, 0xffff0000, v36
	v_lshlrev_b32_e32 v102, 16, v37
	v_and_b32_e32 v103, 0xffff0000, v37
	v_add_f32_e32 v94, v94, v100
	v_add_f32_e32 v95, v95, v101
	v_add_f32_e32 v96, v96, v102
	v_add_f32_e32 v97, v97, v103
	v_fma_f32 v100, v94, v119, -v100
	v_fma_f32 v101, v95, v119, -v101
	v_fma_f32 v102, v96, v119, -v102
	v_fma_f32 v103, v97, v119, -v103
	v_cvt_pk_bf16_f32 v110, v100, v101
	v_cvt_pk_bf16_f32 v111, v102, v103
	global_store_dwordx2 v122, v[110:111], s[70:71]
	s_add_u32 s70, s70, 0x800
	s_addc_u32 s71, s71, 0
	v_lshlrev_b32_e32 v100, 16, v6
	v_and_b32_e32 v101, 0xffff0000, v6
	v_lshlrev_b32_e32 v102, 16, v7
	v_and_b32_e32 v103, 0xffff0000, v7
	v_sub_f32_e32 v94, v94, v100
	v_sub_f32_e32 v95, v95, v101
	v_sub_f32_e32 v96, v96, v102
	v_sub_f32_e32 v97, v97, v103
	v_add_u32_e32 v123, 5, v120
	v_min_u32_e32 v123, 16, v123
	v_cvt_f32_u32_e32 v112, v123
	v_div_scale_f32 v113, s[72:73], v112, v112, v118
	v_rcp_f32_e32 v114, v113
	v_div_scale_f32 v115, vcc, v118, v112, v118
	v_fma_f32 v116, -v113, v114, 1.0
	v_fmac_f32_e32 v114, v116, v114
	v_mul_f32_e32 v116, v115, v114
	v_fma_f32 v117, -v113, v116, v115
	v_fmac_f32_e32 v116, v117, v114
	v_fma_f32 v113, -v113, v116, v115
	v_div_fmas_f32 v113, v113, v114, v116
	v_div_fixup_f32 v119, v113, v112, v118
	v_lshlrev_b32_e32 v100, 16, v38
	v_and_b32_e32 v101, 0xffff0000, v38
	v_lshlrev_b32_e32 v102, 16, v39
	v_and_b32_e32 v103, 0xffff0000, v39
	v_add_f32_e32 v94, v94, v100
	v_add_f32_e32 v95, v95, v101
	v_add_f32_e32 v96, v96, v102
	v_add_f32_e32 v97, v97, v103
	v_fma_f32 v100, v94, v119, -v100
	v_fma_f32 v101, v95, v119, -v101
	v_fma_f32 v102, v96, v119, -v102
	v_fma_f32 v103, v97, v119, -v103
	v_cvt_pk_bf16_f32 v108, v100, v101
	v_cvt_pk_bf16_f32 v109, v102, v103
	global_store_dwordx2 v122, v[108:109], s[70:71]
	s_add_u32 s70, s70, 0x800
	s_addc_u32 s71, s71, 0
	v_lshlrev_b32_e32 v100, 16, v8
	v_and_b32_e32 v101, 0xffff0000, v8
	v_lshlrev_b32_e32 v102, 16, v9
	v_and_b32_e32 v103, 0xffff0000, v9
	v_sub_f32_e32 v94, v94, v100
	v_sub_f32_e32 v95, v95, v101
	v_sub_f32_e32 v96, v96, v102
	v_sub_f32_e32 v97, v97, v103
	v_add_u32_e32 v123, 6, v120
	v_min_u32_e32 v123, 16, v123
	v_cvt_f32_u32_e32 v112, v123
	v_div_scale_f32 v113, s[72:73], v112, v112, v118
	v_rcp_f32_e32 v114, v113
	v_div_scale_f32 v115, vcc, v118, v112, v118
	v_fma_f32 v116, -v113, v114, 1.0
	v_fmac_f32_e32 v114, v116, v114
	v_mul_f32_e32 v116, v115, v114
	v_fma_f32 v117, -v113, v116, v115
	v_fmac_f32_e32 v116, v117, v114
	v_fma_f32 v113, -v113, v116, v115
	v_div_fmas_f32 v113, v113, v114, v116
	v_div_fixup_f32 v119, v113, v112, v118
	v_lshlrev_b32_e32 v100, 16, v40
	v_and_b32_e32 v101, 0xffff0000, v40
	v_lshlrev_b32_e32 v102, 16, v41
	v_and_b32_e32 v103, 0xffff0000, v41
	v_add_f32_e32 v94, v94, v100
	v_add_f32_e32 v95, v95, v101
	v_add_f32_e32 v96, v96, v102
	v_add_f32_e32 v97, v97, v103
	v_fma_f32 v100, v94, v119, -v100
	v_fma_f32 v101, v95, v119, -v101
	v_fma_f32 v102, v96, v119, -v102
	v_fma_f32 v103, v97, v119, -v103
	v_cvt_pk_bf16_f32 v110, v100, v101
	v_cvt_pk_bf16_f32 v111, v102, v103
	global_store_dwordx2 v122, v[110:111], s[70:71]
	s_add_u32 s70, s70, 0x800
	s_addc_u32 s71, s71, 0
	v_lshlrev_b32_e32 v100, 16, v10
	v_and_b32_e32 v101, 0xffff0000, v10
	v_lshlrev_b32_e32 v102, 16, v11
	v_and_b32_e32 v103, 0xffff0000, v11
	v_sub_f32_e32 v94, v94, v100
	v_sub_f32_e32 v95, v95, v101
	v_sub_f32_e32 v96, v96, v102
	v_sub_f32_e32 v97, v97, v103
	v_add_u32_e32 v123, 7, v120
	v_min_u32_e32 v123, 16, v123
	v_cvt_f32_u32_e32 v112, v123
	v_div_scale_f32 v113, s[72:73], v112, v112, v118
	v_rcp_f32_e32 v114, v113
	v_div_scale_f32 v115, vcc, v118, v112, v118
	v_fma_f32 v116, -v113, v114, 1.0
	v_fmac_f32_e32 v114, v116, v114
	v_mul_f32_e32 v116, v115, v114
	v_fma_f32 v117, -v113, v116, v115
	v_fmac_f32_e32 v116, v117, v114
	v_fma_f32 v113, -v113, v116, v115
	v_div_fmas_f32 v113, v113, v114, v116
	v_div_fixup_f32 v119, v113, v112, v118
	v_lshlrev_b32_e32 v100, 16, v42
	v_and_b32_e32 v101, 0xffff0000, v42
	v_lshlrev_b32_e32 v102, 16, v43
	v_and_b32_e32 v103, 0xffff0000, v43
	v_add_f32_e32 v94, v94, v100
	v_add_f32_e32 v95, v95, v101
	v_add_f32_e32 v96, v96, v102
	v_add_f32_e32 v97, v97, v103
	v_fma_f32 v100, v94, v119, -v100
	v_fma_f32 v101, v95, v119, -v101
	v_fma_f32 v102, v96, v119, -v102
	v_fma_f32 v103, v97, v119, -v103
	v_cvt_pk_bf16_f32 v108, v100, v101
	v_cvt_pk_bf16_f32 v109, v102, v103
	global_store_dwordx2 v122, v[108:109], s[70:71]
	s_add_u32 s70, s70, 0x800
	s_addc_u32 s71, s71, 0
	v_lshlrev_b32_e32 v100, 16, v12
	v_and_b32_e32 v101, 0xffff0000, v12
	v_lshlrev_b32_e32 v102, 16, v13
	v_and_b32_e32 v103, 0xffff0000, v13
	v_sub_f32_e32 v94, v94, v100
	v_sub_f32_e32 v95, v95, v101
	v_sub_f32_e32 v96, v96, v102
	v_sub_f32_e32 v97, v97, v103
	v_add_u32_e32 v123, 8, v120
	v_min_u32_e32 v123, 16, v123
	v_cvt_f32_u32_e32 v112, v123
	v_div_scale_f32 v113, s[72:73], v112, v112, v118
	v_rcp_f32_e32 v114, v113
	v_div_scale_f32 v115, vcc, v118, v112, v118
	v_fma_f32 v116, -v113, v114, 1.0
	v_fmac_f32_e32 v114, v116, v114
	v_mul_f32_e32 v116, v115, v114
	v_fma_f32 v117, -v113, v116, v115
	v_fmac_f32_e32 v116, v117, v114
	v_fma_f32 v113, -v113, v116, v115
	v_div_fmas_f32 v113, v113, v114, v116
	v_div_fixup_f32 v119, v113, v112, v118
	v_lshlrev_b32_e32 v100, 16, v44
	v_and_b32_e32 v101, 0xffff0000, v44
	v_lshlrev_b32_e32 v102, 16, v45
	v_and_b32_e32 v103, 0xffff0000, v45
	v_add_f32_e32 v94, v94, v100
	v_add_f32_e32 v95, v95, v101
	v_add_f32_e32 v96, v96, v102
	v_add_f32_e32 v97, v97, v103
	v_fma_f32 v100, v94, v119, -v100
	v_fma_f32 v101, v95, v119, -v101
	v_fma_f32 v102, v96, v119, -v102
	v_fma_f32 v103, v97, v119, -v103
	v_cvt_pk_bf16_f32 v110, v100, v101
	v_cvt_pk_bf16_f32 v111, v102, v103
	global_store_dwordx2 v122, v[110:111], s[70:71]
	s_add_u32 s70, s70, 0x800
	s_addc_u32 s71, s71, 0
	v_lshlrev_b32_e32 v100, 16, v14
	v_and_b32_e32 v101, 0xffff0000, v14
	v_lshlrev_b32_e32 v102, 16, v15
	v_and_b32_e32 v103, 0xffff0000, v15
	v_sub_f32_e32 v94, v94, v100
	v_sub_f32_e32 v95, v95, v101
	v_sub_f32_e32 v96, v96, v102
	v_sub_f32_e32 v97, v97, v103
	v_add_u32_e32 v123, 9, v120
	v_min_u32_e32 v123, 16, v123
	v_cvt_f32_u32_e32 v112, v123
	v_div_scale_f32 v113, s[72:73], v112, v112, v118
	v_rcp_f32_e32 v114, v113
	v_div_scale_f32 v115, vcc, v118, v112, v118
	v_fma_f32 v116, -v113, v114, 1.0
	v_fmac_f32_e32 v114, v116, v114
	v_mul_f32_e32 v116, v115, v114
	v_fma_f32 v117, -v113, v116, v115
	v_fmac_f32_e32 v116, v117, v114
	v_fma_f32 v113, -v113, v116, v115
	v_div_fmas_f32 v113, v113, v114, v116
	v_div_fixup_f32 v119, v113, v112, v118
	v_lshlrev_b32_e32 v100, 16, v46
	v_and_b32_e32 v101, 0xffff0000, v46
	v_lshlrev_b32_e32 v102, 16, v47
	v_and_b32_e32 v103, 0xffff0000, v47
	v_add_f32_e32 v94, v94, v100
	v_add_f32_e32 v95, v95, v101
	v_add_f32_e32 v96, v96, v102
	v_add_f32_e32 v97, v97, v103
	v_fma_f32 v100, v94, v119, -v100
	v_fma_f32 v101, v95, v119, -v101
	v_fma_f32 v102, v96, v119, -v102
	v_fma_f32 v103, v97, v119, -v103
	v_cvt_pk_bf16_f32 v108, v100, v101
	v_cvt_pk_bf16_f32 v109, v102, v103
	global_store_dwordx2 v122, v[108:109], s[70:71]
	s_add_u32 s70, s70, 0x800
	s_addc_u32 s71, s71, 0
	v_lshlrev_b32_e32 v100, 16, v16
	v_and_b32_e32 v101, 0xffff0000, v16
	v_lshlrev_b32_e32 v102, 16, v17
	v_and_b32_e32 v103, 0xffff0000, v17
	v_sub_f32_e32 v94, v94, v100
	v_sub_f32_e32 v95, v95, v101
	v_sub_f32_e32 v96, v96, v102
	v_sub_f32_e32 v97, v97, v103
	v_add_u32_e32 v123, 10, v120
	v_min_u32_e32 v123, 16, v123
	v_cvt_f32_u32_e32 v112, v123
	v_div_scale_f32 v113, s[72:73], v112, v112, v118
	v_rcp_f32_e32 v114, v113
	v_div_scale_f32 v115, vcc, v118, v112, v118
	v_fma_f32 v116, -v113, v114, 1.0
	v_fmac_f32_e32 v114, v116, v114
	v_mul_f32_e32 v116, v115, v114
	v_fma_f32 v117, -v113, v116, v115
	v_fmac_f32_e32 v116, v117, v114
	v_fma_f32 v113, -v113, v116, v115
	v_div_fmas_f32 v113, v113, v114, v116
	v_div_fixup_f32 v119, v113, v112, v118
	v_lshlrev_b32_e32 v100, 16, v48
	v_and_b32_e32 v101, 0xffff0000, v48
	v_lshlrev_b32_e32 v102, 16, v49
	v_and_b32_e32 v103, 0xffff0000, v49
	v_add_f32_e32 v94, v94, v100
	v_add_f32_e32 v95, v95, v101
	v_add_f32_e32 v96, v96, v102
	v_add_f32_e32 v97, v97, v103
	v_fma_f32 v100, v94, v119, -v100
	v_fma_f32 v101, v95, v119, -v101
	v_fma_f32 v102, v96, v119, -v102
	v_fma_f32 v103, v97, v119, -v103
	v_cvt_pk_bf16_f32 v110, v100, v101
	v_cvt_pk_bf16_f32 v111, v102, v103
	global_store_dwordx2 v122, v[110:111], s[70:71]
	s_add_u32 s70, s70, 0x800
	s_addc_u32 s71, s71, 0
	v_lshlrev_b32_e32 v100, 16, v18
	v_and_b32_e32 v101, 0xffff0000, v18
	v_lshlrev_b32_e32 v102, 16, v19
	v_and_b32_e32 v103, 0xffff0000, v19
	v_sub_f32_e32 v94, v94, v100
	v_sub_f32_e32 v95, v95, v101
	v_sub_f32_e32 v96, v96, v102
	v_sub_f32_e32 v97, v97, v103
	v_add_u32_e32 v123, 11, v120
	v_min_u32_e32 v123, 16, v123
	v_cvt_f32_u32_e32 v112, v123
	v_div_scale_f32 v113, s[72:73], v112, v112, v118
	v_rcp_f32_e32 v114, v113
	v_div_scale_f32 v115, vcc, v118, v112, v118
	v_fma_f32 v116, -v113, v114, 1.0
	v_fmac_f32_e32 v114, v116, v114
	v_mul_f32_e32 v116, v115, v114
	v_fma_f32 v117, -v113, v116, v115
	v_fmac_f32_e32 v116, v117, v114
	v_fma_f32 v113, -v113, v116, v115
	v_div_fmas_f32 v113, v113, v114, v116
	v_div_fixup_f32 v119, v113, v112, v118
	v_lshlrev_b32_e32 v100, 16, v50
	v_and_b32_e32 v101, 0xffff0000, v50
	v_lshlrev_b32_e32 v102, 16, v51
	v_and_b32_e32 v103, 0xffff0000, v51
	v_add_f32_e32 v94, v94, v100
	v_add_f32_e32 v95, v95, v101
	v_add_f32_e32 v96, v96, v102
	v_add_f32_e32 v97, v97, v103
	v_fma_f32 v100, v94, v119, -v100
	v_fma_f32 v101, v95, v119, -v101
	v_fma_f32 v102, v96, v119, -v102
	v_fma_f32 v103, v97, v119, -v103
	v_cvt_pk_bf16_f32 v108, v100, v101
	v_cvt_pk_bf16_f32 v109, v102, v103
	global_store_dwordx2 v122, v[108:109], s[70:71]
	s_add_u32 s70, s70, 0x800
	s_addc_u32 s71, s71, 0
	v_lshlrev_b32_e32 v100, 16, v20
	v_and_b32_e32 v101, 0xffff0000, v20
	v_lshlrev_b32_e32 v102, 16, v21
	v_and_b32_e32 v103, 0xffff0000, v21
	v_sub_f32_e32 v94, v94, v100
	v_sub_f32_e32 v95, v95, v101
	v_sub_f32_e32 v96, v96, v102
	v_sub_f32_e32 v97, v97, v103
	v_add_u32_e32 v123, 12, v120
	v_min_u32_e32 v123, 16, v123
	v_cvt_f32_u32_e32 v112, v123
	v_div_scale_f32 v113, s[72:73], v112, v112, v118
	v_rcp_f32_e32 v114, v113
	v_div_scale_f32 v115, vcc, v118, v112, v118
	v_fma_f32 v116, -v113, v114, 1.0
	v_fmac_f32_e32 v114, v116, v114
	v_mul_f32_e32 v116, v115, v114
	v_fma_f32 v117, -v113, v116, v115
	v_fmac_f32_e32 v116, v117, v114
	v_fma_f32 v113, -v113, v116, v115
	v_div_fmas_f32 v113, v113, v114, v116
	v_div_fixup_f32 v119, v113, v112, v118
	v_lshlrev_b32_e32 v100, 16, v52
	v_and_b32_e32 v101, 0xffff0000, v52
	v_lshlrev_b32_e32 v102, 16, v53
	v_and_b32_e32 v103, 0xffff0000, v53
	v_add_f32_e32 v94, v94, v100
	v_add_f32_e32 v95, v95, v101
	v_add_f32_e32 v96, v96, v102
	v_add_f32_e32 v97, v97, v103
	v_fma_f32 v100, v94, v119, -v100
	v_fma_f32 v101, v95, v119, -v101
	v_fma_f32 v102, v96, v119, -v102
	v_fma_f32 v103, v97, v119, -v103
	v_cvt_pk_bf16_f32 v110, v100, v101
	v_cvt_pk_bf16_f32 v111, v102, v103
	global_store_dwordx2 v122, v[110:111], s[70:71]
	s_add_u32 s70, s70, 0x800
	s_addc_u32 s71, s71, 0
	v_lshlrev_b32_e32 v100, 16, v22
	v_and_b32_e32 v101, 0xffff0000, v22
	v_lshlrev_b32_e32 v102, 16, v23
	v_and_b32_e32 v103, 0xffff0000, v23
	v_sub_f32_e32 v94, v94, v100
	v_sub_f32_e32 v95, v95, v101
	v_sub_f32_e32 v96, v96, v102
	v_sub_f32_e32 v97, v97, v103
	v_add_u32_e32 v123, 13, v120
	v_min_u32_e32 v123, 16, v123
	v_cvt_f32_u32_e32 v112, v123
	v_div_scale_f32 v113, s[72:73], v112, v112, v118
	v_rcp_f32_e32 v114, v113
	v_div_scale_f32 v115, vcc, v118, v112, v118
	v_fma_f32 v116, -v113, v114, 1.0
	v_fmac_f32_e32 v114, v116, v114
	v_mul_f32_e32 v116, v115, v114
	v_fma_f32 v117, -v113, v116, v115
	v_fmac_f32_e32 v116, v117, v114
	v_fma_f32 v113, -v113, v116, v115
	v_div_fmas_f32 v113, v113, v114, v116
	v_div_fixup_f32 v119, v113, v112, v118
	v_lshlrev_b32_e32 v100, 16, v54
	v_and_b32_e32 v101, 0xffff0000, v54
	v_lshlrev_b32_e32 v102, 16, v55
	v_and_b32_e32 v103, 0xffff0000, v55
	v_add_f32_e32 v94, v94, v100
	v_add_f32_e32 v95, v95, v101
	v_add_f32_e32 v96, v96, v102
	v_add_f32_e32 v97, v97, v103
	v_fma_f32 v100, v94, v119, -v100
	v_fma_f32 v101, v95, v119, -v101
	v_fma_f32 v102, v96, v119, -v102
	v_fma_f32 v103, v97, v119, -v103
	v_cvt_pk_bf16_f32 v108, v100, v101
	v_cvt_pk_bf16_f32 v109, v102, v103
	global_store_dwordx2 v122, v[108:109], s[70:71]
	s_add_u32 s70, s70, 0x800
	s_addc_u32 s71, s71, 0
	v_lshlrev_b32_e32 v100, 16, v24
	v_and_b32_e32 v101, 0xffff0000, v24
	v_lshlrev_b32_e32 v102, 16, v25
	v_and_b32_e32 v103, 0xffff0000, v25
	v_sub_f32_e32 v94, v94, v100
	v_sub_f32_e32 v95, v95, v101
	v_sub_f32_e32 v96, v96, v102
	v_sub_f32_e32 v97, v97, v103
	v_add_u32_e32 v123, 14, v120
	v_min_u32_e32 v123, 16, v123
	v_cvt_f32_u32_e32 v112, v123
	v_div_scale_f32 v113, s[72:73], v112, v112, v118
	v_rcp_f32_e32 v114, v113
	v_div_scale_f32 v115, vcc, v118, v112, v118
	v_fma_f32 v116, -v113, v114, 1.0
	v_fmac_f32_e32 v114, v116, v114
	v_mul_f32_e32 v116, v115, v114
	v_fma_f32 v117, -v113, v116, v115
	v_fmac_f32_e32 v116, v117, v114
	v_fma_f32 v113, -v113, v116, v115
	v_div_fmas_f32 v113, v113, v114, v116
	v_div_fixup_f32 v119, v113, v112, v118
	v_lshlrev_b32_e32 v100, 16, v56
	v_and_b32_e32 v101, 0xffff0000, v56
	v_lshlrev_b32_e32 v102, 16, v57
	v_and_b32_e32 v103, 0xffff0000, v57
	v_add_f32_e32 v94, v94, v100
	v_add_f32_e32 v95, v95, v101
	v_add_f32_e32 v96, v96, v102
	v_add_f32_e32 v97, v97, v103
	v_fma_f32 v100, v94, v119, -v100
	v_fma_f32 v101, v95, v119, -v101
	v_fma_f32 v102, v96, v119, -v102
	v_fma_f32 v103, v97, v119, -v103
	v_cvt_pk_bf16_f32 v110, v100, v101
	v_cvt_pk_bf16_f32 v111, v102, v103
	global_store_dwordx2 v122, v[110:111], s[70:71]
	s_add_u32 s70, s70, 0x800
	s_addc_u32 s71, s71, 0
	v_lshlrev_b32_e32 v100, 16, v26
	v_and_b32_e32 v101, 0xffff0000, v26
	v_lshlrev_b32_e32 v102, 16, v27
	v_and_b32_e32 v103, 0xffff0000, v27
	v_sub_f32_e32 v94, v94, v100
	v_sub_f32_e32 v95, v95, v101
	v_sub_f32_e32 v96, v96, v102
	v_sub_f32_e32 v97, v97, v103
	v_add_u32_e32 v123, 15, v120
	v_min_u32_e32 v123, 16, v123
	v_cvt_f32_u32_e32 v112, v123
	v_div_scale_f32 v113, s[72:73], v112, v112, v118
	v_rcp_f32_e32 v114, v113
	v_div_scale_f32 v115, vcc, v118, v112, v118
	v_fma_f32 v116, -v113, v114, 1.0
	v_fmac_f32_e32 v114, v116, v114
	v_mul_f32_e32 v116, v115, v114
	v_fma_f32 v117, -v113, v116, v115
	v_fmac_f32_e32 v116, v117, v114
	v_fma_f32 v113, -v113, v116, v115
	v_div_fmas_f32 v113, v113, v114, v116
	v_div_fixup_f32 v119, v113, v112, v118
	v_lshlrev_b32_e32 v100, 16, v58
	v_and_b32_e32 v101, 0xffff0000, v58
	v_lshlrev_b32_e32 v102, 16, v59
	v_and_b32_e32 v103, 0xffff0000, v59
	v_add_f32_e32 v94, v94, v100
	v_add_f32_e32 v95, v95, v101
	v_add_f32_e32 v96, v96, v102
	v_add_f32_e32 v97, v97, v103
	v_fma_f32 v100, v94, v119, -v100
	v_fma_f32 v101, v95, v119, -v101
	v_fma_f32 v102, v96, v119, -v102
	v_fma_f32 v103, v97, v119, -v103
	v_cvt_pk_bf16_f32 v108, v100, v101
	v_cvt_pk_bf16_f32 v109, v102, v103
	global_store_dwordx2 v122, v[108:109], s[70:71]
	s_add_u32 s70, s70, 0x800
	s_addc_u32 s71, s71, 0
	v_lshlrev_b32_e32 v100, 16, v28
	v_and_b32_e32 v101, 0xffff0000, v28
	v_lshlrev_b32_e32 v102, 16, v29
	v_and_b32_e32 v103, 0xffff0000, v29
	v_sub_f32_e32 v94, v94, v100
	v_sub_f32_e32 v95, v95, v101
	v_sub_f32_e32 v96, v96, v102
	v_sub_f32_e32 v97, v97, v103
	v_mov_b32_e32 v119, 0x3d800000
	v_lshlrev_b32_e32 v100, 16, v60
	v_and_b32_e32 v101, 0xffff0000, v60
	v_lshlrev_b32_e32 v102, 16, v61
	v_and_b32_e32 v103, 0xffff0000, v61
	v_add_f32_e32 v94, v94, v100
	v_add_f32_e32 v95, v95, v101
	v_add_f32_e32 v96, v96, v102
	v_add_f32_e32 v97, v97, v103
	v_fma_f32 v100, v94, v119, -v100
	v_fma_f32 v101, v95, v119, -v101
	v_fma_f32 v102, v96, v119, -v102
	v_fma_f32 v103, v97, v119, -v103
	v_cvt_pk_bf16_f32 v110, v100, v101
	v_cvt_pk_bf16_f32 v111, v102, v103
	global_store_dwordx2 v122, v[110:111], s[70:71]
	s_add_u32 s70, s70, 0x800
	s_addc_u32 s71, s71, 0
	v_lshlrev_b32_e32 v100, 16, v30
	v_and_b32_e32 v101, 0xffff0000, v30
	v_lshlrev_b32_e32 v102, 16, v31
	v_and_b32_e32 v103, 0xffff0000, v31
	v_sub_f32_e32 v94, v94, v100
	v_sub_f32_e32 v95, v95, v101
	v_sub_f32_e32 v96, v96, v102
	v_sub_f32_e32 v97, v97, v103
	v_lshlrev_b32_e32 v100, 16, v62
	v_and_b32_e32 v101, 0xffff0000, v62
	v_lshlrev_b32_e32 v102, 16, v63
	v_and_b32_e32 v103, 0xffff0000, v63
	v_add_f32_e32 v94, v94, v100
	v_add_f32_e32 v95, v95, v101
	v_add_f32_e32 v96, v96, v102
	v_add_f32_e32 v97, v97, v103
	v_fma_f32 v100, v94, v119, -v100
	v_fma_f32 v101, v95, v119, -v101
	v_fma_f32 v102, v96, v119, -v102
	v_fma_f32 v103, v97, v119, -v103
	v_cvt_pk_bf16_f32 v108, v100, v101
	v_cvt_pk_bf16_f32 v109, v102, v103
	global_store_dwordx2 v122, v[108:109], s[70:71]
	s_add_u32 s70, s70, 0x800
	s_addc_u32 s71, s71, 0
	v_lshlrev_b32_e32 v100, 16, v32
	v_and_b32_e32 v101, 0xffff0000, v32
	v_lshlrev_b32_e32 v102, 16, v33
	v_and_b32_e32 v103, 0xffff0000, v33
	v_sub_f32_e32 v94, v94, v100
	v_sub_f32_e32 v95, v95, v101
	v_sub_f32_e32 v96, v96, v102
	v_sub_f32_e32 v97, v97, v103
	v_lshlrev_b32_e32 v100, 16, v64
	v_and_b32_e32 v101, 0xffff0000, v64
	v_lshlrev_b32_e32 v102, 16, v65
	v_and_b32_e32 v103, 0xffff0000, v65
	v_add_f32_e32 v94, v94, v100
	v_add_f32_e32 v95, v95, v101
	v_add_f32_e32 v96, v96, v102
	v_add_f32_e32 v97, v97, v103
	v_fma_f32 v100, v94, v119, -v100
	v_fma_f32 v101, v95, v119, -v101
	v_fma_f32 v102, v96, v119, -v102
	v_fma_f32 v103, v97, v119, -v103
	v_cvt_pk_bf16_f32 v110, v100, v101
	v_cvt_pk_bf16_f32 v111, v102, v103
	global_store_dwordx2 v122, v[110:111], s[70:71]
	s_add_u32 s70, s70, 0x800
	s_addc_u32 s71, s71, 0
	v_lshlrev_b32_e32 v100, 16, v34
	v_and_b32_e32 v101, 0xffff0000, v34
	v_lshlrev_b32_e32 v102, 16, v35
	v_and_b32_e32 v103, 0xffff0000, v35
	v_sub_f32_e32 v94, v94, v100
	v_sub_f32_e32 v95, v95, v101
	v_sub_f32_e32 v96, v96, v102
	v_sub_f32_e32 v97, v97, v103
	v_lshlrev_b32_e32 v100, 16, v66
	v_and_b32_e32 v101, 0xffff0000, v66
	v_lshlrev_b32_e32 v102, 16, v67
	v_and_b32_e32 v103, 0xffff0000, v67
	v_add_f32_e32 v94, v94, v100
	v_add_f32_e32 v95, v95, v101
	v_add_f32_e32 v96, v96, v102
	v_add_f32_e32 v97, v97, v103
	v_fma_f32 v100, v94, v119, -v100
	v_fma_f32 v101, v95, v119, -v101
	v_fma_f32 v102, v96, v119, -v102
	v_fma_f32 v103, v97, v119, -v103
	v_cvt_pk_bf16_f32 v108, v100, v101
	v_cvt_pk_bf16_f32 v109, v102, v103
	global_store_dwordx2 v122, v[108:109], s[70:71]
	s_add_u32 s70, s70, 0x800
	s_addc_u32 s71, s71, 0
	v_lshlrev_b32_e32 v100, 16, v36
	v_and_b32_e32 v101, 0xffff0000, v36
	v_lshlrev_b32_e32 v102, 16, v37
	v_and_b32_e32 v103, 0xffff0000, v37
	v_sub_f32_e32 v94, v94, v100
	v_sub_f32_e32 v95, v95, v101
	v_sub_f32_e32 v96, v96, v102
	v_sub_f32_e32 v97, v97, v103
	v_lshlrev_b32_e32 v100, 16, v68
	v_and_b32_e32 v101, 0xffff0000, v68
	v_lshlrev_b32_e32 v102, 16, v69
	v_and_b32_e32 v103, 0xffff0000, v69
	v_add_f32_e32 v94, v94, v100
	v_add_f32_e32 v95, v95, v101
	v_add_f32_e32 v96, v96, v102
	v_add_f32_e32 v97, v97, v103
	v_fma_f32 v100, v94, v119, -v100
	v_fma_f32 v101, v95, v119, -v101
	v_fma_f32 v102, v96, v119, -v102
	v_fma_f32 v103, v97, v119, -v103
	v_cvt_pk_bf16_f32 v110, v100, v101
	v_cvt_pk_bf16_f32 v111, v102, v103
	global_store_dwordx2 v122, v[110:111], s[70:71]
	s_add_u32 s70, s70, 0x800
	s_addc_u32 s71, s71, 0
	v_lshlrev_b32_e32 v100, 16, v38
	v_and_b32_e32 v101, 0xffff0000, v38
	v_lshlrev_b32_e32 v102, 16, v39
	v_and_b32_e32 v103, 0xffff0000, v39
	v_sub_f32_e32 v94, v94, v100
	v_sub_f32_e32 v95, v95, v101
	v_sub_f32_e32 v96, v96, v102
	v_sub_f32_e32 v97, v97, v103
	v_lshlrev_b32_e32 v100, 16, v70
	v_and_b32_e32 v101, 0xffff0000, v70
	v_lshlrev_b32_e32 v102, 16, v71
	v_and_b32_e32 v103, 0xffff0000, v71
	v_add_f32_e32 v94, v94, v100
	v_add_f32_e32 v95, v95, v101
	v_add_f32_e32 v96, v96, v102
	v_add_f32_e32 v97, v97, v103
	v_fma_f32 v100, v94, v119, -v100
	v_fma_f32 v101, v95, v119, -v101
	v_fma_f32 v102, v96, v119, -v102
	v_fma_f32 v103, v97, v119, -v103
	v_cvt_pk_bf16_f32 v108, v100, v101
	v_cvt_pk_bf16_f32 v109, v102, v103
	global_store_dwordx2 v122, v[108:109], s[70:71]
	s_add_u32 s70, s70, 0x800
	s_addc_u32 s71, s71, 0
	v_lshlrev_b32_e32 v100, 16, v40
	v_and_b32_e32 v101, 0xffff0000, v40
	v_lshlrev_b32_e32 v102, 16, v41
	v_and_b32_e32 v103, 0xffff0000, v41
	v_sub_f32_e32 v94, v94, v100
	v_sub_f32_e32 v95, v95, v101
	v_sub_f32_e32 v96, v96, v102
	v_sub_f32_e32 v97, v97, v103
	v_lshlrev_b32_e32 v100, 16, v72
	v_and_b32_e32 v101, 0xffff0000, v72
	v_lshlrev_b32_e32 v102, 16, v73
	v_and_b32_e32 v103, 0xffff0000, v73
	v_add_f32_e32 v94, v94, v100
	v_add_f32_e32 v95, v95, v101
	v_add_f32_e32 v96, v96, v102
	v_add_f32_e32 v97, v97, v103
	v_fma_f32 v100, v94, v119, -v100
	v_fma_f32 v101, v95, v119, -v101
	v_fma_f32 v102, v96, v119, -v102
	v_fma_f32 v103, v97, v119, -v103
	v_cvt_pk_bf16_f32 v110, v100, v101
	v_cvt_pk_bf16_f32 v111, v102, v103
	global_store_dwordx2 v122, v[110:111], s[70:71]
	s_add_u32 s70, s70, 0x800
	s_addc_u32 s71, s71, 0
	v_lshlrev_b32_e32 v100, 16, v42
	v_and_b32_e32 v101, 0xffff0000, v42
	v_lshlrev_b32_e32 v102, 16, v43
	v_and_b32_e32 v103, 0xffff0000, v43
	v_sub_f32_e32 v94, v94, v100
	v_sub_f32_e32 v95, v95, v101
	v_sub_f32_e32 v96, v96, v102
	v_sub_f32_e32 v97, v97, v103
	v_lshlrev_b32_e32 v100, 16, v74
	v_and_b32_e32 v101, 0xffff0000, v74
	v_lshlrev_b32_e32 v102, 16, v75
	v_and_b32_e32 v103, 0xffff0000, v75
	v_add_f32_e32 v94, v94, v100
	v_add_f32_e32 v95, v95, v101
	v_add_f32_e32 v96, v96, v102
	v_add_f32_e32 v97, v97, v103
	v_fma_f32 v100, v94, v119, -v100
	v_fma_f32 v101, v95, v119, -v101
	v_fma_f32 v102, v96, v119, -v102
	v_fma_f32 v103, v97, v119, -v103
	v_cvt_pk_bf16_f32 v108, v100, v101
	v_cvt_pk_bf16_f32 v109, v102, v103
	global_store_dwordx2 v122, v[108:109], s[70:71]
	s_add_u32 s70, s70, 0x800
	s_addc_u32 s71, s71, 0
	v_lshlrev_b32_e32 v100, 16, v44
	v_and_b32_e32 v101, 0xffff0000, v44
	v_lshlrev_b32_e32 v102, 16, v45
	v_and_b32_e32 v103, 0xffff0000, v45
	v_sub_f32_e32 v94, v94, v100
	v_sub_f32_e32 v95, v95, v101
	v_sub_f32_e32 v96, v96, v102
	v_sub_f32_e32 v97, v97, v103
	v_lshlrev_b32_e32 v100, 16, v76
	v_and_b32_e32 v101, 0xffff0000, v76
	v_lshlrev_b32_e32 v102, 16, v77
	v_and_b32_e32 v103, 0xffff0000, v77
	v_add_f32_e32 v94, v94, v100
	v_add_f32_e32 v95, v95, v101
	v_add_f32_e32 v96, v96, v102
	v_add_f32_e32 v97, v97, v103
	v_fma_f32 v100, v94, v119, -v100
	v_fma_f32 v101, v95, v119, -v101
	v_fma_f32 v102, v96, v119, -v102
	v_fma_f32 v103, v97, v119, -v103
	v_cvt_pk_bf16_f32 v110, v100, v101
	v_cvt_pk_bf16_f32 v111, v102, v103
	global_store_dwordx2 v122, v[110:111], s[70:71]
	s_add_u32 s70, s70, 0x800
	s_addc_u32 s71, s71, 0
	v_lshlrev_b32_e32 v100, 16, v46
	v_and_b32_e32 v101, 0xffff0000, v46
	v_lshlrev_b32_e32 v102, 16, v47
	v_and_b32_e32 v103, 0xffff0000, v47
	v_sub_f32_e32 v94, v94, v100
	v_sub_f32_e32 v95, v95, v101
	v_sub_f32_e32 v96, v96, v102
	v_sub_f32_e32 v97, v97, v103
	v_lshlrev_b32_e32 v100, 16, v78
	v_and_b32_e32 v101, 0xffff0000, v78
	v_lshlrev_b32_e32 v102, 16, v79
	v_and_b32_e32 v103, 0xffff0000, v79
	v_add_f32_e32 v94, v94, v100
	v_add_f32_e32 v95, v95, v101
	v_add_f32_e32 v96, v96, v102
	v_add_f32_e32 v97, v97, v103
	v_fma_f32 v100, v94, v119, -v100
	v_fma_f32 v101, v95, v119, -v101
	v_fma_f32 v102, v96, v119, -v102
	v_fma_f32 v103, v97, v119, -v103
	v_cvt_pk_bf16_f32 v108, v100, v101
	v_cvt_pk_bf16_f32 v109, v102, v103
	global_store_dwordx2 v122, v[108:109], s[70:71]
	s_add_u32 s70, s70, 0x800
	s_addc_u32 s71, s71, 0
	v_lshlrev_b32_e32 v100, 16, v48
	v_and_b32_e32 v101, 0xffff0000, v48
	v_lshlrev_b32_e32 v102, 16, v49
	v_and_b32_e32 v103, 0xffff0000, v49
	v_sub_f32_e32 v94, v94, v100
	v_sub_f32_e32 v95, v95, v101
	v_sub_f32_e32 v96, v96, v102
	v_sub_f32_e32 v97, v97, v103
	v_lshlrev_b32_e32 v100, 16, v80
	v_and_b32_e32 v101, 0xffff0000, v80
	v_lshlrev_b32_e32 v102, 16, v81
	v_and_b32_e32 v103, 0xffff0000, v81
	v_add_f32_e32 v94, v94, v100
	v_add_f32_e32 v95, v95, v101
	v_add_f32_e32 v96, v96, v102
	v_add_f32_e32 v97, v97, v103
	v_fma_f32 v100, v94, v119, -v100
	v_fma_f32 v101, v95, v119, -v101
	v_fma_f32 v102, v96, v119, -v102
	v_fma_f32 v103, v97, v119, -v103
	v_cvt_pk_bf16_f32 v110, v100, v101
	v_cvt_pk_bf16_f32 v111, v102, v103
	global_store_dwordx2 v122, v[110:111], s[70:71]
	s_add_u32 s70, s70, 0x800
	s_addc_u32 s71, s71, 0
	v_lshlrev_b32_e32 v100, 16, v50
	v_and_b32_e32 v101, 0xffff0000, v50
	v_lshlrev_b32_e32 v102, 16, v51
	v_and_b32_e32 v103, 0xffff0000, v51
	v_sub_f32_e32 v94, v94, v100
	v_sub_f32_e32 v95, v95, v101
	v_sub_f32_e32 v96, v96, v102
	v_sub_f32_e32 v97, v97, v103
	v_lshlrev_b32_e32 v100, 16, v82
	v_and_b32_e32 v101, 0xffff0000, v82
	v_lshlrev_b32_e32 v102, 16, v83
	v_and_b32_e32 v103, 0xffff0000, v83
	v_add_f32_e32 v94, v94, v100
	v_add_f32_e32 v95, v95, v101
	v_add_f32_e32 v96, v96, v102
	v_add_f32_e32 v97, v97, v103
	v_fma_f32 v100, v94, v119, -v100
	v_fma_f32 v101, v95, v119, -v101
	v_fma_f32 v102, v96, v119, -v102
	v_fma_f32 v103, v97, v119, -v103
	v_cvt_pk_bf16_f32 v108, v100, v101
	v_cvt_pk_bf16_f32 v109, v102, v103
	global_store_dwordx2 v122, v[108:109], s[70:71]
	s_add_u32 s70, s70, 0x800
	s_addc_u32 s71, s71, 0
	v_lshlrev_b32_e32 v100, 16, v52
	v_and_b32_e32 v101, 0xffff0000, v52
	v_lshlrev_b32_e32 v102, 16, v53
	v_and_b32_e32 v103, 0xffff0000, v53
	v_sub_f32_e32 v94, v94, v100
	v_sub_f32_e32 v95, v95, v101
	v_sub_f32_e32 v96, v96, v102
	v_sub_f32_e32 v97, v97, v103
	v_lshlrev_b32_e32 v100, 16, v84
	v_and_b32_e32 v101, 0xffff0000, v84
	v_lshlrev_b32_e32 v102, 16, v85
	v_and_b32_e32 v103, 0xffff0000, v85
	v_add_f32_e32 v94, v94, v100
	v_add_f32_e32 v95, v95, v101
	v_add_f32_e32 v96, v96, v102
	v_add_f32_e32 v97, v97, v103
	v_fma_f32 v100, v94, v119, -v100
	v_fma_f32 v101, v95, v119, -v101
	v_fma_f32 v102, v96, v119, -v102
	v_fma_f32 v103, v97, v119, -v103
	v_cvt_pk_bf16_f32 v110, v100, v101
	v_cvt_pk_bf16_f32 v111, v102, v103
	global_store_dwordx2 v122, v[110:111], s[70:71]
	s_add_u32 s70, s70, 0x800
	s_addc_u32 s71, s71, 0
	v_lshlrev_b32_e32 v100, 16, v54
	v_and_b32_e32 v101, 0xffff0000, v54
	v_lshlrev_b32_e32 v102, 16, v55
	v_and_b32_e32 v103, 0xffff0000, v55
	v_sub_f32_e32 v94, v94, v100
	v_sub_f32_e32 v95, v95, v101
	v_sub_f32_e32 v96, v96, v102
	v_sub_f32_e32 v97, v97, v103
	v_lshlrev_b32_e32 v100, 16, v86
	v_and_b32_e32 v101, 0xffff0000, v86
	v_lshlrev_b32_e32 v102, 16, v87
	v_and_b32_e32 v103, 0xffff0000, v87
	v_add_f32_e32 v94, v94, v100
	v_add_f32_e32 v95, v95, v101
	v_add_f32_e32 v96, v96, v102
	v_add_f32_e32 v97, v97, v103
	v_fma_f32 v100, v94, v119, -v100
	v_fma_f32 v101, v95, v119, -v101
	v_fma_f32 v102, v96, v119, -v102
	v_fma_f32 v103, v97, v119, -v103
	v_cvt_pk_bf16_f32 v108, v100, v101
	v_cvt_pk_bf16_f32 v109, v102, v103
	global_store_dwordx2 v122, v[108:109], s[70:71]
	s_add_u32 s70, s70, 0x800
	s_addc_u32 s71, s71, 0
	v_lshlrev_b32_e32 v100, 16, v56
	v_and_b32_e32 v101, 0xffff0000, v56
	v_lshlrev_b32_e32 v102, 16, v57
	v_and_b32_e32 v103, 0xffff0000, v57
	v_sub_f32_e32 v94, v94, v100
	v_sub_f32_e32 v95, v95, v101
	v_sub_f32_e32 v96, v96, v102
	v_sub_f32_e32 v97, v97, v103
	v_lshlrev_b32_e32 v100, 16, v88
	v_and_b32_e32 v101, 0xffff0000, v88
	v_lshlrev_b32_e32 v102, 16, v89
	v_and_b32_e32 v103, 0xffff0000, v89
	v_add_f32_e32 v94, v94, v100
	v_add_f32_e32 v95, v95, v101
	v_add_f32_e32 v96, v96, v102
	v_add_f32_e32 v97, v97, v103
	v_fma_f32 v100, v94, v119, -v100
	v_fma_f32 v101, v95, v119, -v101
	v_fma_f32 v102, v96, v119, -v102
	v_fma_f32 v103, v97, v119, -v103
	v_cvt_pk_bf16_f32 v110, v100, v101
	v_cvt_pk_bf16_f32 v111, v102, v103
	global_store_dwordx2 v122, v[110:111], s[70:71]
	s_add_u32 s70, s70, 0x800
	s_addc_u32 s71, s71, 0
	v_lshlrev_b32_e32 v100, 16, v58
	v_and_b32_e32 v101, 0xffff0000, v58
	v_lshlrev_b32_e32 v102, 16, v59
	v_and_b32_e32 v103, 0xffff0000, v59
	v_sub_f32_e32 v94, v94, v100
	v_sub_f32_e32 v95, v95, v101
	v_sub_f32_e32 v96, v96, v102
	v_sub_f32_e32 v97, v97, v103
	v_lshlrev_b32_e32 v100, 16, v90
	v_and_b32_e32 v101, 0xffff0000, v90
	v_lshlrev_b32_e32 v102, 16, v91
	v_and_b32_e32 v103, 0xffff0000, v91
	v_add_f32_e32 v94, v94, v100
	v_add_f32_e32 v95, v95, v101
	v_add_f32_e32 v96, v96, v102
	v_add_f32_e32 v97, v97, v103
	v_fma_f32 v100, v94, v119, -v100
	v_fma_f32 v101, v95, v119, -v101
	v_fma_f32 v102, v96, v119, -v102
	v_fma_f32 v103, v97, v119, -v103
	v_cvt_pk_bf16_f32 v108, v100, v101
	v_cvt_pk_bf16_f32 v109, v102, v103
	global_store_dwordx2 v122, v[108:109], s[70:71]
	s_add_u32 s70, s70, 0x800
	s_addc_u32 s71, s71, 0
	v_lshlrev_b32_e32 v100, 16, v60
	v_and_b32_e32 v101, 0xffff0000, v60
	v_lshlrev_b32_e32 v102, 16, v61
	v_and_b32_e32 v103, 0xffff0000, v61
	v_sub_f32_e32 v94, v94, v100
	v_sub_f32_e32 v95, v95, v101
	v_sub_f32_e32 v96, v96, v102
	v_sub_f32_e32 v97, v97, v103
	v_lshlrev_b32_e32 v100, 16, v92
	v_and_b32_e32 v101, 0xffff0000, v92
	v_lshlrev_b32_e32 v102, 16, v93
	v_and_b32_e32 v103, 0xffff0000, v93
	v_add_f32_e32 v94, v94, v100
	v_add_f32_e32 v95, v95, v101
	v_add_f32_e32 v96, v96, v102
	v_add_f32_e32 v97, v97, v103
	v_fma_f32 v100, v94, v119, -v100
	v_fma_f32 v101, v95, v119, -v101
	v_fma_f32 v102, v96, v119, -v102
	v_fma_f32 v103, v97, v119, -v103
	v_cvt_pk_bf16_f32 v110, v100, v101
	v_cvt_pk_bf16_f32 v111, v102, v103
	global_store_dwordx2 v122, v[110:111], s[70:71]
	s_branch .Lpl_done
